# leftover g1 item (WGs 144..207) front part made straight-line with all loads before first barrier; s91 clobber in g1 main items removed
# baseline (speedup 1.0000x reference)
.LBB0_1602:
	s_lshl_b32 s24, s86, 4
	s_lshl_b32 s25, s86, 6
	s_and_b32 s24, s24, 0xffffe000
	s_and_b32 s25, s25, 0x1fc0
	s_or_b32 s90, s24, s25
	s_bfe_u32 s87, s86, 0x20007
	s_nop 0
	s_load_dwordx2 s[98:99], s[0:1], 0x98
	s_load_dwordx2 s[100:101], s[0:1], 0xa0
	v_lshlrev_b32_e32 v178, 2, v182
	v_ashrrev_i32_e32 v150, 4, v180
	v_add_u32_e32 v152, s90, v150
	v_mad_i64_i32 v[152:153], vcc, v152, s62, v[22:23]
	global_load_dword v170, v[152:153], off
	v_add_u32_e32 v151, 0x200, v180
	v_ashrrev_i32_e32 v151, 4, v151
	v_add_u32_e32 v154, s90, v151
	v_mad_i64_i32 v[154:155], vcc, v154, s62, v[22:23]
	global_load_dword v171, v[154:155], off
	v_lshl_add_u32 v174, v150, 2, v59
	v_lshl_add_u32 v175, v151, 2, v59
	s_waitcnt lgkmcnt(0)
	s_lshl_b32 s56, s87, 8
	v_and_b32_e32 v156, 0xffffff00, v43
	v_ashrrev_i32_e32 v157, 31, v156
	v_lshl_add_u64 v[158:159], v[156:157], 2, s[98:99]
	v_lshl_add_u64 v[158:159], v[158:159], 0, s[56:57]
	v_lshl_add_u64 v[158:159], v[158:159], 0, v[178:179]
	global_load_dword v172, v[158:159], off
	v_add_u32_e32 v176, s4, v43
	v_add_u32_e32 v160, 0x800, v43
	v_and_b32_e32 v156, 0xffffff00, v160
	v_ashrrev_i32_e32 v157, 31, v156
	v_lshl_add_u64 v[162:163], v[156:157], 2, s[98:99]
	v_lshl_add_u64 v[162:163], v[162:163], 0, s[56:57]
	v_lshl_add_u64 v[162:163], v[162:163], 0, v[178:179]
	global_load_dword v173, v[162:163], off
	v_add_u32_e32 v177, s4, v160
	v_ashrrev_i32_e32 v90, 6, v180
	v_lshl_add_u32 v164, s87, 6, v90
	v_ashrrev_i32_e32 v165, 31, v164
	v_lshl_add_u64 v[166:167], v[164:165], 2, s[100:101]
	global_load_dword v132, v[166:167], off
	v_add_u32_e32 v164, 0x200, v180
	v_ashrrev_i32_e32 v91, 6, v164
	v_lshl_add_u32 v164, s87, 6, v91
	v_ashrrev_i32_e32 v165, 31, v164
	v_lshl_add_u64 v[166:167], v[164:165], 2, s[100:101]
	global_load_dword v133, v[166:167], off
	v_add_u32_e32 v164, 0x400, v180
	v_ashrrev_i32_e32 v92, 6, v164
	v_lshl_add_u32 v164, s87, 6, v92
	v_ashrrev_i32_e32 v165, 31, v164
	v_lshl_add_u64 v[166:167], v[164:165], 2, s[100:101]
	global_load_dword v134, v[166:167], off
	v_add_u32_e32 v164, 0x600, v180
	v_ashrrev_i32_e32 v93, 6, v164
	v_lshl_add_u32 v164, s87, 6, v93
	v_ashrrev_i32_e32 v165, 31, v164
	v_lshl_add_u64 v[166:167], v[164:165], 2, s[100:101]
	global_load_dword v135, v[166:167], off
	v_add_u32_e32 v164, 0x800, v180
	v_ashrrev_i32_e32 v94, 6, v164
	v_lshl_add_u32 v164, s87, 6, v94
	v_ashrrev_i32_e32 v165, 31, v164
	v_lshl_add_u64 v[166:167], v[164:165], 2, s[100:101]
	global_load_dword v136, v[166:167], off
	v_add_u32_e32 v164, 0xa00, v180
	v_ashrrev_i32_e32 v95, 6, v164
	v_lshl_add_u32 v164, s87, 6, v95
	v_ashrrev_i32_e32 v165, 31, v164
	v_lshl_add_u64 v[166:167], v[164:165], 2, s[100:101]
	global_load_dword v137, v[166:167], off
	v_add_u32_e32 v164, 0xc00, v180
	v_ashrrev_i32_e32 v96, 6, v164
	v_lshl_add_u32 v164, s87, 6, v96
	v_ashrrev_i32_e32 v165, 31, v164
	v_lshl_add_u64 v[166:167], v[164:165], 2, s[100:101]
	global_load_dword v138, v[166:167], off
	v_add_u32_e32 v164, 0xe00, v180
	v_ashrrev_i32_e32 v97, 6, v164
	v_lshl_add_u32 v164, s87, 6, v97
	v_ashrrev_i32_e32 v165, 31, v164
	v_lshl_add_u64 v[166:167], v[164:165], 2, s[100:101]
	global_load_dword v139, v[166:167], off
	s_lshl_b32 s24, s86, 4
	s_lshl_b32 s25, s86, 6
	s_and_b32 s24, s24, 0xffffe000
	s_and_b32 s25, s25, 0x1fc0
	s_or_b32 s90, s24, s25
	s_bfe_u32 s87, s86, 0x20007
	v_add_u32_e32 v2, s90, v35
	v_mov_b64_e32 v[10:11], s[46:47]
	v_mad_i64_i32 v[2:3], s[24:25], v2, s62, v[10:11]
	s_lshl_b32 s56, s87, 8
	v_lshl_add_u64 v[2:3], v[2:3], 0, s[56:57]
	v_lshlrev_b32_e32 v178, 2, v182
	v_add_u32_e32 v4, s90, v36
	v_lshl_add_u64 v[2:3], v[2:3], 0, v[178:179]
	v_mad_i64_i32 v[4:5], s[24:25], v4, s62, v[10:11]
	v_add_co_u32_e32 v2, vcc, s50, v2
	v_lshl_add_u64 v[4:5], v[4:5], 0, s[56:57]
	v_add_u32_e32 v6, s90, v37
	v_addc_co_u32_e32 v3, vcc, 0, v3, vcc
	v_lshl_add_u64 v[4:5], v[4:5], 0, v[178:179]
	v_mad_i64_i32 v[6:7], s[24:25], v6, s62, v[10:11]
	v_add_co_u32_e32 v4, vcc, s50, v4
	v_lshl_add_u64 v[6:7], v[6:7], 0, s[56:57]
	v_add_u32_e32 v8, s90, v38
	v_addc_co_u32_e32 v5, vcc, 0, v5, vcc
	v_lshl_add_u64 v[6:7], v[6:7], 0, v[178:179]
	v_mad_i64_i32 v[8:9], s[24:25], v8, s62, v[10:11]
	v_add_co_u32_e32 v6, vcc, s50, v6
	v_lshl_add_u64 v[8:9], v[8:9], 0, s[56:57]
	v_add_u32_e32 v12, s90, v39
	v_addc_co_u32_e32 v7, vcc, 0, v7, vcc
	v_lshl_add_u64 v[8:9], v[8:9], 0, v[178:179]
	v_mad_i64_i32 v[12:13], s[24:25], v12, s62, v[10:11]
	v_add_co_u32_e32 v8, vcc, s50, v8
	v_lshl_add_u64 v[12:13], v[12:13], 0, s[56:57]
	v_add_u32_e32 v14, s90, v40
	v_addc_co_u32_e32 v9, vcc, 0, v9, vcc
	v_lshl_add_u64 v[12:13], v[12:13], 0, v[178:179]
	v_mad_i64_i32 v[14:15], s[24:25], v14, s62, v[10:11]
	v_add_co_u32_e32 v12, vcc, s50, v12
	v_lshl_add_u64 v[14:15], v[14:15], 0, s[56:57]
	v_add_u32_e32 v16, s90, v41
	v_addc_co_u32_e32 v13, vcc, 0, v13, vcc
	v_lshl_add_u64 v[14:15], v[14:15], 0, v[178:179]
	v_mad_i64_i32 v[16:17], s[24:25], v16, s62, v[10:11]
	v_add_co_u32_e32 v14, vcc, s50, v14
	v_lshl_add_u64 v[16:17], v[16:17], 0, s[56:57]
	v_add_u32_e32 v29, s90, v42
	v_addc_co_u32_e32 v15, vcc, 0, v15, vcc
	v_lshl_add_u64 v[16:17], v[16:17], 0, v[178:179]
	v_mad_i64_i32 v[66:67], s[24:25], v29, s62, v[10:11]
	v_add_co_u32_e32 v16, vcc, s50, v16
	v_lshl_add_u64 v[66:67], v[66:67], 0, s[56:57]
	s_nop 0
	v_addc_co_u32_e32 v17, vcc, 0, v17, vcc
	v_lshl_add_u64 v[66:67], v[66:67], 0, v[178:179]
	v_add_co_u32_e32 v74, vcc, s50, v66
	s_lshl_b32 s56, s87, 9
	s_nop 0
	v_addc_co_u32_e32 v75, vcc, 0, v67, vcc
	global_load_dword v72, v[2:3], off offset:2144
	global_load_dword v71, v[4:5], off offset:2144
	global_load_dword v70, v[6:7], off offset:2144
	global_load_dword v69, v[8:9], off offset:2144
	global_load_dword v68, v[12:13], off offset:2144
	global_load_dword v67, v[14:15], off offset:2144
	global_load_dword v66, v[16:17], off offset:2144
	global_load_dword v65, v[74:75], off offset:2144
	v_add_u32_e32 v2, s90, v44
	v_mad_i64_i32 v[2:3], s[24:25], v2, s62, v[10:11]
	v_lshl_add_u64 v[2:3], v[2:3], 0, s[56:57]
	v_mov_b32_e32 v29, v179
	v_add_u32_e32 v4, s90, v45
	v_lshl_add_u64 v[2:3], v[2:3], 0, v[28:29]
	v_mad_i64_i32 v[4:5], s[24:25], v4, s62, v[10:11]
	v_add_co_u32_e32 v2, vcc, s50, v2
	v_lshl_add_u64 v[4:5], v[4:5], 0, s[56:57]
	v_add_u32_e32 v12, s90, v46
	v_addc_co_u32_e32 v3, vcc, 0, v3, vcc
	v_lshl_add_u64 v[4:5], v[4:5], 0, v[28:29]
	v_mad_i64_i32 v[12:13], s[24:25], v12, s62, v[10:11]
	v_add_co_u32_e32 v6, vcc, s50, v4
	v_lshl_add_u64 v[12:13], v[12:13], 0, s[56:57]
	v_add_u32_e32 v14, s90, v47
	v_addc_co_u32_e32 v7, vcc, 0, v5, vcc
	v_lshl_add_u64 v[12:13], v[12:13], 0, v[28:29]
	v_mad_i64_i32 v[10:11], s[24:25], v14, s62, v[10:11]
	v_add_co_u32_e32 v12, vcc, s50, v12
	v_lshl_add_u64 v[10:11], v[10:11], 0, s[56:57]
	s_nop 0
	v_addc_co_u32_e32 v13, vcc, 0, v13, vcc
	v_lshl_add_u64 v[10:11], v[10:11], 0, v[28:29]
	v_add_co_u32_e32 v14, vcc, 0x1000, v10
	global_load_dwordx4 v[2:5], v[2:3], off offset:3168
	s_nop 0
	global_load_dwordx4 v[6:9], v[6:7], off offset:3168
	v_addc_co_u32_e32 v15, vcc, 0, v11, vcc
	global_load_dwordx4 v[10:13], v[12:13], off offset:3168
	s_nop 0
	global_load_dwordx4 v[14:17], v[14:15], off offset:3168
	s_lshl_b32 s87, s87, 6
	s_waitcnt lgkmcnt(0)
	s_barrier
	s_waitcnt vmcnt(20)
	ds_write_b32 v174, v170
	ds_write_b32 v175, v171
	ds_write_b32 v176, v172
	ds_write_b32 v177, v173
	s_waitcnt lgkmcnt(0)
	s_barrier
	ds_read2st64_b32 v[100:101], v60 offset1:1
	ds_read2st64_b32 v[102:103], v60 offset0:2 offset1:3
	ds_read2st64_b32 v[104:105], v60 offset0:4 offset1:5
	ds_read2st64_b32 v[106:107], v60 offset0:6 offset1:7
	ds_read2st64_b32 v[108:109], v60 offset0:8 offset1:9
	ds_read2st64_b32 v[110:111], v60 offset0:10 offset1:11
	ds_read2st64_b32 v[112:113], v60 offset0:12 offset1:13
	ds_read2st64_b32 v[114:115], v60 offset0:14 offset1:15
	v_lshl_add_u32 v143, v90, 2, s4
	ds_read2st64_b32 v[116:117], v143 offset1:1
	ds_read2st64_b32 v[118:119], v143 offset0:2 offset1:3
	ds_read2st64_b32 v[120:121], v143 offset0:4 offset1:5
	ds_read2st64_b32 v[122:123], v143 offset0:6 offset1:7
	ds_read2st64_b32 v[124:125], v143 offset0:8 offset1:9
	ds_read2st64_b32 v[126:127], v143 offset0:10 offset1:11
	ds_read2st64_b32 v[128:129], v143 offset0:12 offset1:13
	ds_read2st64_b32 v[130:131], v143 offset0:14 offset1:15
	s_waitcnt vmcnt(12)
	s_waitcnt lgkmcnt(0)
	v_lshl_add_u32 v143, v91, 2, s4
	ds_read2st64_b32 v[204:205], v143 offset1:1
	ds_read2st64_b32 v[206:207], v143 offset0:2 offset1:3
	ds_read2st64_b32 v[208:209], v143 offset0:4 offset1:5
	ds_read2st64_b32 v[210:211], v143 offset0:6 offset1:7
	ds_read2st64_b32 v[212:213], v143 offset0:8 offset1:9
	ds_read2st64_b32 v[214:215], v143 offset0:10 offset1:11
	ds_read2st64_b32 v[216:217], v143 offset0:12 offset1:13
	ds_read2st64_b32 v[218:219], v143 offset0:14 offset1:15
	v_fmac_f32_e32 v132, v100, v116
	v_fmac_f32_e32 v132, v101, v117
	v_fmac_f32_e32 v132, v102, v118
	v_fmac_f32_e32 v132, v103, v119
	v_fmac_f32_e32 v132, v104, v120
	v_fmac_f32_e32 v132, v105, v121
	v_mul_f32_e32 v140, v106, v122
	v_mul_f32_e32 v141, v107, v123
	v_add_f32_e32 v132, v132, v140
	v_add_f32_e32 v132, v132, v141
	v_mul_f32_e32 v140, v108, v124
	v_mul_f32_e32 v141, v109, v125
	v_add_f32_e32 v132, v132, v140
	v_add_f32_e32 v132, v132, v141
	v_mul_f32_e32 v140, v110, v126
	v_mul_f32_e32 v141, v111, v127
	v_add_f32_e32 v132, v132, v140
	v_add_f32_e32 v132, v132, v141
	v_mul_f32_e32 v140, v112, v128
	v_mul_f32_e32 v141, v113, v129
	v_add_f32_e32 v132, v132, v140
	v_add_f32_e32 v132, v132, v141
	v_mul_f32_e32 v140, v114, v130
	v_mul_f32_e32 v141, v115, v131
	v_add_f32_e32 v132, v132, v140
	v_add_f32_e32 v132, v132, v141
	s_mov_b32 s24, 0xbfb8aa3b
	v_min_f32_e32 v141, 0, v132
	v_mul_f32_e64 v140, |v132|, s24
	v_exp_f32_e32 v140, v140
	s_mov_b32 s24, 0x800000
	v_add_f32_e32 v140, 1.0, v140
	v_cmp_gt_f32_e32 vcc, s24, v140
	s_mov_b32 s24, 0x3f317217
	s_nop 0
	v_cndmask_b32_e64 v142, 0, 32, vcc
	v_ldexp_f32 v140, v140, v142
	v_log_f32_e32 v140, v140
	s_nop 0
	v_mul_f32_e32 v142, 0x3f317217, v140
	v_fma_f32 v142, v140, s24, -v142
	v_fmac_f32_e32 v142, 0x3377d1cf, v140
	s_mov_b32 s24, 0x7f800000
	v_fmac_f32_e32 v142, 0x3f317217, v140
	v_cmp_lt_f32_e64 s[24:25], |v140|, s24
	s_nop 1
	v_cndmask_b32_e64 v140, v140, v142, s[24:25]
	v_cndmask_b32_e32 v142, 0, v183, vcc
	v_sub_f32_e32 v140, v140, v142
	v_sub_f32_e32 v140, v141, v140
	v_mul_f32_e32 v142, 0x3d800000, v140
	v_mad_u64_u32 v[144:145], s[24:25], v90, s51, v[18:19]
	ds_write_b32 v144, v142
	s_waitcnt lgkmcnt(1)
	v_lshl_add_u32 v143, v92, 2, s4
	ds_read2st64_b32 v[116:117], v143 offset1:1
	ds_read2st64_b32 v[118:119], v143 offset0:2 offset1:3
	ds_read2st64_b32 v[120:121], v143 offset0:4 offset1:5
	ds_read2st64_b32 v[122:123], v143 offset0:6 offset1:7
	ds_read2st64_b32 v[124:125], v143 offset0:8 offset1:9
	ds_read2st64_b32 v[126:127], v143 offset0:10 offset1:11
	ds_read2st64_b32 v[128:129], v143 offset0:12 offset1:13
	ds_read2st64_b32 v[130:131], v143 offset0:14 offset1:15
	v_fmac_f32_e32 v133, v100, v204
	v_fmac_f32_e32 v133, v101, v205
	v_fmac_f32_e32 v133, v102, v206
	v_fmac_f32_e32 v133, v103, v207
	v_fmac_f32_e32 v133, v104, v208
	v_fmac_f32_e32 v133, v105, v209
	v_mul_f32_e32 v140, v106, v210
	v_mul_f32_e32 v141, v107, v211
	v_add_f32_e32 v133, v133, v140
	v_add_f32_e32 v133, v133, v141
	v_mul_f32_e32 v140, v108, v212
	v_mul_f32_e32 v141, v109, v213
	v_add_f32_e32 v133, v133, v140
	v_add_f32_e32 v133, v133, v141
	v_mul_f32_e32 v140, v110, v214
	v_mul_f32_e32 v141, v111, v215
	v_add_f32_e32 v133, v133, v140
	v_add_f32_e32 v133, v133, v141
	v_mul_f32_e32 v140, v112, v216
	v_mul_f32_e32 v141, v113, v217
	v_add_f32_e32 v133, v133, v140
	v_add_f32_e32 v133, v133, v141
	v_mul_f32_e32 v140, v114, v218
	v_mul_f32_e32 v141, v115, v219
	v_add_f32_e32 v133, v133, v140
	v_add_f32_e32 v133, v133, v141
	s_mov_b32 s24, 0xbfb8aa3b
	v_min_f32_e32 v141, 0, v133
	v_mul_f32_e64 v140, |v133|, s24
	v_exp_f32_e32 v140, v140
	s_mov_b32 s24, 0x800000
	v_add_f32_e32 v140, 1.0, v140
	v_cmp_gt_f32_e32 vcc, s24, v140
	s_mov_b32 s24, 0x3f317217
	s_nop 0
	v_cndmask_b32_e64 v142, 0, 32, vcc
	v_ldexp_f32 v140, v140, v142
	v_log_f32_e32 v140, v140
	s_nop 0
	v_mul_f32_e32 v142, 0x3f317217, v140
	v_fma_f32 v142, v140, s24, -v142
	v_fmac_f32_e32 v142, 0x3377d1cf, v140
	s_mov_b32 s24, 0x7f800000
	v_fmac_f32_e32 v142, 0x3f317217, v140
	v_cmp_lt_f32_e64 s[24:25], |v140|, s24
	s_nop 1
	v_cndmask_b32_e64 v140, v140, v142, s[24:25]
	v_cndmask_b32_e32 v142, 0, v183, vcc
	v_sub_f32_e32 v140, v140, v142
	v_sub_f32_e32 v140, v141, v140
	v_mul_f32_e32 v142, 0x3d800000, v140
	v_mad_u64_u32 v[144:145], s[24:25], v91, s51, v[18:19]
	ds_write_b32 v144, v142
	s_waitcnt lgkmcnt(1)
	v_lshl_add_u32 v143, v93, 2, s4
	ds_read2st64_b32 v[204:205], v143 offset1:1
	ds_read2st64_b32 v[206:207], v143 offset0:2 offset1:3
	ds_read2st64_b32 v[208:209], v143 offset0:4 offset1:5
	ds_read2st64_b32 v[210:211], v143 offset0:6 offset1:7
	ds_read2st64_b32 v[212:213], v143 offset0:8 offset1:9
	ds_read2st64_b32 v[214:215], v143 offset0:10 offset1:11
	ds_read2st64_b32 v[216:217], v143 offset0:12 offset1:13
	ds_read2st64_b32 v[218:219], v143 offset0:14 offset1:15
	v_fmac_f32_e32 v134, v100, v116
	v_fmac_f32_e32 v134, v101, v117
	v_fmac_f32_e32 v134, v102, v118
	v_fmac_f32_e32 v134, v103, v119
	v_fmac_f32_e32 v134, v104, v120
	v_fmac_f32_e32 v134, v105, v121
	v_mul_f32_e32 v140, v106, v122
	v_mul_f32_e32 v141, v107, v123
	v_add_f32_e32 v134, v134, v140
	v_add_f32_e32 v134, v134, v141
	v_mul_f32_e32 v140, v108, v124
	v_mul_f32_e32 v141, v109, v125
	v_add_f32_e32 v134, v134, v140
	v_add_f32_e32 v134, v134, v141
	v_mul_f32_e32 v140, v110, v126
	v_mul_f32_e32 v141, v111, v127
	v_add_f32_e32 v134, v134, v140
	v_add_f32_e32 v134, v134, v141
	v_mul_f32_e32 v140, v112, v128
	v_mul_f32_e32 v141, v113, v129
	v_add_f32_e32 v134, v134, v140
	v_add_f32_e32 v134, v134, v141
	v_mul_f32_e32 v140, v114, v130
	v_mul_f32_e32 v141, v115, v131
	v_add_f32_e32 v134, v134, v140
	v_add_f32_e32 v134, v134, v141
	s_mov_b32 s24, 0xbfb8aa3b
	v_min_f32_e32 v141, 0, v134
	v_mul_f32_e64 v140, |v134|, s24
	v_exp_f32_e32 v140, v140
	s_mov_b32 s24, 0x800000
	v_add_f32_e32 v140, 1.0, v140
	v_cmp_gt_f32_e32 vcc, s24, v140
	s_mov_b32 s24, 0x3f317217
	s_nop 0
	v_cndmask_b32_e64 v142, 0, 32, vcc
	v_ldexp_f32 v140, v140, v142
	v_log_f32_e32 v140, v140
	s_nop 0
	v_mul_f32_e32 v142, 0x3f317217, v140
	v_fma_f32 v142, v140, s24, -v142
	v_fmac_f32_e32 v142, 0x3377d1cf, v140
	s_mov_b32 s24, 0x7f800000
	v_fmac_f32_e32 v142, 0x3f317217, v140
	v_cmp_lt_f32_e64 s[24:25], |v140|, s24
	s_nop 1
	v_cndmask_b32_e64 v140, v140, v142, s[24:25]
	v_cndmask_b32_e32 v142, 0, v183, vcc
	v_sub_f32_e32 v140, v140, v142
	v_sub_f32_e32 v140, v141, v140
	v_mul_f32_e32 v142, 0x3d800000, v140
	v_mad_u64_u32 v[144:145], s[24:25], v92, s51, v[18:19]
	ds_write_b32 v144, v142
	s_waitcnt lgkmcnt(1)
	v_lshl_add_u32 v143, v94, 2, s4
	ds_read2st64_b32 v[116:117], v143 offset1:1
	ds_read2st64_b32 v[118:119], v143 offset0:2 offset1:3
	ds_read2st64_b32 v[120:121], v143 offset0:4 offset1:5
	ds_read2st64_b32 v[122:123], v143 offset0:6 offset1:7
	ds_read2st64_b32 v[124:125], v143 offset0:8 offset1:9
	ds_read2st64_b32 v[126:127], v143 offset0:10 offset1:11
	ds_read2st64_b32 v[128:129], v143 offset0:12 offset1:13
	ds_read2st64_b32 v[130:131], v143 offset0:14 offset1:15
	v_fmac_f32_e32 v135, v100, v204
	v_fmac_f32_e32 v135, v101, v205
	v_fmac_f32_e32 v135, v102, v206
	v_fmac_f32_e32 v135, v103, v207
	v_fmac_f32_e32 v135, v104, v208
	v_fmac_f32_e32 v135, v105, v209
	v_mul_f32_e32 v140, v106, v210
	v_mul_f32_e32 v141, v107, v211
	v_add_f32_e32 v135, v135, v140
	v_add_f32_e32 v135, v135, v141
	v_mul_f32_e32 v140, v108, v212
	v_mul_f32_e32 v141, v109, v213
	v_add_f32_e32 v135, v135, v140
	v_add_f32_e32 v135, v135, v141
	v_mul_f32_e32 v140, v110, v214
	v_mul_f32_e32 v141, v111, v215
	v_add_f32_e32 v135, v135, v140
	v_add_f32_e32 v135, v135, v141
	v_mul_f32_e32 v140, v112, v216
	v_mul_f32_e32 v141, v113, v217
	v_add_f32_e32 v135, v135, v140
	v_add_f32_e32 v135, v135, v141
	v_mul_f32_e32 v140, v114, v218
	v_mul_f32_e32 v141, v115, v219
	v_add_f32_e32 v135, v135, v140
	v_add_f32_e32 v135, v135, v141
	s_mov_b32 s24, 0xbfb8aa3b
	v_min_f32_e32 v141, 0, v135
	v_mul_f32_e64 v140, |v135|, s24
	v_exp_f32_e32 v140, v140
	s_mov_b32 s24, 0x800000
	v_add_f32_e32 v140, 1.0, v140
	v_cmp_gt_f32_e32 vcc, s24, v140
	s_mov_b32 s24, 0x3f317217
	s_nop 0
	v_cndmask_b32_e64 v142, 0, 32, vcc
	v_ldexp_f32 v140, v140, v142
	v_log_f32_e32 v140, v140
	s_nop 0
	v_mul_f32_e32 v142, 0x3f317217, v140
	v_fma_f32 v142, v140, s24, -v142
	v_fmac_f32_e32 v142, 0x3377d1cf, v140
	s_mov_b32 s24, 0x7f800000
	v_fmac_f32_e32 v142, 0x3f317217, v140
	v_cmp_lt_f32_e64 s[24:25], |v140|, s24
	s_nop 1
	v_cndmask_b32_e64 v140, v140, v142, s[24:25]
	v_cndmask_b32_e32 v142, 0, v183, vcc
	v_sub_f32_e32 v140, v140, v142
	v_sub_f32_e32 v140, v141, v140
	v_mul_f32_e32 v142, 0x3d800000, v140
	v_mad_u64_u32 v[144:145], s[24:25], v93, s51, v[18:19]
	ds_write_b32 v144, v142
	s_waitcnt lgkmcnt(1)
	v_lshl_add_u32 v143, v95, 2, s4
	ds_read2st64_b32 v[204:205], v143 offset1:1
	ds_read2st64_b32 v[206:207], v143 offset0:2 offset1:3
	ds_read2st64_b32 v[208:209], v143 offset0:4 offset1:5
	ds_read2st64_b32 v[210:211], v143 offset0:6 offset1:7
	ds_read2st64_b32 v[212:213], v143 offset0:8 offset1:9
	ds_read2st64_b32 v[214:215], v143 offset0:10 offset1:11
	ds_read2st64_b32 v[216:217], v143 offset0:12 offset1:13
	ds_read2st64_b32 v[218:219], v143 offset0:14 offset1:15
	v_fmac_f32_e32 v136, v100, v116
	v_fmac_f32_e32 v136, v101, v117
	v_fmac_f32_e32 v136, v102, v118
	v_fmac_f32_e32 v136, v103, v119
	v_fmac_f32_e32 v136, v104, v120
	v_fmac_f32_e32 v136, v105, v121
	v_mul_f32_e32 v140, v106, v122
	v_mul_f32_e32 v141, v107, v123
	v_add_f32_e32 v136, v136, v140
	v_add_f32_e32 v136, v136, v141
	v_mul_f32_e32 v140, v108, v124
	v_mul_f32_e32 v141, v109, v125
	v_add_f32_e32 v136, v136, v140
	v_add_f32_e32 v136, v136, v141
	v_mul_f32_e32 v140, v110, v126
	v_mul_f32_e32 v141, v111, v127
	v_add_f32_e32 v136, v136, v140
	v_add_f32_e32 v136, v136, v141
	v_mul_f32_e32 v140, v112, v128
	v_mul_f32_e32 v141, v113, v129
	v_add_f32_e32 v136, v136, v140
	v_add_f32_e32 v136, v136, v141
	v_mul_f32_e32 v140, v114, v130
	v_mul_f32_e32 v141, v115, v131
	v_add_f32_e32 v136, v136, v140
	v_add_f32_e32 v136, v136, v141
	s_mov_b32 s24, 0xbfb8aa3b
	v_min_f32_e32 v141, 0, v136
	v_mul_f32_e64 v140, |v136|, s24
	v_exp_f32_e32 v140, v140
	s_mov_b32 s24, 0x800000
	v_add_f32_e32 v140, 1.0, v140
	v_cmp_gt_f32_e32 vcc, s24, v140
	s_mov_b32 s24, 0x3f317217
	s_nop 0
	v_cndmask_b32_e64 v142, 0, 32, vcc
	v_ldexp_f32 v140, v140, v142
	v_log_f32_e32 v140, v140
	s_nop 0
	v_mul_f32_e32 v142, 0x3f317217, v140
	v_fma_f32 v142, v140, s24, -v142
	v_fmac_f32_e32 v142, 0x3377d1cf, v140
	s_mov_b32 s24, 0x7f800000
	v_fmac_f32_e32 v142, 0x3f317217, v140
	v_cmp_lt_f32_e64 s[24:25], |v140|, s24
	s_nop 1
	v_cndmask_b32_e64 v140, v140, v142, s[24:25]
	v_cndmask_b32_e32 v142, 0, v183, vcc
	v_sub_f32_e32 v140, v140, v142
	v_sub_f32_e32 v140, v141, v140
	v_mul_f32_e32 v142, 0x3d800000, v140
	v_mad_u64_u32 v[144:145], s[24:25], v94, s51, v[18:19]
	ds_write_b32 v144, v142
	s_waitcnt lgkmcnt(1)
	v_lshl_add_u32 v143, v96, 2, s4
	ds_read2st64_b32 v[116:117], v143 offset1:1
	ds_read2st64_b32 v[118:119], v143 offset0:2 offset1:3
	ds_read2st64_b32 v[120:121], v143 offset0:4 offset1:5
	ds_read2st64_b32 v[122:123], v143 offset0:6 offset1:7
	ds_read2st64_b32 v[124:125], v143 offset0:8 offset1:9
	ds_read2st64_b32 v[126:127], v143 offset0:10 offset1:11
	ds_read2st64_b32 v[128:129], v143 offset0:12 offset1:13
	ds_read2st64_b32 v[130:131], v143 offset0:14 offset1:15
	v_fmac_f32_e32 v137, v100, v204
	v_fmac_f32_e32 v137, v101, v205
	v_fmac_f32_e32 v137, v102, v206
	v_fmac_f32_e32 v137, v103, v207
	v_fmac_f32_e32 v137, v104, v208
	v_fmac_f32_e32 v137, v105, v209
	v_mul_f32_e32 v140, v106, v210
	v_mul_f32_e32 v141, v107, v211
	v_add_f32_e32 v137, v137, v140
	v_add_f32_e32 v137, v137, v141
	v_mul_f32_e32 v140, v108, v212
	v_mul_f32_e32 v141, v109, v213
	v_add_f32_e32 v137, v137, v140
	v_add_f32_e32 v137, v137, v141
	v_mul_f32_e32 v140, v110, v214
	v_mul_f32_e32 v141, v111, v215
	v_add_f32_e32 v137, v137, v140
	v_add_f32_e32 v137, v137, v141
	v_mul_f32_e32 v140, v112, v216
	v_mul_f32_e32 v141, v113, v217
	v_add_f32_e32 v137, v137, v140
	v_add_f32_e32 v137, v137, v141
	v_mul_f32_e32 v140, v114, v218
	v_mul_f32_e32 v141, v115, v219
	v_add_f32_e32 v137, v137, v140
	v_add_f32_e32 v137, v137, v141
	s_mov_b32 s24, 0xbfb8aa3b
	v_min_f32_e32 v141, 0, v137
	v_mul_f32_e64 v140, |v137|, s24
	v_exp_f32_e32 v140, v140
	s_mov_b32 s24, 0x800000
	v_add_f32_e32 v140, 1.0, v140
	v_cmp_gt_f32_e32 vcc, s24, v140
	s_mov_b32 s24, 0x3f317217
	s_nop 0
	v_cndmask_b32_e64 v142, 0, 32, vcc
	v_ldexp_f32 v140, v140, v142
	v_log_f32_e32 v140, v140
	s_nop 0
	v_mul_f32_e32 v142, 0x3f317217, v140
	v_fma_f32 v142, v140, s24, -v142
	v_fmac_f32_e32 v142, 0x3377d1cf, v140
	s_mov_b32 s24, 0x7f800000
	v_fmac_f32_e32 v142, 0x3f317217, v140
	v_cmp_lt_f32_e64 s[24:25], |v140|, s24
	s_nop 1
	v_cndmask_b32_e64 v140, v140, v142, s[24:25]
	v_cndmask_b32_e32 v142, 0, v183, vcc
	v_sub_f32_e32 v140, v140, v142
	v_sub_f32_e32 v140, v141, v140
	v_mul_f32_e32 v142, 0x3d800000, v140
	v_mad_u64_u32 v[144:145], s[24:25], v95, s51, v[18:19]
	ds_write_b32 v144, v142
	s_waitcnt lgkmcnt(1)
	v_lshl_add_u32 v143, v97, 2, s4
	ds_read2st64_b32 v[204:205], v143 offset1:1
	ds_read2st64_b32 v[206:207], v143 offset0:2 offset1:3
	ds_read2st64_b32 v[208:209], v143 offset0:4 offset1:5
	ds_read2st64_b32 v[210:211], v143 offset0:6 offset1:7
	ds_read2st64_b32 v[212:213], v143 offset0:8 offset1:9
	ds_read2st64_b32 v[214:215], v143 offset0:10 offset1:11
	ds_read2st64_b32 v[216:217], v143 offset0:12 offset1:13
	ds_read2st64_b32 v[218:219], v143 offset0:14 offset1:15
	v_fmac_f32_e32 v138, v100, v116
	v_fmac_f32_e32 v138, v101, v117
	v_fmac_f32_e32 v138, v102, v118
	v_fmac_f32_e32 v138, v103, v119
	v_fmac_f32_e32 v138, v104, v120
	v_fmac_f32_e32 v138, v105, v121
	v_mul_f32_e32 v140, v106, v122
	v_mul_f32_e32 v141, v107, v123
	v_add_f32_e32 v138, v138, v140
	v_add_f32_e32 v138, v138, v141
	v_mul_f32_e32 v140, v108, v124
	v_mul_f32_e32 v141, v109, v125
	v_add_f32_e32 v138, v138, v140
	v_add_f32_e32 v138, v138, v141
	v_mul_f32_e32 v140, v110, v126
	v_mul_f32_e32 v141, v111, v127
	v_add_f32_e32 v138, v138, v140
	v_add_f32_e32 v138, v138, v141
	v_mul_f32_e32 v140, v112, v128
	v_mul_f32_e32 v141, v113, v129
	v_add_f32_e32 v138, v138, v140
	v_add_f32_e32 v138, v138, v141
	v_mul_f32_e32 v140, v114, v130
	v_mul_f32_e32 v141, v115, v131
	v_add_f32_e32 v138, v138, v140
	v_add_f32_e32 v138, v138, v141
	s_mov_b32 s24, 0xbfb8aa3b
	v_min_f32_e32 v141, 0, v138
	v_mul_f32_e64 v140, |v138|, s24
	v_exp_f32_e32 v140, v140
	s_mov_b32 s24, 0x800000
	v_add_f32_e32 v140, 1.0, v140
	v_cmp_gt_f32_e32 vcc, s24, v140
	s_mov_b32 s24, 0x3f317217
	s_nop 0
	v_cndmask_b32_e64 v142, 0, 32, vcc
	v_ldexp_f32 v140, v140, v142
	v_log_f32_e32 v140, v140
	s_nop 0
	v_mul_f32_e32 v142, 0x3f317217, v140
	v_fma_f32 v142, v140, s24, -v142
	v_fmac_f32_e32 v142, 0x3377d1cf, v140
	s_mov_b32 s24, 0x7f800000
	v_fmac_f32_e32 v142, 0x3f317217, v140
	v_cmp_lt_f32_e64 s[24:25], |v140|, s24
	s_nop 1
	v_cndmask_b32_e64 v140, v140, v142, s[24:25]
	v_cndmask_b32_e32 v142, 0, v183, vcc
	v_sub_f32_e32 v140, v140, v142
	v_sub_f32_e32 v140, v141, v140
	v_mul_f32_e32 v142, 0x3d800000, v140
	v_mad_u64_u32 v[144:145], s[24:25], v96, s51, v[18:19]
	ds_write_b32 v144, v142
	s_waitcnt lgkmcnt(1)
	v_fmac_f32_e32 v139, v100, v204
	v_fmac_f32_e32 v139, v101, v205
	v_fmac_f32_e32 v139, v102, v206
	v_fmac_f32_e32 v139, v103, v207
	v_fmac_f32_e32 v139, v104, v208
	v_fmac_f32_e32 v139, v105, v209
	v_mul_f32_e32 v140, v106, v210
	v_mul_f32_e32 v141, v107, v211
	v_add_f32_e32 v139, v139, v140
	v_add_f32_e32 v139, v139, v141
	v_mul_f32_e32 v140, v108, v212
	v_mul_f32_e32 v141, v109, v213
	v_add_f32_e32 v139, v139, v140
	v_add_f32_e32 v139, v139, v141
	v_mul_f32_e32 v140, v110, v214
	v_mul_f32_e32 v141, v111, v215
	v_add_f32_e32 v139, v139, v140
	v_add_f32_e32 v139, v139, v141
	v_mul_f32_e32 v140, v112, v216
	v_mul_f32_e32 v141, v113, v217
	v_add_f32_e32 v139, v139, v140
	v_add_f32_e32 v139, v139, v141
	v_mul_f32_e32 v140, v114, v218
	v_mul_f32_e32 v141, v115, v219
	v_add_f32_e32 v139, v139, v140
	v_add_f32_e32 v139, v139, v141
	s_mov_b32 s24, 0xbfb8aa3b
	v_min_f32_e32 v141, 0, v139
	v_mul_f32_e64 v140, |v139|, s24
	v_exp_f32_e32 v140, v140
	s_mov_b32 s24, 0x800000
	v_add_f32_e32 v140, 1.0, v140
	v_cmp_gt_f32_e32 vcc, s24, v140
	s_mov_b32 s24, 0x3f317217
	s_nop 0
	v_cndmask_b32_e64 v142, 0, 32, vcc
	v_ldexp_f32 v140, v140, v142
	v_log_f32_e32 v140, v140
	s_nop 0
	v_mul_f32_e32 v142, 0x3f317217, v140
	v_fma_f32 v142, v140, s24, -v142
	v_fmac_f32_e32 v142, 0x3377d1cf, v140
	s_mov_b32 s24, 0x7f800000
	v_fmac_f32_e32 v142, 0x3f317217, v140
	v_cmp_lt_f32_e64 s[24:25], |v140|, s24
	s_nop 1
	v_cndmask_b32_e64 v140, v140, v142, s[24:25]
	v_cndmask_b32_e32 v142, 0, v183, vcc
	v_sub_f32_e32 v140, v140, v142
	v_sub_f32_e32 v140, v141, v140
	v_mul_f32_e32 v142, 0x3d800000, v140
	v_mad_u64_u32 v[144:145], s[24:25], v97, s51, v[18:19]
	ds_write_b32 v144, v142
	s_waitcnt vmcnt(0)

.LBB0_1622:
	s_load_dwordx4 s[92:95], s[0:1], 0xd0
	v_mov_b32_e32 v18, v0
	s_add_i32 s2, s40, 0xffffff70
	v_readlane_b32 s50, v228, 15
	s_cmp_lt_u32 s2, 64
	v_readfirstlane_b32 s2, v18
	v_readlane_b32 s97, v228, 14
	v_readlane_b32 s51, v228, 16
	s_cbranch_scc0 .LBB0_1636
	s_lshl_b32 s3, s40, 4
	s_and_b32 s12, s3, 0xf00
	s_and_b32 s5, s40, 15
	s_addk_i32 s12, 0xf700
	s_lshl_b32 s6, s12, 4
	s_lshl_b32 s7, s5, 6
	s_or_b32 s6, s7, s6
	s_lshr_b32 s3, s12, 7
	s_and_b32 s10, s6, 0x7fffe3c0
	v_ashrrev_i32_e32 v19, 6, v18
	s_and_b32 s3, s3, 2
	s_waitcnt lgkmcnt(0)
	v_add_u32_e32 v2, s10, v19
	s_movk_i32 s11, 0x3000
	v_mov_b64_e32 v[10:11], s[46:47]
	v_add_u32_e32 v24, 0x200, v18
	v_and_b32_e32 v26, 63, v18
	s_mov_b32 s7, 0
	v_mad_i64_i32 v[2:3], s[8:9], v2, s11, v[10:11]
	s_lshl_b32 s6, s3, 8
	v_ashrrev_i32_e32 v29, 6, v24
	v_mov_b32_e32 v23, 0
	v_lshl_add_u64 v[2:3], v[2:3], 0, s[6:7]
	v_lshlrev_b32_e32 v22, 2, v26
	v_add_u32_e32 v4, s10, v29
	v_add_u32_e32 v25, 0x400, v18
	v_lshl_add_u64 v[2:3], v[2:3], 0, v[22:23]
	s_movk_i32 s13, 0x1000
	v_mad_i64_i32 v[4:5], s[8:9], v4, s11, v[10:11]
	v_ashrrev_i32_e32 v33, 6, v25
	v_add_co_u32_e32 v2, vcc, s13, v2
	v_lshl_add_u64 v[4:5], v[4:5], 0, s[6:7]
	v_add_u32_e32 v6, s10, v33
	v_add_u32_e32 v43, 0x600, v18
	v_addc_co_u32_e32 v3, vcc, 0, v3, vcc
	v_lshl_add_u64 v[4:5], v[4:5], 0, v[22:23]
	v_mad_i64_i32 v[6:7], s[8:9], v6, s11, v[10:11]
	v_ashrrev_i32_e32 v30, 6, v43
	v_add_co_u32_e32 v4, vcc, s13, v4
	v_lshl_add_u64 v[6:7], v[6:7], 0, s[6:7]
	v_add_u32_e32 v8, s10, v30
	v_add_u32_e32 v12, 0x800, v18
	v_addc_co_u32_e32 v5, vcc, 0, v5, vcc
	v_lshl_add_u64 v[6:7], v[6:7], 0, v[22:23]
	v_mad_i64_i32 v[8:9], s[8:9], v8, s11, v[10:11]
	v_ashrrev_i32_e32 v32, 6, v12
	v_add_co_u32_e32 v6, vcc, s13, v6
	v_lshl_add_u64 v[8:9], v[8:9], 0, s[6:7]
	v_add_u32_e32 v12, s10, v32
	v_add_u32_e32 v14, 0xa00, v18
	v_addc_co_u32_e32 v7, vcc, 0, v7, vcc
	v_lshl_add_u64 v[8:9], v[8:9], 0, v[22:23]
	v_mad_i64_i32 v[12:13], s[8:9], v12, s11, v[10:11]
	v_ashrrev_i32_e32 v28, 6, v14
	v_add_co_u32_e32 v8, vcc, s13, v8
	v_lshl_add_u64 v[12:13], v[12:13], 0, s[6:7]
	v_add_u32_e32 v14, s10, v28
	v_add_u32_e32 v16, 0xc00, v18
	v_addc_co_u32_e32 v9, vcc, 0, v9, vcc
	v_lshl_add_u64 v[12:13], v[12:13], 0, v[22:23]
	v_mad_i64_i32 v[14:15], s[8:9], v14, s11, v[10:11]
	v_ashrrev_i32_e32 v31, 6, v16
	v_add_co_u32_e32 v12, vcc, s13, v12
	v_lshl_add_u64 v[14:15], v[14:15], 0, s[6:7]
	v_add_u32_e32 v16, s10, v31
	v_add_u32_e32 v20, 0xe00, v18
	v_addc_co_u32_e32 v13, vcc, 0, v13, vcc
	v_lshl_add_u64 v[14:15], v[14:15], 0, v[22:23]
	v_mad_i64_i32 v[16:17], s[8:9], v16, s11, v[10:11]
	v_ashrrev_i32_e32 v27, 6, v20
	v_add_co_u32_e32 v14, vcc, s13, v14
	v_lshl_add_u64 v[16:17], v[16:17], 0, s[6:7]
	v_add_u32_e32 v20, s10, v27
	v_addc_co_u32_e32 v15, vcc, 0, v15, vcc
	v_lshl_add_u64 v[16:17], v[16:17], 0, v[22:23]
	v_mad_i64_i32 v[20:21], s[8:9], v20, s11, v[10:11]
	v_add_co_u32_e32 v16, vcc, s13, v16
	v_lshl_add_u64 v[20:21], v[20:21], 0, s[6:7]
	s_nop 0
	v_addc_co_u32_e32 v17, vcc, 0, v17, vcc
	v_lshl_add_u64 v[20:21], v[20:21], 0, v[22:23]
	v_add_co_u32_e32 v20, vcc, s13, v20
	v_lshlrev_b32_e32 v35, 2, v18
	s_nop 0
	v_addc_co_u32_e32 v21, vcc, 0, v21, vcc
	global_load_dword v42, v[2:3], off offset:2144
	global_load_dword v41, v[4:5], off offset:2144
	global_load_dword v40, v[6:7], off offset:2144
	global_load_dword v39, v[8:9], off offset:2144
	global_load_dword v38, v[12:13], off offset:2144
	global_load_dword v37, v[14:15], off offset:2144
	global_load_dword v36, v[16:17], off offset:2144
	global_load_dword v34, v[20:21], off offset:2144
	v_ashrrev_i32_e32 v2, 5, v18
	v_and_b32_e32 v4, 0x7c, v35
	v_add_u32_e32 v2, s10, v2
	v_mad_i64_i32 v[2:3], s[8:9], v2, s11, v[10:11]
	s_lshl_b32 s6, s3, 9
	v_lshlrev_b32_e32 v20, 2, v4
	v_ashrrev_i32_e32 v4, 5, v24
	v_lshl_add_u64 v[2:3], v[2:3], 0, s[6:7]
	v_mov_b32_e32 v21, v23
	v_add_u32_e32 v4, s10, v4
	v_lshl_add_u64 v[2:3], v[2:3], 0, v[20:21]
	v_mad_i64_i32 v[4:5], s[8:9], v4, s11, v[10:11]
	v_ashrrev_i32_e32 v12, 5, v25
	v_add_co_u32_e32 v2, vcc, s13, v2
	v_lshl_add_u64 v[4:5], v[4:5], 0, s[6:7]
	v_add_u32_e32 v12, s10, v12
	v_addc_co_u32_e32 v3, vcc, 0, v3, vcc
	v_lshl_add_u64 v[4:5], v[4:5], 0, v[20:21]
	v_mad_i64_i32 v[12:13], s[8:9], v12, s11, v[10:11]
	v_ashrrev_i32_e32 v14, 5, v43
	v_add_co_u32_e32 v6, vcc, s13, v4
	v_lshl_add_u64 v[12:13], v[12:13], 0, s[6:7]
	v_add_u32_e32 v14, s10, v14
	v_addc_co_u32_e32 v7, vcc, 0, v5, vcc
	v_lshl_add_u64 v[12:13], v[12:13], 0, v[20:21]
	v_mad_i64_i32 v[10:11], s[8:9], v14, s11, v[10:11]
	v_add_co_u32_e32 v12, vcc, s13, v12
	v_lshl_add_u64 v[10:11], v[10:11], 0, s[6:7]
	s_nop 0
	v_addc_co_u32_e32 v13, vcc, 0, v13, vcc
	v_lshl_add_u64 v[10:11], v[10:11], 0, v[20:21]
	v_add_co_u32_e32 v14, vcc, 0x1000, v10
	global_load_dwordx4 v[2:5], v[2:3], off offset:3168
	s_nop 0
	global_load_dwordx4 v[6:9], v[6:7], off offset:3168
	v_addc_co_u32_e32 v15, vcc, 0, v11, vcc
	global_load_dwordx4 v[10:13], v[12:13], off offset:3168
	s_nop 0
	global_load_dwordx4 v[14:17], v[14:15], off offset:3168
	s_movk_i32 s6, 0x400
	s_lshl_b32 s3, s3, 6
	v_cmp_gt_i32_e32 vcc, s6, v18
	s_load_dwordx2 s[98:99], s[0:1], 0x98
	s_load_dwordx2 s[100:101], s[0:1], 0xa0
	v_and_b32_e32 v150, 15, v18
	v_readlane_b32 s8, v228, 27
	v_lshlrev_b32_e32 v152, 2, v150
	v_mov_b32_e32 v153, 0
	v_readlane_b32 s9, v228, 28
	s_nop 1
	v_lshl_add_u64 v[178:179], s[8:9], 0, v[152:153]
	v_readlane_b32 s8, v228, 19
	s_nop 1
	v_lshl_add_u32 v146, v150, 8, s8
	v_add_u32_e32 v147, s8, v22
	v_add_u32_e32 v148, s96, v22
	v_mov_b32_e32 v149, 0x41b17218
	v_ashrrev_i32_e32 v150, 4, v18
	v_add_u32_e32 v152, s10, v150
	v_mad_i64_i32 v[152:153], vcc, v152, s11, v[178:179]
	global_load_dword v170, v[152:153], off
	v_add_u32_e32 v151, 0x200, v18
	v_ashrrev_i32_e32 v151, 4, v151
	v_add_u32_e32 v154, s10, v151
	v_mad_i64_i32 v[154:155], vcc, v154, s11, v[178:179]
	global_load_dword v171, v[154:155], off
	v_lshl_add_u32 v174, v150, 2, v146
	v_lshl_add_u32 v175, v151, 2, v146
	s_waitcnt lgkmcnt(0)
	s_lshl_b32 s8, s3, 2
	s_mov_b32 s9, 0
	v_and_b32_e32 v156, 0xffffff00, v35
	v_ashrrev_i32_e32 v157, 31, v156
	v_lshl_add_u64 v[158:159], v[156:157], 2, s[98:99]
	v_lshl_add_u64 v[158:159], v[158:159], 0, s[8:9]
	v_lshl_add_u64 v[158:159], v[158:159], 0, v[22:23]
	global_load_dword v172, v[158:159], off
	v_add_u32_e32 v176, s4, v35
	v_add_u32_e32 v160, 0x800, v35
	v_and_b32_e32 v156, 0xffffff00, v160
	v_ashrrev_i32_e32 v157, 31, v156
	v_lshl_add_u64 v[162:163], v[156:157], 2, s[98:99]
	v_lshl_add_u64 v[162:163], v[162:163], 0, s[8:9]
	v_lshl_add_u64 v[162:163], v[162:163], 0, v[22:23]
	global_load_dword v173, v[162:163], off
	v_add_u32_e32 v177, s4, v160
	v_ashrrev_i32_e32 v90, 6, v18
	v_add_u32_e32 v164, s3, v90
	v_ashrrev_i32_e32 v165, 31, v164
	v_lshl_add_u64 v[166:167], v[164:165], 2, s[100:101]
	global_load_dword v132, v[166:167], off
	v_add_u32_e32 v164, 0x200, v18
	v_ashrrev_i32_e32 v91, 6, v164
	v_add_u32_e32 v164, s3, v91
	v_ashrrev_i32_e32 v165, 31, v164
	v_lshl_add_u64 v[166:167], v[164:165], 2, s[100:101]
	global_load_dword v133, v[166:167], off
	v_add_u32_e32 v164, 0x400, v18
	v_ashrrev_i32_e32 v92, 6, v164
	v_add_u32_e32 v164, s3, v92
	v_ashrrev_i32_e32 v165, 31, v164
	v_lshl_add_u64 v[166:167], v[164:165], 2, s[100:101]
	global_load_dword v134, v[166:167], off
	v_add_u32_e32 v164, 0x600, v18
	v_ashrrev_i32_e32 v93, 6, v164
	v_add_u32_e32 v164, s3, v93
	v_ashrrev_i32_e32 v165, 31, v164
	v_lshl_add_u64 v[166:167], v[164:165], 2, s[100:101]
	global_load_dword v135, v[166:167], off
	v_add_u32_e32 v164, 0x800, v18
	v_ashrrev_i32_e32 v94, 6, v164
	v_add_u32_e32 v164, s3, v94
	v_ashrrev_i32_e32 v165, 31, v164
	v_lshl_add_u64 v[166:167], v[164:165], 2, s[100:101]
	global_load_dword v136, v[166:167], off
	v_add_u32_e32 v164, 0xa00, v18
	v_ashrrev_i32_e32 v95, 6, v164
	v_add_u32_e32 v164, s3, v95
	v_ashrrev_i32_e32 v165, 31, v164
	v_lshl_add_u64 v[166:167], v[164:165], 2, s[100:101]
	global_load_dword v137, v[166:167], off
	v_add_u32_e32 v164, 0xc00, v18
	v_ashrrev_i32_e32 v96, 6, v164
	v_add_u32_e32 v164, s3, v96
	v_ashrrev_i32_e32 v165, 31, v164
	v_lshl_add_u64 v[166:167], v[164:165], 2, s[100:101]
	global_load_dword v138, v[166:167], off
	v_add_u32_e32 v164, 0xe00, v18
	v_ashrrev_i32_e32 v97, 6, v164
	v_add_u32_e32 v164, s3, v97
	v_ashrrev_i32_e32 v165, 31, v164
	v_lshl_add_u64 v[166:167], v[164:165], 2, s[100:101]
	global_load_dword v139, v[166:167], off
	s_waitcnt vmcnt(0) lgkmcnt(0)
	s_barrier
	s_or_b32 s16, s12, s5
	ds_write_b32 v174, v170
	ds_write_b32 v175, v171
	ds_write_b32 v176, v172
	ds_write_b32 v177, v173
	s_movk_i32 s15, 0x104
	s_waitcnt lgkmcnt(0)
	s_barrier
	ds_read2st64_b32 v[100:101], v147 offset1:1
	ds_read2st64_b32 v[102:103], v147 offset0:2 offset1:3
	ds_read2st64_b32 v[104:105], v147 offset0:4 offset1:5
	ds_read2st64_b32 v[106:107], v147 offset0:6 offset1:7
	ds_read2st64_b32 v[108:109], v147 offset0:8 offset1:9
	ds_read2st64_b32 v[110:111], v147 offset0:10 offset1:11
	ds_read2st64_b32 v[112:113], v147 offset0:12 offset1:13
	ds_read2st64_b32 v[114:115], v147 offset0:14 offset1:15
	v_lshl_add_u32 v143, v90, 2, s4
	ds_read2st64_b32 v[180:181], v143 offset1:1
	ds_read2st64_b32 v[182:183], v143 offset0:2 offset1:3
	ds_read2st64_b32 v[184:185], v143 offset0:4 offset1:5
	ds_read2st64_b32 v[186:187], v143 offset0:6 offset1:7
	ds_read2st64_b32 v[188:189], v143 offset0:8 offset1:9
	ds_read2st64_b32 v[190:191], v143 offset0:10 offset1:11
	ds_read2st64_b32 v[192:193], v143 offset0:12 offset1:13
	ds_read2st64_b32 v[194:195], v143 offset0:14 offset1:15
	s_waitcnt lgkmcnt(0)
	v_lshl_add_u32 v143, v91, 2, s4
	ds_read2st64_b32 v[204:205], v143 offset1:1
	ds_read2st64_b32 v[206:207], v143 offset0:2 offset1:3
	ds_read2st64_b32 v[208:209], v143 offset0:4 offset1:5
	ds_read2st64_b32 v[210:211], v143 offset0:6 offset1:7
	ds_read2st64_b32 v[212:213], v143 offset0:8 offset1:9
	ds_read2st64_b32 v[214:215], v143 offset0:10 offset1:11
	ds_read2st64_b32 v[216:217], v143 offset0:12 offset1:13
	ds_read2st64_b32 v[218:219], v143 offset0:14 offset1:15
	v_fmac_f32_e32 v132, v100, v180
	v_fmac_f32_e32 v132, v101, v181
	v_fmac_f32_e32 v132, v102, v182
	v_fmac_f32_e32 v132, v103, v183
	v_fmac_f32_e32 v132, v104, v184
	v_fmac_f32_e32 v132, v105, v185
	v_mul_f32_e32 v140, v106, v186
	v_mul_f32_e32 v141, v107, v187
	v_add_f32_e32 v132, v132, v140
	v_add_f32_e32 v132, v132, v141
	v_mul_f32_e32 v140, v108, v188
	v_mul_f32_e32 v141, v109, v189
	v_add_f32_e32 v132, v132, v140
	v_add_f32_e32 v132, v132, v141
	v_mul_f32_e32 v140, v110, v190
	v_mul_f32_e32 v141, v111, v191
	v_add_f32_e32 v132, v132, v140
	v_add_f32_e32 v132, v132, v141
	v_mul_f32_e32 v140, v112, v192
	v_mul_f32_e32 v141, v113, v193
	v_add_f32_e32 v132, v132, v140
	v_add_f32_e32 v132, v132, v141
	v_mul_f32_e32 v140, v114, v194
	v_mul_f32_e32 v141, v115, v195
	v_add_f32_e32 v132, v132, v140
	v_add_f32_e32 v132, v132, v141
	s_mov_b32 s14, 0xbfb8aa3b
	v_min_f32_e32 v141, 0, v132
	v_mul_f32_e64 v140, |v132|, s14
	v_exp_f32_e32 v140, v140
	s_mov_b32 s14, 0x800000
	v_add_f32_e32 v140, 1.0, v140
	v_cmp_gt_f32_e32 vcc, s14, v140
	s_mov_b32 s14, 0x3f317217
	s_nop 0
	v_cndmask_b32_e64 v142, 0, 32, vcc
	v_ldexp_f32 v140, v140, v142
	v_log_f32_e32 v140, v140
	s_nop 0
	v_mul_f32_e32 v142, 0x3f317217, v140
	v_fma_f32 v142, v140, s14, -v142
	v_fmac_f32_e32 v142, 0x3377d1cf, v140
	s_mov_b32 s14, 0x7f800000
	v_fmac_f32_e32 v142, 0x3f317217, v140
	v_cmp_lt_f32_e64 s[18:19], |v140|, s14
	s_nop 1
	v_cndmask_b32_e64 v140, v140, v142, s[18:19]
	v_cndmask_b32_e32 v142, 0, v149, vcc
	v_sub_f32_e32 v140, v140, v142
	v_sub_f32_e32 v140, v141, v140
	v_mul_f32_e32 v142, 0x3d800000, v140
	v_mad_u32_u24 v144, v90, s15, v148
	ds_write_b32 v144, v142
	s_waitcnt lgkmcnt(1)
	v_lshl_add_u32 v143, v92, 2, s4
	ds_read2st64_b32 v[180:181], v143 offset1:1
	ds_read2st64_b32 v[182:183], v143 offset0:2 offset1:3
	ds_read2st64_b32 v[184:185], v143 offset0:4 offset1:5
	ds_read2st64_b32 v[186:187], v143 offset0:6 offset1:7
	ds_read2st64_b32 v[188:189], v143 offset0:8 offset1:9
	ds_read2st64_b32 v[190:191], v143 offset0:10 offset1:11
	ds_read2st64_b32 v[192:193], v143 offset0:12 offset1:13
	ds_read2st64_b32 v[194:195], v143 offset0:14 offset1:15
	v_fmac_f32_e32 v133, v100, v204
	v_fmac_f32_e32 v133, v101, v205
	v_fmac_f32_e32 v133, v102, v206
	v_fmac_f32_e32 v133, v103, v207
	v_fmac_f32_e32 v133, v104, v208
	v_fmac_f32_e32 v133, v105, v209
	v_mul_f32_e32 v140, v106, v210
	v_mul_f32_e32 v141, v107, v211
	v_add_f32_e32 v133, v133, v140
	v_add_f32_e32 v133, v133, v141
	v_mul_f32_e32 v140, v108, v212
	v_mul_f32_e32 v141, v109, v213
	v_add_f32_e32 v133, v133, v140
	v_add_f32_e32 v133, v133, v141
	v_mul_f32_e32 v140, v110, v214
	v_mul_f32_e32 v141, v111, v215
	v_add_f32_e32 v133, v133, v140
	v_add_f32_e32 v133, v133, v141
	v_mul_f32_e32 v140, v112, v216
	v_mul_f32_e32 v141, v113, v217
	v_add_f32_e32 v133, v133, v140
	v_add_f32_e32 v133, v133, v141
	v_mul_f32_e32 v140, v114, v218
	v_mul_f32_e32 v141, v115, v219
	v_add_f32_e32 v133, v133, v140
	v_add_f32_e32 v133, v133, v141
	s_mov_b32 s14, 0xbfb8aa3b
	v_min_f32_e32 v141, 0, v133
	v_mul_f32_e64 v140, |v133|, s14
	v_exp_f32_e32 v140, v140
	s_mov_b32 s14, 0x800000
	v_add_f32_e32 v140, 1.0, v140
	v_cmp_gt_f32_e32 vcc, s14, v140
	s_mov_b32 s14, 0x3f317217
	s_nop 0
	v_cndmask_b32_e64 v142, 0, 32, vcc
	v_ldexp_f32 v140, v140, v142
	v_log_f32_e32 v140, v140
	s_nop 0
	v_mul_f32_e32 v142, 0x3f317217, v140
	v_fma_f32 v142, v140, s14, -v142
	v_fmac_f32_e32 v142, 0x3377d1cf, v140
	s_mov_b32 s14, 0x7f800000
	v_fmac_f32_e32 v142, 0x3f317217, v140
	v_cmp_lt_f32_e64 s[18:19], |v140|, s14
	s_nop 1
	v_cndmask_b32_e64 v140, v140, v142, s[18:19]
	v_cndmask_b32_e32 v142, 0, v149, vcc
	v_sub_f32_e32 v140, v140, v142
	v_sub_f32_e32 v140, v141, v140
	v_mul_f32_e32 v142, 0x3d800000, v140
	v_mad_u32_u24 v144, v91, s15, v148
	ds_write_b32 v144, v142
	s_waitcnt lgkmcnt(1)
	v_lshl_add_u32 v143, v93, 2, s4
	ds_read2st64_b32 v[204:205], v143 offset1:1
	ds_read2st64_b32 v[206:207], v143 offset0:2 offset1:3
	ds_read2st64_b32 v[208:209], v143 offset0:4 offset1:5
	ds_read2st64_b32 v[210:211], v143 offset0:6 offset1:7
	ds_read2st64_b32 v[212:213], v143 offset0:8 offset1:9
	ds_read2st64_b32 v[214:215], v143 offset0:10 offset1:11
	ds_read2st64_b32 v[216:217], v143 offset0:12 offset1:13
	ds_read2st64_b32 v[218:219], v143 offset0:14 offset1:15
	v_fmac_f32_e32 v134, v100, v180
	v_fmac_f32_e32 v134, v101, v181
	v_fmac_f32_e32 v134, v102, v182
	v_fmac_f32_e32 v134, v103, v183
	v_fmac_f32_e32 v134, v104, v184
	v_fmac_f32_e32 v134, v105, v185
	v_mul_f32_e32 v140, v106, v186
	v_mul_f32_e32 v141, v107, v187
	v_add_f32_e32 v134, v134, v140
	v_add_f32_e32 v134, v134, v141
	v_mul_f32_e32 v140, v108, v188
	v_mul_f32_e32 v141, v109, v189
	v_add_f32_e32 v134, v134, v140
	v_add_f32_e32 v134, v134, v141
	v_mul_f32_e32 v140, v110, v190
	v_mul_f32_e32 v141, v111, v191
	v_add_f32_e32 v134, v134, v140
	v_add_f32_e32 v134, v134, v141
	v_mul_f32_e32 v140, v112, v192
	v_mul_f32_e32 v141, v113, v193
	v_add_f32_e32 v134, v134, v140
	v_add_f32_e32 v134, v134, v141
	v_mul_f32_e32 v140, v114, v194
	v_mul_f32_e32 v141, v115, v195
	v_add_f32_e32 v134, v134, v140
	v_add_f32_e32 v134, v134, v141
	s_mov_b32 s14, 0xbfb8aa3b
	v_min_f32_e32 v141, 0, v134
	v_mul_f32_e64 v140, |v134|, s14
	v_exp_f32_e32 v140, v140
	s_mov_b32 s14, 0x800000
	v_add_f32_e32 v140, 1.0, v140
	v_cmp_gt_f32_e32 vcc, s14, v140
	s_mov_b32 s14, 0x3f317217
	s_nop 0
	v_cndmask_b32_e64 v142, 0, 32, vcc
	v_ldexp_f32 v140, v140, v142
	v_log_f32_e32 v140, v140
	s_nop 0
	v_mul_f32_e32 v142, 0x3f317217, v140
	v_fma_f32 v142, v140, s14, -v142
	v_fmac_f32_e32 v142, 0x3377d1cf, v140
	s_mov_b32 s14, 0x7f800000
	v_fmac_f32_e32 v142, 0x3f317217, v140
	v_cmp_lt_f32_e64 s[18:19], |v140|, s14
	s_nop 1
	v_cndmask_b32_e64 v140, v140, v142, s[18:19]
	v_cndmask_b32_e32 v142, 0, v149, vcc
	v_sub_f32_e32 v140, v140, v142
	v_sub_f32_e32 v140, v141, v140
	v_mul_f32_e32 v142, 0x3d800000, v140
	v_mad_u32_u24 v144, v92, s15, v148
	ds_write_b32 v144, v142
	s_waitcnt lgkmcnt(1)
	v_lshl_add_u32 v143, v94, 2, s4
	ds_read2st64_b32 v[180:181], v143 offset1:1
	ds_read2st64_b32 v[182:183], v143 offset0:2 offset1:3
	ds_read2st64_b32 v[184:185], v143 offset0:4 offset1:5
	ds_read2st64_b32 v[186:187], v143 offset0:6 offset1:7
	ds_read2st64_b32 v[188:189], v143 offset0:8 offset1:9
	ds_read2st64_b32 v[190:191], v143 offset0:10 offset1:11
	ds_read2st64_b32 v[192:193], v143 offset0:12 offset1:13
	ds_read2st64_b32 v[194:195], v143 offset0:14 offset1:15
	v_fmac_f32_e32 v135, v100, v204
	v_fmac_f32_e32 v135, v101, v205
	v_fmac_f32_e32 v135, v102, v206
	v_fmac_f32_e32 v135, v103, v207
	v_fmac_f32_e32 v135, v104, v208
	v_fmac_f32_e32 v135, v105, v209
	v_mul_f32_e32 v140, v106, v210
	v_mul_f32_e32 v141, v107, v211
	v_add_f32_e32 v135, v135, v140
	v_add_f32_e32 v135, v135, v141
	v_mul_f32_e32 v140, v108, v212
	v_mul_f32_e32 v141, v109, v213
	v_add_f32_e32 v135, v135, v140
	v_add_f32_e32 v135, v135, v141
	v_mul_f32_e32 v140, v110, v214
	v_mul_f32_e32 v141, v111, v215
	v_add_f32_e32 v135, v135, v140
	v_add_f32_e32 v135, v135, v141
	v_mul_f32_e32 v140, v112, v216
	v_mul_f32_e32 v141, v113, v217
	v_add_f32_e32 v135, v135, v140
	v_add_f32_e32 v135, v135, v141
	v_mul_f32_e32 v140, v114, v218
	v_mul_f32_e32 v141, v115, v219
	v_add_f32_e32 v135, v135, v140
	v_add_f32_e32 v135, v135, v141
	s_mov_b32 s14, 0xbfb8aa3b
	v_min_f32_e32 v141, 0, v135
	v_mul_f32_e64 v140, |v135|, s14
	v_exp_f32_e32 v140, v140
	s_mov_b32 s14, 0x800000
	v_add_f32_e32 v140, 1.0, v140
	v_cmp_gt_f32_e32 vcc, s14, v140
	s_mov_b32 s14, 0x3f317217
	s_nop 0
	v_cndmask_b32_e64 v142, 0, 32, vcc
	v_ldexp_f32 v140, v140, v142
	v_log_f32_e32 v140, v140
	s_nop 0
	v_mul_f32_e32 v142, 0x3f317217, v140
	v_fma_f32 v142, v140, s14, -v142
	v_fmac_f32_e32 v142, 0x3377d1cf, v140
	s_mov_b32 s14, 0x7f800000
	v_fmac_f32_e32 v142, 0x3f317217, v140
	v_cmp_lt_f32_e64 s[18:19], |v140|, s14
	s_nop 1
	v_cndmask_b32_e64 v140, v140, v142, s[18:19]
	v_cndmask_b32_e32 v142, 0, v149, vcc
	v_sub_f32_e32 v140, v140, v142
	v_sub_f32_e32 v140, v141, v140
	v_mul_f32_e32 v142, 0x3d800000, v140
	v_mad_u32_u24 v144, v93, s15, v148
	ds_write_b32 v144, v142
	s_waitcnt lgkmcnt(1)
	v_lshl_add_u32 v143, v95, 2, s4
	ds_read2st64_b32 v[204:205], v143 offset1:1
	ds_read2st64_b32 v[206:207], v143 offset0:2 offset1:3
	ds_read2st64_b32 v[208:209], v143 offset0:4 offset1:5
	ds_read2st64_b32 v[210:211], v143 offset0:6 offset1:7
	ds_read2st64_b32 v[212:213], v143 offset0:8 offset1:9
	ds_read2st64_b32 v[214:215], v143 offset0:10 offset1:11
	ds_read2st64_b32 v[216:217], v143 offset0:12 offset1:13
	ds_read2st64_b32 v[218:219], v143 offset0:14 offset1:15
	v_fmac_f32_e32 v136, v100, v180
	v_fmac_f32_e32 v136, v101, v181
	v_fmac_f32_e32 v136, v102, v182
	v_fmac_f32_e32 v136, v103, v183
	v_fmac_f32_e32 v136, v104, v184
	v_fmac_f32_e32 v136, v105, v185
	v_mul_f32_e32 v140, v106, v186
	v_mul_f32_e32 v141, v107, v187
	v_add_f32_e32 v136, v136, v140
	v_add_f32_e32 v136, v136, v141
	v_mul_f32_e32 v140, v108, v188
	v_mul_f32_e32 v141, v109, v189
	v_add_f32_e32 v136, v136, v140
	v_add_f32_e32 v136, v136, v141
	v_mul_f32_e32 v140, v110, v190
	v_mul_f32_e32 v141, v111, v191
	v_add_f32_e32 v136, v136, v140
	v_add_f32_e32 v136, v136, v141
	v_mul_f32_e32 v140, v112, v192
	v_mul_f32_e32 v141, v113, v193
	v_add_f32_e32 v136, v136, v140
	v_add_f32_e32 v136, v136, v141
	v_mul_f32_e32 v140, v114, v194
	v_mul_f32_e32 v141, v115, v195
	v_add_f32_e32 v136, v136, v140
	v_add_f32_e32 v136, v136, v141
	s_mov_b32 s14, 0xbfb8aa3b
	v_min_f32_e32 v141, 0, v136
	v_mul_f32_e64 v140, |v136|, s14
	v_exp_f32_e32 v140, v140
	s_mov_b32 s14, 0x800000
	v_add_f32_e32 v140, 1.0, v140
	v_cmp_gt_f32_e32 vcc, s14, v140
	s_mov_b32 s14, 0x3f317217
	s_nop 0
	v_cndmask_b32_e64 v142, 0, 32, vcc
	v_ldexp_f32 v140, v140, v142
	v_log_f32_e32 v140, v140
	s_nop 0
	v_mul_f32_e32 v142, 0x3f317217, v140
	v_fma_f32 v142, v140, s14, -v142
	v_fmac_f32_e32 v142, 0x3377d1cf, v140
	s_mov_b32 s14, 0x7f800000
	v_fmac_f32_e32 v142, 0x3f317217, v140
	v_cmp_lt_f32_e64 s[18:19], |v140|, s14
	s_nop 1
	v_cndmask_b32_e64 v140, v140, v142, s[18:19]
	v_cndmask_b32_e32 v142, 0, v149, vcc
	v_sub_f32_e32 v140, v140, v142
	v_sub_f32_e32 v140, v141, v140
	v_mul_f32_e32 v142, 0x3d800000, v140
	v_mad_u32_u24 v144, v94, s15, v148
	ds_write_b32 v144, v142
	s_waitcnt lgkmcnt(1)
	v_lshl_add_u32 v143, v96, 2, s4
	ds_read2st64_b32 v[180:181], v143 offset1:1
	ds_read2st64_b32 v[182:183], v143 offset0:2 offset1:3
	ds_read2st64_b32 v[184:185], v143 offset0:4 offset1:5
	ds_read2st64_b32 v[186:187], v143 offset0:6 offset1:7
	ds_read2st64_b32 v[188:189], v143 offset0:8 offset1:9
	ds_read2st64_b32 v[190:191], v143 offset0:10 offset1:11
	ds_read2st64_b32 v[192:193], v143 offset0:12 offset1:13
	ds_read2st64_b32 v[194:195], v143 offset0:14 offset1:15
	v_fmac_f32_e32 v137, v100, v204
	v_fmac_f32_e32 v137, v101, v205
	v_fmac_f32_e32 v137, v102, v206
	v_fmac_f32_e32 v137, v103, v207
	v_fmac_f32_e32 v137, v104, v208
	v_fmac_f32_e32 v137, v105, v209
	v_mul_f32_e32 v140, v106, v210
	v_mul_f32_e32 v141, v107, v211
	v_add_f32_e32 v137, v137, v140
	v_add_f32_e32 v137, v137, v141
	v_mul_f32_e32 v140, v108, v212
	v_mul_f32_e32 v141, v109, v213
	v_add_f32_e32 v137, v137, v140
	v_add_f32_e32 v137, v137, v141
	v_mul_f32_e32 v140, v110, v214
	v_mul_f32_e32 v141, v111, v215
	v_add_f32_e32 v137, v137, v140
	v_add_f32_e32 v137, v137, v141
	v_mul_f32_e32 v140, v112, v216
	v_mul_f32_e32 v141, v113, v217
	v_add_f32_e32 v137, v137, v140
	v_add_f32_e32 v137, v137, v141
	v_mul_f32_e32 v140, v114, v218
	v_mul_f32_e32 v141, v115, v219
	v_add_f32_e32 v137, v137, v140
	v_add_f32_e32 v137, v137, v141
	s_mov_b32 s14, 0xbfb8aa3b
	v_min_f32_e32 v141, 0, v137
	v_mul_f32_e64 v140, |v137|, s14
	v_exp_f32_e32 v140, v140
	s_mov_b32 s14, 0x800000
	v_add_f32_e32 v140, 1.0, v140
	v_cmp_gt_f32_e32 vcc, s14, v140
	s_mov_b32 s14, 0x3f317217
	s_nop 0
	v_cndmask_b32_e64 v142, 0, 32, vcc
	v_ldexp_f32 v140, v140, v142
	v_log_f32_e32 v140, v140
	s_nop 0
	v_mul_f32_e32 v142, 0x3f317217, v140
	v_fma_f32 v142, v140, s14, -v142
	v_fmac_f32_e32 v142, 0x3377d1cf, v140
	s_mov_b32 s14, 0x7f800000
	v_fmac_f32_e32 v142, 0x3f317217, v140
	v_cmp_lt_f32_e64 s[18:19], |v140|, s14
	s_nop 1
	v_cndmask_b32_e64 v140, v140, v142, s[18:19]
	v_cndmask_b32_e32 v142, 0, v149, vcc
	v_sub_f32_e32 v140, v140, v142
	v_sub_f32_e32 v140, v141, v140
	v_mul_f32_e32 v142, 0x3d800000, v140
	v_mad_u32_u24 v144, v95, s15, v148
	ds_write_b32 v144, v142
	s_waitcnt lgkmcnt(1)
	v_lshl_add_u32 v143, v97, 2, s4
	ds_read2st64_b32 v[204:205], v143 offset1:1
	ds_read2st64_b32 v[206:207], v143 offset0:2 offset1:3
	ds_read2st64_b32 v[208:209], v143 offset0:4 offset1:5
	ds_read2st64_b32 v[210:211], v143 offset0:6 offset1:7
	ds_read2st64_b32 v[212:213], v143 offset0:8 offset1:9
	ds_read2st64_b32 v[214:215], v143 offset0:10 offset1:11
	ds_read2st64_b32 v[216:217], v143 offset0:12 offset1:13
	ds_read2st64_b32 v[218:219], v143 offset0:14 offset1:15
	v_fmac_f32_e32 v138, v100, v180
	v_fmac_f32_e32 v138, v101, v181
	v_fmac_f32_e32 v138, v102, v182
	v_fmac_f32_e32 v138, v103, v183
	v_fmac_f32_e32 v138, v104, v184
	v_fmac_f32_e32 v138, v105, v185
	v_mul_f32_e32 v140, v106, v186
	v_mul_f32_e32 v141, v107, v187
	v_add_f32_e32 v138, v138, v140
	v_add_f32_e32 v138, v138, v141
	v_mul_f32_e32 v140, v108, v188
	v_mul_f32_e32 v141, v109, v189
	v_add_f32_e32 v138, v138, v140
	v_add_f32_e32 v138, v138, v141
	v_mul_f32_e32 v140, v110, v190
	v_mul_f32_e32 v141, v111, v191
	v_add_f32_e32 v138, v138, v140
	v_add_f32_e32 v138, v138, v141
	v_mul_f32_e32 v140, v112, v192
	v_mul_f32_e32 v141, v113, v193
	v_add_f32_e32 v138, v138, v140
	v_add_f32_e32 v138, v138, v141
	v_mul_f32_e32 v140, v114, v194
	v_mul_f32_e32 v141, v115, v195
	v_add_f32_e32 v138, v138, v140
	v_add_f32_e32 v138, v138, v141
	s_mov_b32 s14, 0xbfb8aa3b
	v_min_f32_e32 v141, 0, v138
	v_mul_f32_e64 v140, |v138|, s14
	v_exp_f32_e32 v140, v140
	s_mov_b32 s14, 0x800000
	v_add_f32_e32 v140, 1.0, v140
	v_cmp_gt_f32_e32 vcc, s14, v140
	s_mov_b32 s14, 0x3f317217
	s_nop 0
	v_cndmask_b32_e64 v142, 0, 32, vcc
	v_ldexp_f32 v140, v140, v142
	v_log_f32_e32 v140, v140
	s_nop 0
	v_mul_f32_e32 v142, 0x3f317217, v140
	v_fma_f32 v142, v140, s14, -v142
	v_fmac_f32_e32 v142, 0x3377d1cf, v140
	s_mov_b32 s14, 0x7f800000
	v_fmac_f32_e32 v142, 0x3f317217, v140
	v_cmp_lt_f32_e64 s[18:19], |v140|, s14
	s_nop 1
	v_cndmask_b32_e64 v140, v140, v142, s[18:19]
	v_cndmask_b32_e32 v142, 0, v149, vcc
	v_sub_f32_e32 v140, v140, v142
	v_sub_f32_e32 v140, v141, v140
	v_mul_f32_e32 v142, 0x3d800000, v140
	v_mad_u32_u24 v144, v96, s15, v148
	ds_write_b32 v144, v142
	s_waitcnt lgkmcnt(1)
	v_fmac_f32_e32 v139, v100, v204
	v_fmac_f32_e32 v139, v101, v205
	v_fmac_f32_e32 v139, v102, v206
	v_fmac_f32_e32 v139, v103, v207
	v_fmac_f32_e32 v139, v104, v208
	v_fmac_f32_e32 v139, v105, v209
	v_mul_f32_e32 v140, v106, v210
	v_mul_f32_e32 v141, v107, v211
	v_add_f32_e32 v139, v139, v140
	v_add_f32_e32 v139, v139, v141
	v_mul_f32_e32 v140, v108, v212
	v_mul_f32_e32 v141, v109, v213
	v_add_f32_e32 v139, v139, v140
	v_add_f32_e32 v139, v139, v141
	v_mul_f32_e32 v140, v110, v214
	v_mul_f32_e32 v141, v111, v215
	v_add_f32_e32 v139, v139, v140
	v_add_f32_e32 v139, v139, v141
	v_mul_f32_e32 v140, v112, v216
	v_mul_f32_e32 v141, v113, v217
	v_add_f32_e32 v139, v139, v140
	v_add_f32_e32 v139, v139, v141
	v_mul_f32_e32 v140, v114, v218
	v_mul_f32_e32 v141, v115, v219
	v_add_f32_e32 v139, v139, v140
	v_add_f32_e32 v139, v139, v141
	s_mov_b32 s14, 0xbfb8aa3b
	v_min_f32_e32 v141, 0, v139
	v_mul_f32_e64 v140, |v139|, s14
	v_exp_f32_e32 v140, v140
	s_mov_b32 s14, 0x800000
	v_add_f32_e32 v140, 1.0, v140
	v_cmp_gt_f32_e32 vcc, s14, v140
	s_mov_b32 s14, 0x3f317217
	s_nop 0
	v_cndmask_b32_e64 v142, 0, 32, vcc
	v_ldexp_f32 v140, v140, v142
	v_log_f32_e32 v140, v140
	s_nop 0
	v_mul_f32_e32 v142, 0x3f317217, v140
	v_fma_f32 v142, v140, s14, -v142
	v_fmac_f32_e32 v142, 0x3377d1cf, v140
	s_mov_b32 s14, 0x7f800000
	v_fmac_f32_e32 v142, 0x3f317217, v140
	v_cmp_lt_f32_e64 s[18:19], |v140|, s14
	s_nop 1
	v_cndmask_b32_e64 v140, v140, v142, s[18:19]
	v_cndmask_b32_e32 v142, 0, v149, vcc
	v_sub_f32_e32 v140, v140, v142
	v_sub_f32_e32 v140, v141, v140
	v_mul_f32_e32 v142, 0x3d800000, v140
	v_mad_u32_u24 v144, v97, s15, v148
	ds_write_b32 v144, v142
	s_ashr_i32 s3, s2, 6
	s_mul_i32 s4, s3, 0x820
	s_add_i32 s4, s4, s96
	v_lshl_add_u32 v24, v26, 2, s4
	s_waitcnt lgkmcnt(0)
	s_barrier
	ds_read2_b32 v[22:23], v24 offset1:65
	v_and_b32_e32 v21, 64, v1
	v_add_u32_e32 v25, -1, v1
	v_cmp_lt_i32_e32 vcc, v25, v21
	v_subrev_u32_e32 v49, 32, v1
	v_cmp_lt_i32_e64 s[14:15], v49, v21
	v_cndmask_b32_e32 v25, v25, v1, vcc
	v_lshlrev_b32_e32 v25, 2, v25
	s_waitcnt lgkmcnt(0)
	ds_bpermute_b32 v43, v25, v22
	v_cmp_eq_u32_e32 vcc, 0, v26
	ds_bpermute_b32 v47, v25, v23
	s_movk_i32 s4, 0x104
	s_mov_b32 s17, 0
	s_waitcnt lgkmcnt(1)
	v_add_f32_e32 v43, v22, v43
	v_cndmask_b32_e32 v22, v43, v22, vcc
	v_add_u32_e32 v43, -2, v1
	v_cmp_lt_i32_e64 s[6:7], v43, v21
	s_waitcnt lgkmcnt(0)
	v_add_f32_e32 v47, v23, v47
	v_cndmask_b32_e32 v23, v47, v23, vcc
	v_cndmask_b32_e64 v43, v43, v1, s[6:7]
	v_lshlrev_b32_e32 v43, 2, v43
	ds_bpermute_b32 v44, v43, v22
	v_cmp_gt_u32_e64 s[6:7], 2, v26
	ds_bpermute_b32 v47, v43, v23
	s_and_b32 s3, s3, 3
	s_ashr_i32 s2, s2, 8
	s_waitcnt lgkmcnt(1)
	v_add_f32_e32 v44, v22, v44
	v_cndmask_b32_e64 v22, v44, v22, s[6:7]
	v_add_u32_e32 v44, -4, v1
	v_cmp_lt_i32_e64 s[8:9], v44, v21
	s_waitcnt lgkmcnt(0)
	v_add_f32_e32 v47, v23, v47
	v_cndmask_b32_e64 v23, v47, v23, s[6:7]
	v_cndmask_b32_e64 v44, v44, v1, s[8:9]
	v_lshlrev_b32_e32 v44, 2, v44
	ds_bpermute_b32 v45, v44, v22
	v_cmp_gt_u32_e64 s[8:9], 4, v26
	ds_bpermute_b32 v47, v44, v23
	s_waitcnt lgkmcnt(1)
	v_add_f32_e32 v45, v22, v45
	v_cndmask_b32_e64 v22, v45, v22, s[8:9]
	v_add_u32_e32 v45, -8, v1
	v_cmp_lt_i32_e64 s[10:11], v45, v21
	s_nop 1
	v_cndmask_b32_e64 v45, v45, v1, s[10:11]
	v_lshlrev_b32_e32 v45, 2, v45
	ds_bpermute_b32 v46, v45, v22
	v_cmp_gt_u32_e64 s[10:11], 8, v26
	s_waitcnt lgkmcnt(0)
	v_add_f32_e32 v46, v22, v46
	v_cndmask_b32_e64 v22, v46, v22, s[10:11]
	v_add_u32_e32 v46, -16, v1
	v_cmp_lt_i32_e64 s[12:13], v46, v21
	v_cndmask_b32_e64 v21, v49, v1, s[14:15]
	v_lshlrev_b32_e32 v21, 2, v21
	v_cndmask_b32_e64 v46, v46, v1, s[12:13]
	v_lshlrev_b32_e32 v46, 2, v46
	ds_bpermute_b32 v48, v46, v22
	v_cmp_gt_u32_e64 s[12:13], 16, v26
	v_cmp_gt_u32_e64 s[14:15], 32, v26
	s_waitcnt lgkmcnt(0)
	v_add_f32_e32 v48, v22, v48
	v_cndmask_b32_e64 v48, v48, v22, s[12:13]
	v_add_f32_e32 v22, v23, v47
	v_cndmask_b32_e64 v47, v22, v23, s[8:9]
	ds_read2_b32 v[22:23], v24 offset0:130 offset1:195
	ds_bpermute_b32 v50, v45, v47
	ds_bpermute_b32 v51, v21, v48
	s_waitcnt lgkmcnt(2)
	ds_bpermute_b32 v49, v25, v22
	s_waitcnt lgkmcnt(2)
	v_add_f32_e32 v50, v47, v50
	v_cndmask_b32_e64 v47, v50, v47, s[10:11]
	ds_bpermute_b32 v50, v46, v47
	s_waitcnt lgkmcnt(2)
	v_add_f32_e32 v51, v48, v51
	s_waitcnt lgkmcnt(1)
	v_add_f32_e32 v49, v22, v49
	v_cndmask_b32_e32 v22, v49, v22, vcc
	ds_bpermute_b32 v49, v43, v22
	s_waitcnt lgkmcnt(1)
	v_add_f32_e32 v50, v47, v50
	v_cndmask_b32_e64 v47, v50, v47, s[12:13]
	ds_bpermute_b32 v50, v21, v47
	v_cndmask_b32_e64 v48, v51, v48, s[14:15]
	s_waitcnt lgkmcnt(1)
	v_add_f32_e32 v49, v22, v49
	v_cndmask_b32_e64 v22, v49, v22, s[6:7]
	ds_bpermute_b32 v49, v44, v22
	ds_bpermute_b32 v51, v25, v23
	s_waitcnt lgkmcnt(2)
	v_add_f32_e32 v50, v47, v50
	v_cndmask_b32_e64 v47, v50, v47, s[14:15]
	ds_write2_b32 v24, v48, v47 offset1:65
	s_waitcnt lgkmcnt(2)
	v_add_f32_e32 v49, v22, v49
	v_cndmask_b32_e64 v22, v49, v22, s[8:9]
	s_waitcnt lgkmcnt(1)
	v_add_f32_e32 v50, v23, v51
	ds_bpermute_b32 v49, v45, v22
	v_cndmask_b32_e32 v23, v50, v23, vcc
	ds_bpermute_b32 v50, v43, v23
	s_waitcnt lgkmcnt(1)
	v_add_f32_e32 v47, v22, v49
	v_cndmask_b32_e64 v47, v47, v22, s[10:11]
	s_waitcnt lgkmcnt(0)
	v_add_f32_e32 v22, v23, v50
	v_cndmask_b32_e64 v49, v22, v23, s[6:7]
	v_add_u32_e32 v50, 0x400, v24
	ds_read2_b32 v[22:23], v50 offset0:4 offset1:69
	ds_bpermute_b32 v51, v44, v49
	ds_bpermute_b32 v48, v46, v47
	s_waitcnt lgkmcnt(2)
	ds_bpermute_b32 v52, v25, v22
	s_waitcnt lgkmcnt(2)
	v_add_f32_e32 v51, v49, v51
	v_cndmask_b32_e64 v49, v51, v49, s[8:9]
	ds_bpermute_b32 v51, v45, v49
	s_waitcnt lgkmcnt(2)
	v_add_f32_e32 v48, v47, v48
	v_cndmask_b32_e64 v47, v48, v47, s[12:13]
	s_waitcnt lgkmcnt(1)
	v_add_f32_e32 v52, v22, v52
	ds_bpermute_b32 v48, v21, v47
	v_cndmask_b32_e32 v22, v52, v22, vcc
	ds_bpermute_b32 v52, v43, v22
	s_waitcnt lgkmcnt(2)
	v_add_f32_e32 v51, v49, v51
	v_cndmask_b32_e64 v49, v51, v49, s[10:11]
	ds_bpermute_b32 v51, v46, v49
	s_waitcnt lgkmcnt(2)
	v_add_f32_e32 v48, v47, v48
	v_cndmask_b32_e64 v47, v48, v47, s[14:15]
	s_waitcnt lgkmcnt(1)
	v_add_f32_e32 v48, v22, v52
	v_cndmask_b32_e64 v22, v48, v22, s[6:7]
	ds_bpermute_b32 v48, v44, v22
	s_waitcnt lgkmcnt(1)
	v_add_f32_e32 v51, v49, v51
	v_cndmask_b32_e64 v49, v51, v49, s[12:13]
	ds_bpermute_b32 v51, v25, v23
	ds_bpermute_b32 v52, v21, v49
	s_waitcnt lgkmcnt(2)
	v_add_f32_e32 v48, v22, v48
	v_cndmask_b32_e64 v22, v48, v22, s[8:9]
	ds_bpermute_b32 v48, v45, v22
	s_waitcnt lgkmcnt(2)
	v_add_f32_e32 v51, v23, v51
	v_cndmask_b32_e32 v23, v51, v23, vcc
	ds_bpermute_b32 v51, v43, v23
	s_waitcnt lgkmcnt(2)
	v_add_f32_e32 v52, v49, v52
	s_waitcnt lgkmcnt(1)
	v_add_f32_e32 v48, v22, v48
	v_cndmask_b32_e64 v22, v48, v22, s[10:11]
	ds_bpermute_b32 v48, v46, v22
	s_waitcnt lgkmcnt(1)
	v_add_f32_e32 v51, v23, v51
	v_cndmask_b32_e64 v23, v51, v23, s[6:7]
	ds_bpermute_b32 v51, v44, v23
	v_cndmask_b32_e64 v49, v52, v49, s[14:15]
	s_waitcnt lgkmcnt(1)
	v_add_f32_e32 v48, v22, v48
	v_cndmask_b32_e64 v48, v48, v22, s[12:13]
	ds_write2_b32 v24, v47, v49 offset0:130 offset1:195
	s_waitcnt lgkmcnt(1)
	v_add_f32_e32 v22, v23, v51
	v_cndmask_b32_e64 v51, v22, v23, s[8:9]
	ds_read2_b32 v[22:23], v50 offset0:134 offset1:199
	ds_bpermute_b32 v52, v21, v48
	ds_bpermute_b32 v53, v45, v51
	s_waitcnt lgkmcnt(2)
	ds_bpermute_b32 v47, v25, v22
	ds_bpermute_b32 v25, v25, v23
	s_waitcnt lgkmcnt(3)
	v_add_f32_e32 v24, v48, v52
	v_cndmask_b32_e64 v24, v24, v48, s[14:15]
	s_waitcnt lgkmcnt(2)
	v_add_f32_e32 v48, v51, v53
	s_waitcnt lgkmcnt(1)
	v_add_f32_e32 v47, v22, v47
	s_waitcnt lgkmcnt(0)
	v_add_f32_e32 v25, v23, v25
	v_cndmask_b32_e32 v22, v47, v22, vcc
	v_cndmask_b32_e32 v23, v25, v23, vcc
	ds_bpermute_b32 v47, v43, v22
	ds_bpermute_b32 v25, v43, v23
	v_cndmask_b32_e64 v48, v48, v51, s[10:11]
	ds_bpermute_b32 v49, v46, v48
	s_waitcnt lgkmcnt(2)
	v_add_f32_e32 v47, v22, v47
	s_waitcnt lgkmcnt(1)
	v_add_f32_e32 v25, v23, v25
	v_cndmask_b32_e64 v22, v47, v22, s[6:7]
	v_cndmask_b32_e64 v23, v25, v23, s[6:7]
	ds_bpermute_b32 v47, v44, v22
	ds_bpermute_b32 v25, v44, v23
	s_waitcnt lgkmcnt(2)
	v_add_f32_e32 v43, v48, v49
	v_cndmask_b32_e64 v43, v43, v48, s[12:13]
	v_readlane_b32 s6, v228, 25
	s_waitcnt lgkmcnt(1)
	v_add_f32_e32 v44, v22, v47
	s_waitcnt lgkmcnt(0)
	v_add_f32_e32 v25, v23, v25
	v_cndmask_b32_e64 v22, v44, v22, s[8:9]
	v_cndmask_b32_e64 v23, v25, v23, s[8:9]
	ds_bpermute_b32 v44, v45, v22
	ds_bpermute_b32 v25, v45, v23
	ds_bpermute_b32 v45, v21, v43
	v_readlane_b32 s7, v228, 26
	s_waitcnt lgkmcnt(2)
	v_add_f32_e32 v44, v22, v44
	s_waitcnt lgkmcnt(1)
	v_add_f32_e32 v25, v23, v25
	v_cndmask_b32_e64 v22, v44, v22, s[10:11]
	v_cndmask_b32_e64 v23, v25, v23, s[10:11]
	ds_bpermute_b32 v44, v46, v22
	ds_bpermute_b32 v25, v46, v23
	s_waitcnt lgkmcnt(2)
	v_add_f32_e32 v45, v43, v45
	s_waitcnt lgkmcnt(1)
	v_add_f32_e32 v44, v22, v44
	s_waitcnt lgkmcnt(0)
	v_add_f32_e32 v25, v23, v25
	v_cndmask_b32_e64 v22, v44, v22, s[12:13]
	v_cndmask_b32_e64 v23, v25, v23, s[12:13]
	ds_bpermute_b32 v44, v21, v22
	ds_bpermute_b32 v21, v21, v23
	v_cndmask_b32_e64 v25, v45, v43, s[14:15]
	ds_write2_b32 v50, v24, v25 offset0:4 offset1:69
	s_waitcnt lgkmcnt(2)
	v_add_f32_e32 v24, v22, v44
	s_waitcnt lgkmcnt(1)
	v_add_f32_e32 v21, v23, v21
	v_cndmask_b32_e64 v22, v24, v22, s[14:15]
	v_cndmask_b32_e64 v21, v21, v23, s[14:15]
	ds_write2_b32 v50, v22, v21 offset0:134 offset1:199
	v_mov_b32_e32 v21, s96
	v_mad_u32_u24 v21, v26, s4, v21
	v_lshl_add_u32 v19, v19, 2, v21
	s_waitcnt lgkmcnt(0)
	s_barrier
	ds_read_b32 v24, v19
	ds_read_b32 v19, v21 offset:252
	s_lshl_b64 s[4:5], s[16:17], 14
	s_add_u32 s4, s6, s4
	s_addc_u32 s5, s7, s5
	v_lshl_add_u32 v28, v28, 2, v21
	s_waitcnt lgkmcnt(0)
	v_sub_f32_e32 v19, v19, v24
	v_mul_f32_e32 v19, 0x3fb8aa3b, v19
	v_exp_f32_e32 v19, v19
	s_lshl_b32 s3, s3, 7
	v_mul_f32_e32 v22, v42, v19
	v_ashrrev_i32_e32 v19, 31, v18
	v_lshl_add_u32 v42, v18, 2, s96
	ds_write_b32 v42, v22 offset:16640
	v_lshl_add_u64 v[22:23], v[18:19], 2, s[4:5]
	global_store_dword v[22:23], v24, off
	v_lshl_add_u32 v24, v29, 2, v21
	ds_read_b32 v24, v24
	ds_read_b32 v25, v21 offset:252
	s_movk_i32 s4, 0x1000
	s_waitcnt lgkmcnt(0)
	v_sub_f32_e32 v25, v25, v24
	v_mul_f32_e32 v25, 0x3fb8aa3b, v25
	v_exp_f32_e32 v25, v25
	s_nop 0
	v_mul_f32_e32 v25, v41, v25
	ds_write_b32 v42, v25 offset:18688
	global_store_dword v[22:23], v24, off offset:2048
	v_lshl_add_u32 v24, v33, 2, v21
	ds_read_b32 v29, v24
	ds_read_b32 v24, v21 offset:252
	s_waitcnt lgkmcnt(0)
	v_sub_f32_e32 v24, v24, v29
	v_mul_f32_e32 v24, 0x3fb8aa3b, v24
	v_exp_f32_e32 v24, v24
	s_nop 0
	v_mul_f32_e32 v24, v40, v24
	ds_write_b32 v42, v24 offset:20736
	v_add_co_u32_e32 v24, vcc, s4, v22
	s_movk_i32 s4, 0x2000
	s_nop 0
	v_addc_co_u32_e32 v25, vcc, 0, v23, vcc
	global_store_dword v[24:25], v29, off
	v_lshl_add_u32 v29, v30, 2, v21
	ds_read_b32 v29, v29
	ds_read_b32 v30, v21 offset:252
	s_waitcnt lgkmcnt(0)
	v_sub_f32_e32 v30, v30, v29
	v_mul_f32_e32 v30, 0x3fb8aa3b, v30
	v_exp_f32_e32 v30, v30
	s_nop 0
	v_mul_f32_e32 v30, v39, v30
	ds_write_b32 v42, v30 offset:22784
	global_store_dword v[24:25], v29, off offset:2048
	v_lshl_add_u32 v24, v32, 2, v21
	ds_read_b32 v29, v24
	ds_read_b32 v24, v21 offset:252
	s_waitcnt lgkmcnt(0)
	v_sub_f32_e32 v24, v24, v29
	v_mul_f32_e32 v24, 0x3fb8aa3b, v24
	v_exp_f32_e32 v24, v24
	s_nop 0
	v_mul_f32_e32 v24, v38, v24
	ds_write_b32 v42, v24 offset:24832
	v_add_co_u32_e32 v24, vcc, s4, v22
	s_movk_i32 s4, 0x3000
	s_nop 0
	v_addc_co_u32_e32 v25, vcc, 0, v23, vcc
	global_store_dword v[24:25], v29, off
	ds_read_b32 v28, v28
	ds_read_b32 v29, v21 offset:252
	s_waitcnt lgkmcnt(0)
	v_sub_f32_e32 v29, v29, v28
	v_mul_f32_e32 v29, 0x3fb8aa3b, v29
	v_exp_f32_e32 v29, v29
	s_nop 0
	v_mul_f32_e32 v29, v37, v29
	ds_write_b32 v42, v29 offset:26880
	global_store_dword v[24:25], v28, off offset:2048
	v_lshl_add_u32 v24, v31, 2, v21
	ds_read_b32 v28, v24
	ds_read_b32 v24, v21 offset:252
	s_waitcnt lgkmcnt(0)
	v_sub_f32_e32 v24, v24, v28
	v_mul_f32_e32 v24, 0x3fb8aa3b, v24
	v_exp_f32_e32 v24, v24
	s_nop 0
	v_mul_f32_e32 v24, v36, v24
	ds_write_b32 v42, v24 offset:28928
	v_add_co_u32_e32 v24, vcc, s4, v22
	v_lshl_add_u32 v22, v27, 2, v21
	s_nop 0
	v_addc_co_u32_e32 v25, vcc, 0, v23, vcc
	global_store_dword v[24:25], v28, off
	ds_read_b32 v23, v22
	ds_read_b32 v21, v21 offset:252
	v_lshrrev_b32_e32 v22, 5, v26
	v_and_b32_e32 v26, 31, v18
	s_lshl_b32 s4, s2, 7
	s_waitcnt lgkmcnt(0)
	v_sub_f32_e32 v21, v21, v23
	v_mul_f32_e32 v21, 0x3fb8aa3b, v21
	v_exp_f32_e32 v21, v21
	s_nop 0
	v_mul_f32_e32 v21, v34, v21
	ds_write_b32 v42, v21 offset:30976
	v_and_b32_e32 v21, 0x3fffff80, v35
	v_lshlrev_b32_e32 v21, 2, v21
	v_add3_u32 v20, s96, v21, v20
	global_store_dword v[24:25], v23, off offset:2048
	ds_write_b128 v20, v[2:5] offset:33024
	ds_write_b128 v20, v[6:9] offset:41216
	ds_write_b128 v20, v[10:13] offset:49408
	ds_write_b128 v20, v[14:17] offset:57600
	v_lshlrev_b32_e32 v2, 9, v22
	v_lshlrev_b32_e32 v20, 2, v26
	v_or3_b32 v2, v2, s3, v20
	v_add_u32_e32 v2, s96, v2
	v_add_u32_e32 v21, 0x8100, v2
	v_lshl_add_u32 v2, v22, 8, s4
	v_or_b32_e32 v2, v2, v20
	v_add_u32_e32 v2, s96, v2
	v_add_u32_e32 v23, 0x4100, v2
	v_mov_b32_e32 v2, 0
	s_mov_b32 s4, s17
	v_mov_b32_e32 v3, v2
	v_mov_b32_e32 v4, v2
	v_mov_b32_e32 v5, v2
	v_mov_b32_e32 v6, v2
	v_mov_b32_e32 v7, v2
	v_mov_b32_e32 v8, v2
	v_mov_b32_e32 v9, v2
	v_mov_b32_e32 v10, v2
	v_mov_b32_e32 v11, v2
	v_mov_b32_e32 v12, v2
	v_mov_b32_e32 v13, v2
	v_mov_b32_e32 v14, v2
	v_mov_b32_e32 v15, v2
	v_mov_b32_e32 v16, v2
	v_mov_b32_e32 v17, v2
	s_waitcnt lgkmcnt(0)
	s_barrier

.LBB0_4209:
	s_lshl_b32 s24, s86, 4
	s_lshl_b32 s25, s86, 6
	s_and_b32 s24, s24, 0xffffe000
	s_and_b32 s25, s25, 0x1fc0
	s_or_b32 s87, s24, s25
	s_bfe_u32 s88, s86, 0x20007
	s_nop 0
	s_load_dwordx2 s[98:99], s[0:1], 0x98
	s_load_dwordx2 s[100:101], s[0:1], 0xa0
	v_lshlrev_b32_e32 v178, 2, v182
	v_ashrrev_i32_e32 v150, 4, v180
	v_add_u32_e32 v152, s87, v150
	v_mad_i64_i32 v[152:153], vcc, v152, s62, v[22:23]
	global_load_dword v170, v[152:153], off
	v_add_u32_e32 v151, 0x200, v180
	v_ashrrev_i32_e32 v151, 4, v151
	v_add_u32_e32 v154, s87, v151
	v_mad_i64_i32 v[154:155], vcc, v154, s62, v[22:23]
	global_load_dword v171, v[154:155], off
	v_lshl_add_u32 v174, v150, 2, v59
	v_lshl_add_u32 v175, v151, 2, v59
	s_waitcnt lgkmcnt(0)
	s_lshl_b32 s56, s88, 8
	v_and_b32_e32 v156, 0xffffff00, v43
	v_ashrrev_i32_e32 v157, 31, v156
	v_lshl_add_u64 v[158:159], v[156:157], 2, s[98:99]
	v_lshl_add_u64 v[158:159], v[158:159], 0, s[56:57]
	v_lshl_add_u64 v[158:159], v[158:159], 0, v[178:179]
	s_mov_b32 s24, 0x4000
	s_mov_b32 s25, 0
	v_lshl_add_u64 v[158:159], v[158:159], 0, s[24:25]
	global_load_dword v172, v[158:159], off
	v_add_u32_e32 v176, s4, v43
	v_add_u32_e32 v160, 0x800, v43
	v_and_b32_e32 v156, 0xffffff00, v160
	v_ashrrev_i32_e32 v157, 31, v156
	v_lshl_add_u64 v[162:163], v[156:157], 2, s[98:99]
	v_lshl_add_u64 v[162:163], v[162:163], 0, s[56:57]
	v_lshl_add_u64 v[162:163], v[162:163], 0, v[178:179]
	v_lshl_add_u64 v[162:163], v[162:163], 0, s[24:25]
	global_load_dword v173, v[162:163], off
	v_add_u32_e32 v177, s4, v160
	v_ashrrev_i32_e32 v90, 6, v180
	v_lshl_add_u32 v164, s88, 6, v90
	v_ashrrev_i32_e32 v165, 31, v164
	v_lshl_add_u64 v[166:167], v[164:165], 2, s[100:101]
	global_load_dword v132, v[166:167], off offset:1024
	v_add_u32_e32 v164, 0x200, v180
	v_ashrrev_i32_e32 v91, 6, v164
	v_lshl_add_u32 v164, s88, 6, v91
	v_ashrrev_i32_e32 v165, 31, v164
	v_lshl_add_u64 v[166:167], v[164:165], 2, s[100:101]
	global_load_dword v133, v[166:167], off offset:1024
	v_add_u32_e32 v164, 0x400, v180
	v_ashrrev_i32_e32 v92, 6, v164
	v_lshl_add_u32 v164, s88, 6, v92
	v_ashrrev_i32_e32 v165, 31, v164
	v_lshl_add_u64 v[166:167], v[164:165], 2, s[100:101]
	global_load_dword v134, v[166:167], off offset:1024
	v_add_u32_e32 v164, 0x600, v180
	v_ashrrev_i32_e32 v93, 6, v164
	v_lshl_add_u32 v164, s88, 6, v93
	v_ashrrev_i32_e32 v165, 31, v164
	v_lshl_add_u64 v[166:167], v[164:165], 2, s[100:101]
	global_load_dword v135, v[166:167], off offset:1024
	v_add_u32_e32 v164, 0x800, v180
	v_ashrrev_i32_e32 v94, 6, v164
	v_lshl_add_u32 v164, s88, 6, v94
	v_ashrrev_i32_e32 v165, 31, v164
	v_lshl_add_u64 v[166:167], v[164:165], 2, s[100:101]
	global_load_dword v136, v[166:167], off offset:1024
	v_add_u32_e32 v164, 0xa00, v180
	v_ashrrev_i32_e32 v95, 6, v164
	v_lshl_add_u32 v164, s88, 6, v95
	v_ashrrev_i32_e32 v165, 31, v164
	v_lshl_add_u64 v[166:167], v[164:165], 2, s[100:101]
	global_load_dword v137, v[166:167], off offset:1024
	v_add_u32_e32 v164, 0xc00, v180
	v_ashrrev_i32_e32 v96, 6, v164
	v_lshl_add_u32 v164, s88, 6, v96
	v_ashrrev_i32_e32 v165, 31, v164
	v_lshl_add_u64 v[166:167], v[164:165], 2, s[100:101]
	global_load_dword v138, v[166:167], off offset:1024
	v_add_u32_e32 v164, 0xe00, v180
	v_ashrrev_i32_e32 v97, 6, v164
	v_lshl_add_u32 v164, s88, 6, v97
	v_ashrrev_i32_e32 v165, 31, v164
	v_lshl_add_u64 v[166:167], v[164:165], 2, s[100:101]
	global_load_dword v139, v[166:167], off offset:1024
	s_lshl_b32 s24, s86, 4
	s_lshl_b32 s25, s86, 6
	s_and_b32 s24, s24, 0xffffe000
	s_and_b32 s25, s25, 0x1fc0
	s_or_b32 s87, s24, s25
	s_bfe_u32 s88, s86, 0x20007
	v_add_u32_e32 v2, s87, v35
	v_mov_b64_e32 v[10:11], s[46:47]
	v_mad_i64_i32 v[2:3], s[24:25], v2, s62, v[10:11]
	s_lshl_b32 s56, s88, 8
	v_lshl_add_u64 v[2:3], v[2:3], 0, s[56:57]
	v_lshlrev_b32_e32 v178, 2, v182
	v_add_u32_e32 v4, s87, v36
	v_lshl_add_u64 v[2:3], v[2:3], 0, v[178:179]
	v_mad_i64_i32 v[4:5], s[24:25], v4, s62, v[10:11]
	v_add_co_u32_e32 v2, vcc, s30, v2
	v_lshl_add_u64 v[4:5], v[4:5], 0, s[56:57]
	v_add_u32_e32 v6, s87, v37
	v_addc_co_u32_e32 v3, vcc, 0, v3, vcc
	v_lshl_add_u64 v[4:5], v[4:5], 0, v[178:179]
	v_mad_i64_i32 v[6:7], s[24:25], v6, s62, v[10:11]
	v_add_co_u32_e32 v4, vcc, s30, v4
	v_lshl_add_u64 v[6:7], v[6:7], 0, s[56:57]
	v_add_u32_e32 v8, s87, v38
	v_addc_co_u32_e32 v5, vcc, 0, v5, vcc
	v_lshl_add_u64 v[6:7], v[6:7], 0, v[178:179]
	v_mad_i64_i32 v[8:9], s[24:25], v8, s62, v[10:11]
	v_add_co_u32_e32 v6, vcc, s30, v6
	v_lshl_add_u64 v[8:9], v[8:9], 0, s[56:57]
	v_add_u32_e32 v12, s87, v39
	v_addc_co_u32_e32 v7, vcc, 0, v7, vcc
	v_lshl_add_u64 v[8:9], v[8:9], 0, v[178:179]
	v_mad_i64_i32 v[12:13], s[24:25], v12, s62, v[10:11]
	v_add_co_u32_e32 v8, vcc, s30, v8
	v_lshl_add_u64 v[12:13], v[12:13], 0, s[56:57]
	v_add_u32_e32 v14, s87, v40
	v_addc_co_u32_e32 v9, vcc, 0, v9, vcc
	v_lshl_add_u64 v[12:13], v[12:13], 0, v[178:179]
	v_mad_i64_i32 v[14:15], s[24:25], v14, s62, v[10:11]
	v_add_co_u32_e32 v12, vcc, s30, v12
	v_lshl_add_u64 v[14:15], v[14:15], 0, s[56:57]
	v_add_u32_e32 v16, s87, v41
	v_addc_co_u32_e32 v13, vcc, 0, v13, vcc
	v_lshl_add_u64 v[14:15], v[14:15], 0, v[178:179]
	v_mad_i64_i32 v[16:17], s[24:25], v16, s62, v[10:11]
	v_add_co_u32_e32 v14, vcc, s30, v14
	v_lshl_add_u64 v[16:17], v[16:17], 0, s[56:57]
	v_add_u32_e32 v29, s87, v42
	v_addc_co_u32_e32 v15, vcc, 0, v15, vcc
	v_lshl_add_u64 v[16:17], v[16:17], 0, v[178:179]
	v_mad_i64_i32 v[66:67], s[24:25], v29, s62, v[10:11]
	v_add_co_u32_e32 v16, vcc, s30, v16
	v_lshl_add_u64 v[66:67], v[66:67], 0, s[56:57]
	s_nop 0
	v_addc_co_u32_e32 v17, vcc, 0, v17, vcc
	v_lshl_add_u64 v[66:67], v[66:67], 0, v[178:179]
	v_add_co_u32_e32 v74, vcc, s30, v66
	s_lshl_b32 s56, s88, 9
	s_nop 0
	v_addc_co_u32_e32 v75, vcc, 0, v67, vcc
	global_load_dword v72, v[2:3], off offset:2144
	global_load_dword v71, v[4:5], off offset:2144
	global_load_dword v70, v[6:7], off offset:2144
	global_load_dword v69, v[8:9], off offset:2144
	global_load_dword v68, v[12:13], off offset:2144
	global_load_dword v67, v[14:15], off offset:2144
	global_load_dword v66, v[16:17], off offset:2144
	global_load_dword v65, v[74:75], off offset:2144
	v_add_u32_e32 v2, s87, v44
	v_mad_i64_i32 v[2:3], s[24:25], v2, s62, v[10:11]
	v_lshl_add_u64 v[2:3], v[2:3], 0, s[56:57]
	v_mov_b32_e32 v29, v179
	v_add_u32_e32 v4, s87, v45
	v_lshl_add_u64 v[2:3], v[2:3], 0, v[28:29]
	v_mad_i64_i32 v[4:5], s[24:25], v4, s62, v[10:11]
	v_add_co_u32_e32 v2, vcc, s30, v2
	v_lshl_add_u64 v[4:5], v[4:5], 0, s[56:57]
	v_add_u32_e32 v12, s87, v46
	v_addc_co_u32_e32 v3, vcc, 0, v3, vcc
	v_lshl_add_u64 v[4:5], v[4:5], 0, v[28:29]
	v_mad_i64_i32 v[12:13], s[24:25], v12, s62, v[10:11]
	v_add_co_u32_e32 v6, vcc, s30, v4
	v_lshl_add_u64 v[12:13], v[12:13], 0, s[56:57]
	v_add_u32_e32 v14, s87, v47
	v_addc_co_u32_e32 v7, vcc, 0, v5, vcc
	v_lshl_add_u64 v[12:13], v[12:13], 0, v[28:29]
	v_mad_i64_i32 v[10:11], s[24:25], v14, s62, v[10:11]
	v_add_co_u32_e32 v12, vcc, s30, v12
	v_lshl_add_u64 v[10:11], v[10:11], 0, s[56:57]
	s_nop 0
	v_addc_co_u32_e32 v13, vcc, 0, v13, vcc
	v_lshl_add_u64 v[10:11], v[10:11], 0, v[28:29]
	v_add_co_u32_e32 v14, vcc, 0x1000, v10
	global_load_dwordx4 v[2:5], v[2:3], off offset:3168
	s_nop 0
	global_load_dwordx4 v[6:9], v[6:7], off offset:3168
	v_addc_co_u32_e32 v15, vcc, 0, v11, vcc
	global_load_dwordx4 v[10:13], v[12:13], off offset:3168
	s_nop 0
	global_load_dwordx4 v[14:17], v[14:15], off offset:3168
	s_lshl_b32 s88, s88, 6
	s_mov_b32 s89, s57
	s_waitcnt lgkmcnt(0)
	s_barrier
	s_waitcnt vmcnt(20)
	ds_write_b32 v174, v170
	ds_write_b32 v175, v171
	ds_write_b32 v176, v172
	ds_write_b32 v177, v173
	s_waitcnt lgkmcnt(0)
	s_barrier
	ds_read2st64_b32 v[100:101], v60 offset1:1
	ds_read2st64_b32 v[102:103], v60 offset0:2 offset1:3
	ds_read2st64_b32 v[104:105], v60 offset0:4 offset1:5
	ds_read2st64_b32 v[106:107], v60 offset0:6 offset1:7
	ds_read2st64_b32 v[108:109], v60 offset0:8 offset1:9
	ds_read2st64_b32 v[110:111], v60 offset0:10 offset1:11
	ds_read2st64_b32 v[112:113], v60 offset0:12 offset1:13
	ds_read2st64_b32 v[114:115], v60 offset0:14 offset1:15
	v_lshl_add_u32 v143, v90, 2, s4
	ds_read2st64_b32 v[116:117], v143 offset1:1
	ds_read2st64_b32 v[118:119], v143 offset0:2 offset1:3
	ds_read2st64_b32 v[120:121], v143 offset0:4 offset1:5
	ds_read2st64_b32 v[122:123], v143 offset0:6 offset1:7
	ds_read2st64_b32 v[124:125], v143 offset0:8 offset1:9
	ds_read2st64_b32 v[126:127], v143 offset0:10 offset1:11
	ds_read2st64_b32 v[128:129], v143 offset0:12 offset1:13
	ds_read2st64_b32 v[130:131], v143 offset0:14 offset1:15
	s_waitcnt vmcnt(12)
	s_waitcnt lgkmcnt(0)
	v_lshl_add_u32 v143, v91, 2, s4
	ds_read2st64_b32 v[204:205], v143 offset1:1
	ds_read2st64_b32 v[206:207], v143 offset0:2 offset1:3
	ds_read2st64_b32 v[208:209], v143 offset0:4 offset1:5
	ds_read2st64_b32 v[210:211], v143 offset0:6 offset1:7
	ds_read2st64_b32 v[212:213], v143 offset0:8 offset1:9
	ds_read2st64_b32 v[214:215], v143 offset0:10 offset1:11
	ds_read2st64_b32 v[216:217], v143 offset0:12 offset1:13
	ds_read2st64_b32 v[218:219], v143 offset0:14 offset1:15
	v_fmac_f32_e32 v132, v100, v116
	v_fmac_f32_e32 v132, v101, v117
	v_fmac_f32_e32 v132, v102, v118
	v_fmac_f32_e32 v132, v103, v119
	v_fmac_f32_e32 v132, v104, v120
	v_fmac_f32_e32 v132, v105, v121
	v_mul_f32_e32 v140, v106, v122
	v_mul_f32_e32 v141, v107, v123
	v_add_f32_e32 v132, v132, v140
	v_add_f32_e32 v132, v132, v141
	v_mul_f32_e32 v140, v108, v124
	v_mul_f32_e32 v141, v109, v125
	v_add_f32_e32 v132, v132, v140
	v_add_f32_e32 v132, v132, v141
	v_mul_f32_e32 v140, v110, v126
	v_mul_f32_e32 v141, v111, v127
	v_add_f32_e32 v132, v132, v140
	v_add_f32_e32 v132, v132, v141
	v_mul_f32_e32 v140, v112, v128
	v_mul_f32_e32 v141, v113, v129
	v_add_f32_e32 v132, v132, v140
	v_add_f32_e32 v132, v132, v141
	v_mul_f32_e32 v140, v114, v130
	v_mul_f32_e32 v141, v115, v131
	v_add_f32_e32 v132, v132, v140
	v_add_f32_e32 v132, v132, v141
	s_mov_b32 s24, 0xbfb8aa3b
	v_min_f32_e32 v141, 0, v132
	v_mul_f32_e64 v140, |v132|, s24
	v_exp_f32_e32 v140, v140
	s_mov_b32 s24, 0x800000
	v_add_f32_e32 v140, 1.0, v140
	v_cmp_gt_f32_e32 vcc, s24, v140
	s_mov_b32 s24, 0x3f317217
	s_nop 0
	v_cndmask_b32_e64 v142, 0, 32, vcc
	v_ldexp_f32 v140, v140, v142
	v_log_f32_e32 v140, v140
	s_nop 0
	v_mul_f32_e32 v142, 0x3f317217, v140
	v_fma_f32 v142, v140, s24, -v142
	v_fmac_f32_e32 v142, 0x3377d1cf, v140
	s_mov_b32 s24, 0x7f800000
	v_fmac_f32_e32 v142, 0x3f317217, v140
	v_cmp_lt_f32_e64 s[24:25], |v140|, s24
	s_nop 1
	v_cndmask_b32_e64 v140, v140, v142, s[24:25]
	v_cndmask_b32_e32 v142, 0, v183, vcc
	v_sub_f32_e32 v140, v140, v142
	v_sub_f32_e32 v140, v141, v140
	v_mul_f32_e32 v142, 0x3d800000, v140
	v_mad_u64_u32 v[144:145], s[24:25], v90, s31, v[18:19]
	ds_write_b32 v144, v142
	s_waitcnt lgkmcnt(1)
	v_lshl_add_u32 v143, v92, 2, s4
	ds_read2st64_b32 v[116:117], v143 offset1:1
	ds_read2st64_b32 v[118:119], v143 offset0:2 offset1:3
	ds_read2st64_b32 v[120:121], v143 offset0:4 offset1:5
	ds_read2st64_b32 v[122:123], v143 offset0:6 offset1:7
	ds_read2st64_b32 v[124:125], v143 offset0:8 offset1:9
	ds_read2st64_b32 v[126:127], v143 offset0:10 offset1:11
	ds_read2st64_b32 v[128:129], v143 offset0:12 offset1:13
	ds_read2st64_b32 v[130:131], v143 offset0:14 offset1:15
	v_fmac_f32_e32 v133, v100, v204
	v_fmac_f32_e32 v133, v101, v205
	v_fmac_f32_e32 v133, v102, v206
	v_fmac_f32_e32 v133, v103, v207
	v_fmac_f32_e32 v133, v104, v208
	v_fmac_f32_e32 v133, v105, v209
	v_mul_f32_e32 v140, v106, v210
	v_mul_f32_e32 v141, v107, v211
	v_add_f32_e32 v133, v133, v140
	v_add_f32_e32 v133, v133, v141
	v_mul_f32_e32 v140, v108, v212
	v_mul_f32_e32 v141, v109, v213
	v_add_f32_e32 v133, v133, v140
	v_add_f32_e32 v133, v133, v141
	v_mul_f32_e32 v140, v110, v214
	v_mul_f32_e32 v141, v111, v215
	v_add_f32_e32 v133, v133, v140
	v_add_f32_e32 v133, v133, v141
	v_mul_f32_e32 v140, v112, v216
	v_mul_f32_e32 v141, v113, v217
	v_add_f32_e32 v133, v133, v140
	v_add_f32_e32 v133, v133, v141
	v_mul_f32_e32 v140, v114, v218
	v_mul_f32_e32 v141, v115, v219
	v_add_f32_e32 v133, v133, v140
	v_add_f32_e32 v133, v133, v141
	s_mov_b32 s24, 0xbfb8aa3b
	v_min_f32_e32 v141, 0, v133
	v_mul_f32_e64 v140, |v133|, s24
	v_exp_f32_e32 v140, v140
	s_mov_b32 s24, 0x800000
	v_add_f32_e32 v140, 1.0, v140
	v_cmp_gt_f32_e32 vcc, s24, v140
	s_mov_b32 s24, 0x3f317217
	s_nop 0
	v_cndmask_b32_e64 v142, 0, 32, vcc
	v_ldexp_f32 v140, v140, v142
	v_log_f32_e32 v140, v140
	s_nop 0
	v_mul_f32_e32 v142, 0x3f317217, v140
	v_fma_f32 v142, v140, s24, -v142
	v_fmac_f32_e32 v142, 0x3377d1cf, v140
	s_mov_b32 s24, 0x7f800000
	v_fmac_f32_e32 v142, 0x3f317217, v140
	v_cmp_lt_f32_e64 s[24:25], |v140|, s24
	s_nop 1
	v_cndmask_b32_e64 v140, v140, v142, s[24:25]
	v_cndmask_b32_e32 v142, 0, v183, vcc
	v_sub_f32_e32 v140, v140, v142
	v_sub_f32_e32 v140, v141, v140
	v_mul_f32_e32 v142, 0x3d800000, v140
	v_mad_u64_u32 v[144:145], s[24:25], v91, s31, v[18:19]
	ds_write_b32 v144, v142
	s_waitcnt lgkmcnt(1)
	v_lshl_add_u32 v143, v93, 2, s4
	ds_read2st64_b32 v[204:205], v143 offset1:1
	ds_read2st64_b32 v[206:207], v143 offset0:2 offset1:3
	ds_read2st64_b32 v[208:209], v143 offset0:4 offset1:5
	ds_read2st64_b32 v[210:211], v143 offset0:6 offset1:7
	ds_read2st64_b32 v[212:213], v143 offset0:8 offset1:9
	ds_read2st64_b32 v[214:215], v143 offset0:10 offset1:11
	ds_read2st64_b32 v[216:217], v143 offset0:12 offset1:13
	ds_read2st64_b32 v[218:219], v143 offset0:14 offset1:15
	v_fmac_f32_e32 v134, v100, v116
	v_fmac_f32_e32 v134, v101, v117
	v_fmac_f32_e32 v134, v102, v118
	v_fmac_f32_e32 v134, v103, v119
	v_fmac_f32_e32 v134, v104, v120
	v_fmac_f32_e32 v134, v105, v121
	v_mul_f32_e32 v140, v106, v122
	v_mul_f32_e32 v141, v107, v123
	v_add_f32_e32 v134, v134, v140
	v_add_f32_e32 v134, v134, v141
	v_mul_f32_e32 v140, v108, v124
	v_mul_f32_e32 v141, v109, v125
	v_add_f32_e32 v134, v134, v140
	v_add_f32_e32 v134, v134, v141
	v_mul_f32_e32 v140, v110, v126
	v_mul_f32_e32 v141, v111, v127
	v_add_f32_e32 v134, v134, v140
	v_add_f32_e32 v134, v134, v141
	v_mul_f32_e32 v140, v112, v128
	v_mul_f32_e32 v141, v113, v129
	v_add_f32_e32 v134, v134, v140
	v_add_f32_e32 v134, v134, v141
	v_mul_f32_e32 v140, v114, v130
	v_mul_f32_e32 v141, v115, v131
	v_add_f32_e32 v134, v134, v140
	v_add_f32_e32 v134, v134, v141
	s_mov_b32 s24, 0xbfb8aa3b
	v_min_f32_e32 v141, 0, v134
	v_mul_f32_e64 v140, |v134|, s24
	v_exp_f32_e32 v140, v140
	s_mov_b32 s24, 0x800000
	v_add_f32_e32 v140, 1.0, v140
	v_cmp_gt_f32_e32 vcc, s24, v140
	s_mov_b32 s24, 0x3f317217
	s_nop 0
	v_cndmask_b32_e64 v142, 0, 32, vcc
	v_ldexp_f32 v140, v140, v142
	v_log_f32_e32 v140, v140
	s_nop 0
	v_mul_f32_e32 v142, 0x3f317217, v140
	v_fma_f32 v142, v140, s24, -v142
	v_fmac_f32_e32 v142, 0x3377d1cf, v140
	s_mov_b32 s24, 0x7f800000
	v_fmac_f32_e32 v142, 0x3f317217, v140
	v_cmp_lt_f32_e64 s[24:25], |v140|, s24
	s_nop 1
	v_cndmask_b32_e64 v140, v140, v142, s[24:25]
	v_cndmask_b32_e32 v142, 0, v183, vcc
	v_sub_f32_e32 v140, v140, v142
	v_sub_f32_e32 v140, v141, v140
	v_mul_f32_e32 v142, 0x3d800000, v140
	v_mad_u64_u32 v[144:145], s[24:25], v92, s31, v[18:19]
	ds_write_b32 v144, v142
	s_waitcnt lgkmcnt(1)
	v_lshl_add_u32 v143, v94, 2, s4
	ds_read2st64_b32 v[116:117], v143 offset1:1
	ds_read2st64_b32 v[118:119], v143 offset0:2 offset1:3
	ds_read2st64_b32 v[120:121], v143 offset0:4 offset1:5
	ds_read2st64_b32 v[122:123], v143 offset0:6 offset1:7
	ds_read2st64_b32 v[124:125], v143 offset0:8 offset1:9
	ds_read2st64_b32 v[126:127], v143 offset0:10 offset1:11
	ds_read2st64_b32 v[128:129], v143 offset0:12 offset1:13
	ds_read2st64_b32 v[130:131], v143 offset0:14 offset1:15
	v_fmac_f32_e32 v135, v100, v204
	v_fmac_f32_e32 v135, v101, v205
	v_fmac_f32_e32 v135, v102, v206
	v_fmac_f32_e32 v135, v103, v207
	v_fmac_f32_e32 v135, v104, v208
	v_fmac_f32_e32 v135, v105, v209
	v_mul_f32_e32 v140, v106, v210
	v_mul_f32_e32 v141, v107, v211
	v_add_f32_e32 v135, v135, v140
	v_add_f32_e32 v135, v135, v141
	v_mul_f32_e32 v140, v108, v212
	v_mul_f32_e32 v141, v109, v213
	v_add_f32_e32 v135, v135, v140
	v_add_f32_e32 v135, v135, v141
	v_mul_f32_e32 v140, v110, v214
	v_mul_f32_e32 v141, v111, v215
	v_add_f32_e32 v135, v135, v140
	v_add_f32_e32 v135, v135, v141
	v_mul_f32_e32 v140, v112, v216
	v_mul_f32_e32 v141, v113, v217
	v_add_f32_e32 v135, v135, v140
	v_add_f32_e32 v135, v135, v141
	v_mul_f32_e32 v140, v114, v218
	v_mul_f32_e32 v141, v115, v219
	v_add_f32_e32 v135, v135, v140
	v_add_f32_e32 v135, v135, v141
	s_mov_b32 s24, 0xbfb8aa3b
	v_min_f32_e32 v141, 0, v135
	v_mul_f32_e64 v140, |v135|, s24
	v_exp_f32_e32 v140, v140
	s_mov_b32 s24, 0x800000
	v_add_f32_e32 v140, 1.0, v140
	v_cmp_gt_f32_e32 vcc, s24, v140
	s_mov_b32 s24, 0x3f317217
	s_nop 0
	v_cndmask_b32_e64 v142, 0, 32, vcc
	v_ldexp_f32 v140, v140, v142
	v_log_f32_e32 v140, v140
	s_nop 0
	v_mul_f32_e32 v142, 0x3f317217, v140
	v_fma_f32 v142, v140, s24, -v142
	v_fmac_f32_e32 v142, 0x3377d1cf, v140
	s_mov_b32 s24, 0x7f800000
	v_fmac_f32_e32 v142, 0x3f317217, v140
	v_cmp_lt_f32_e64 s[24:25], |v140|, s24
	s_nop 1
	v_cndmask_b32_e64 v140, v140, v142, s[24:25]
	v_cndmask_b32_e32 v142, 0, v183, vcc
	v_sub_f32_e32 v140, v140, v142
	v_sub_f32_e32 v140, v141, v140
	v_mul_f32_e32 v142, 0x3d800000, v140
	v_mad_u64_u32 v[144:145], s[24:25], v93, s31, v[18:19]
	ds_write_b32 v144, v142
	s_waitcnt lgkmcnt(1)
	v_lshl_add_u32 v143, v95, 2, s4
	ds_read2st64_b32 v[204:205], v143 offset1:1
	ds_read2st64_b32 v[206:207], v143 offset0:2 offset1:3
	ds_read2st64_b32 v[208:209], v143 offset0:4 offset1:5
	ds_read2st64_b32 v[210:211], v143 offset0:6 offset1:7
	ds_read2st64_b32 v[212:213], v143 offset0:8 offset1:9
	ds_read2st64_b32 v[214:215], v143 offset0:10 offset1:11
	ds_read2st64_b32 v[216:217], v143 offset0:12 offset1:13
	ds_read2st64_b32 v[218:219], v143 offset0:14 offset1:15
	v_fmac_f32_e32 v136, v100, v116
	v_fmac_f32_e32 v136, v101, v117
	v_fmac_f32_e32 v136, v102, v118
	v_fmac_f32_e32 v136, v103, v119
	v_fmac_f32_e32 v136, v104, v120
	v_fmac_f32_e32 v136, v105, v121
	v_mul_f32_e32 v140, v106, v122
	v_mul_f32_e32 v141, v107, v123
	v_add_f32_e32 v136, v136, v140
	v_add_f32_e32 v136, v136, v141
	v_mul_f32_e32 v140, v108, v124
	v_mul_f32_e32 v141, v109, v125
	v_add_f32_e32 v136, v136, v140
	v_add_f32_e32 v136, v136, v141
	v_mul_f32_e32 v140, v110, v126
	v_mul_f32_e32 v141, v111, v127
	v_add_f32_e32 v136, v136, v140
	v_add_f32_e32 v136, v136, v141
	v_mul_f32_e32 v140, v112, v128
	v_mul_f32_e32 v141, v113, v129
	v_add_f32_e32 v136, v136, v140
	v_add_f32_e32 v136, v136, v141
	v_mul_f32_e32 v140, v114, v130
	v_mul_f32_e32 v141, v115, v131
	v_add_f32_e32 v136, v136, v140
	v_add_f32_e32 v136, v136, v141
	s_mov_b32 s24, 0xbfb8aa3b
	v_min_f32_e32 v141, 0, v136
	v_mul_f32_e64 v140, |v136|, s24
	v_exp_f32_e32 v140, v140
	s_mov_b32 s24, 0x800000
	v_add_f32_e32 v140, 1.0, v140
	v_cmp_gt_f32_e32 vcc, s24, v140
	s_mov_b32 s24, 0x3f317217
	s_nop 0
	v_cndmask_b32_e64 v142, 0, 32, vcc
	v_ldexp_f32 v140, v140, v142
	v_log_f32_e32 v140, v140
	s_nop 0
	v_mul_f32_e32 v142, 0x3f317217, v140
	v_fma_f32 v142, v140, s24, -v142
	v_fmac_f32_e32 v142, 0x3377d1cf, v140
	s_mov_b32 s24, 0x7f800000
	v_fmac_f32_e32 v142, 0x3f317217, v140
	v_cmp_lt_f32_e64 s[24:25], |v140|, s24
	s_nop 1
	v_cndmask_b32_e64 v140, v140, v142, s[24:25]
	v_cndmask_b32_e32 v142, 0, v183, vcc
	v_sub_f32_e32 v140, v140, v142
	v_sub_f32_e32 v140, v141, v140
	v_mul_f32_e32 v142, 0x3d800000, v140
	v_mad_u64_u32 v[144:145], s[24:25], v94, s31, v[18:19]
	ds_write_b32 v144, v142
	s_waitcnt lgkmcnt(1)
	v_lshl_add_u32 v143, v96, 2, s4
	ds_read2st64_b32 v[116:117], v143 offset1:1
	ds_read2st64_b32 v[118:119], v143 offset0:2 offset1:3
	ds_read2st64_b32 v[120:121], v143 offset0:4 offset1:5
	ds_read2st64_b32 v[122:123], v143 offset0:6 offset1:7
	ds_read2st64_b32 v[124:125], v143 offset0:8 offset1:9
	ds_read2st64_b32 v[126:127], v143 offset0:10 offset1:11
	ds_read2st64_b32 v[128:129], v143 offset0:12 offset1:13
	ds_read2st64_b32 v[130:131], v143 offset0:14 offset1:15
	v_fmac_f32_e32 v137, v100, v204
	v_fmac_f32_e32 v137, v101, v205
	v_fmac_f32_e32 v137, v102, v206
	v_fmac_f32_e32 v137, v103, v207
	v_fmac_f32_e32 v137, v104, v208
	v_fmac_f32_e32 v137, v105, v209
	v_mul_f32_e32 v140, v106, v210
	v_mul_f32_e32 v141, v107, v211
	v_add_f32_e32 v137, v137, v140
	v_add_f32_e32 v137, v137, v141
	v_mul_f32_e32 v140, v108, v212
	v_mul_f32_e32 v141, v109, v213
	v_add_f32_e32 v137, v137, v140
	v_add_f32_e32 v137, v137, v141
	v_mul_f32_e32 v140, v110, v214
	v_mul_f32_e32 v141, v111, v215
	v_add_f32_e32 v137, v137, v140
	v_add_f32_e32 v137, v137, v141
	v_mul_f32_e32 v140, v112, v216
	v_mul_f32_e32 v141, v113, v217
	v_add_f32_e32 v137, v137, v140
	v_add_f32_e32 v137, v137, v141
	v_mul_f32_e32 v140, v114, v218
	v_mul_f32_e32 v141, v115, v219
	v_add_f32_e32 v137, v137, v140
	v_add_f32_e32 v137, v137, v141
	s_mov_b32 s24, 0xbfb8aa3b
	v_min_f32_e32 v141, 0, v137
	v_mul_f32_e64 v140, |v137|, s24
	v_exp_f32_e32 v140, v140
	s_mov_b32 s24, 0x800000
	v_add_f32_e32 v140, 1.0, v140
	v_cmp_gt_f32_e32 vcc, s24, v140
	s_mov_b32 s24, 0x3f317217
	s_nop 0
	v_cndmask_b32_e64 v142, 0, 32, vcc
	v_ldexp_f32 v140, v140, v142
	v_log_f32_e32 v140, v140
	s_nop 0
	v_mul_f32_e32 v142, 0x3f317217, v140
	v_fma_f32 v142, v140, s24, -v142
	v_fmac_f32_e32 v142, 0x3377d1cf, v140
	s_mov_b32 s24, 0x7f800000
	v_fmac_f32_e32 v142, 0x3f317217, v140
	v_cmp_lt_f32_e64 s[24:25], |v140|, s24
	s_nop 1
	v_cndmask_b32_e64 v140, v140, v142, s[24:25]
	v_cndmask_b32_e32 v142, 0, v183, vcc
	v_sub_f32_e32 v140, v140, v142
	v_sub_f32_e32 v140, v141, v140
	v_mul_f32_e32 v142, 0x3d800000, v140
	v_mad_u64_u32 v[144:145], s[24:25], v95, s31, v[18:19]
	ds_write_b32 v144, v142
	s_waitcnt lgkmcnt(1)
	v_lshl_add_u32 v143, v97, 2, s4
	ds_read2st64_b32 v[204:205], v143 offset1:1
	ds_read2st64_b32 v[206:207], v143 offset0:2 offset1:3
	ds_read2st64_b32 v[208:209], v143 offset0:4 offset1:5
	ds_read2st64_b32 v[210:211], v143 offset0:6 offset1:7
	ds_read2st64_b32 v[212:213], v143 offset0:8 offset1:9
	ds_read2st64_b32 v[214:215], v143 offset0:10 offset1:11
	ds_read2st64_b32 v[216:217], v143 offset0:12 offset1:13
	ds_read2st64_b32 v[218:219], v143 offset0:14 offset1:15
	v_fmac_f32_e32 v138, v100, v116
	v_fmac_f32_e32 v138, v101, v117
	v_fmac_f32_e32 v138, v102, v118
	v_fmac_f32_e32 v138, v103, v119
	v_fmac_f32_e32 v138, v104, v120
	v_fmac_f32_e32 v138, v105, v121
	v_mul_f32_e32 v140, v106, v122
	v_mul_f32_e32 v141, v107, v123
	v_add_f32_e32 v138, v138, v140
	v_add_f32_e32 v138, v138, v141
	v_mul_f32_e32 v140, v108, v124
	v_mul_f32_e32 v141, v109, v125
	v_add_f32_e32 v138, v138, v140
	v_add_f32_e32 v138, v138, v141
	v_mul_f32_e32 v140, v110, v126
	v_mul_f32_e32 v141, v111, v127
	v_add_f32_e32 v138, v138, v140
	v_add_f32_e32 v138, v138, v141
	v_mul_f32_e32 v140, v112, v128
	v_mul_f32_e32 v141, v113, v129
	v_add_f32_e32 v138, v138, v140
	v_add_f32_e32 v138, v138, v141
	v_mul_f32_e32 v140, v114, v130
	v_mul_f32_e32 v141, v115, v131
	v_add_f32_e32 v138, v138, v140
	v_add_f32_e32 v138, v138, v141
	s_mov_b32 s24, 0xbfb8aa3b
	v_min_f32_e32 v141, 0, v138
	v_mul_f32_e64 v140, |v138|, s24
	v_exp_f32_e32 v140, v140
	s_mov_b32 s24, 0x800000
	v_add_f32_e32 v140, 1.0, v140
	v_cmp_gt_f32_e32 vcc, s24, v140
	s_mov_b32 s24, 0x3f317217
	s_nop 0
	v_cndmask_b32_e64 v142, 0, 32, vcc
	v_ldexp_f32 v140, v140, v142
	v_log_f32_e32 v140, v140
	s_nop 0
	v_mul_f32_e32 v142, 0x3f317217, v140
	v_fma_f32 v142, v140, s24, -v142
	v_fmac_f32_e32 v142, 0x3377d1cf, v140
	s_mov_b32 s24, 0x7f800000
	v_fmac_f32_e32 v142, 0x3f317217, v140
	v_cmp_lt_f32_e64 s[24:25], |v140|, s24
	s_nop 1
	v_cndmask_b32_e64 v140, v140, v142, s[24:25]
	v_cndmask_b32_e32 v142, 0, v183, vcc
	v_sub_f32_e32 v140, v140, v142
	v_sub_f32_e32 v140, v141, v140
	v_mul_f32_e32 v142, 0x3d800000, v140
	v_mad_u64_u32 v[144:145], s[24:25], v96, s31, v[18:19]
	ds_write_b32 v144, v142
	s_waitcnt lgkmcnt(1)
	v_fmac_f32_e32 v139, v100, v204
	v_fmac_f32_e32 v139, v101, v205
	v_fmac_f32_e32 v139, v102, v206
	v_fmac_f32_e32 v139, v103, v207
	v_fmac_f32_e32 v139, v104, v208
	v_fmac_f32_e32 v139, v105, v209
	v_mul_f32_e32 v140, v106, v210
	v_mul_f32_e32 v141, v107, v211
	v_add_f32_e32 v139, v139, v140
	v_add_f32_e32 v139, v139, v141
	v_mul_f32_e32 v140, v108, v212
	v_mul_f32_e32 v141, v109, v213
	v_add_f32_e32 v139, v139, v140
	v_add_f32_e32 v139, v139, v141
	v_mul_f32_e32 v140, v110, v214
	v_mul_f32_e32 v141, v111, v215
	v_add_f32_e32 v139, v139, v140
	v_add_f32_e32 v139, v139, v141
	v_mul_f32_e32 v140, v112, v216
	v_mul_f32_e32 v141, v113, v217
	v_add_f32_e32 v139, v139, v140
	v_add_f32_e32 v139, v139, v141
	v_mul_f32_e32 v140, v114, v218
	v_mul_f32_e32 v141, v115, v219
	v_add_f32_e32 v139, v139, v140
	v_add_f32_e32 v139, v139, v141
	s_mov_b32 s24, 0xbfb8aa3b
	v_min_f32_e32 v141, 0, v139
	v_mul_f32_e64 v140, |v139|, s24
	v_exp_f32_e32 v140, v140
	s_mov_b32 s24, 0x800000
	v_add_f32_e32 v140, 1.0, v140
	v_cmp_gt_f32_e32 vcc, s24, v140
	s_mov_b32 s24, 0x3f317217
	s_nop 0
	v_cndmask_b32_e64 v142, 0, 32, vcc
	v_ldexp_f32 v140, v140, v142
	v_log_f32_e32 v140, v140
	s_nop 0
	v_mul_f32_e32 v142, 0x3f317217, v140
	v_fma_f32 v142, v140, s24, -v142
	v_fmac_f32_e32 v142, 0x3377d1cf, v140
	s_mov_b32 s24, 0x7f800000
	v_fmac_f32_e32 v142, 0x3f317217, v140
	v_cmp_lt_f32_e64 s[24:25], |v140|, s24
	s_nop 1
	v_cndmask_b32_e64 v140, v140, v142, s[24:25]
	v_cndmask_b32_e32 v142, 0, v183, vcc
	v_sub_f32_e32 v140, v140, v142
	v_sub_f32_e32 v140, v141, v140
	v_mul_f32_e32 v142, 0x3d800000, v140
	v_mad_u64_u32 v[144:145], s[24:25], v97, s31, v[18:19]
	ds_write_b32 v144, v142
	s_waitcnt vmcnt(0)

.LBB0_4229:
	v_mov_b32_e32 v18, v0
	s_add_i32 s2, s40, 0xffffff70
	v_readlane_b32 s48, v228, 34
	s_cmp_gt_u32 s2, 63
	v_readfirstlane_b32 s2, v18
	v_readlane_b32 s97, v228, 14
	v_readlane_b32 s49, v228, 35
	s_cbranch_scc1 .LBB0_4243
	s_lshl_b32 s5, s40, 4
	s_and_b32 s5, s5, 0xf00
	s_and_b32 s3, s40, 15
	s_addk_i32 s5, 0xf700
	s_lshl_b32 s7, s5, 4
	s_lshl_b32 s8, s3, 6
	s_or_b32 s7, s8, s7
	s_and_b32 s12, s7, 0x7fffe3c0
	v_ashrrev_i32_e32 v19, 6, v18
	s_lshr_b32 s6, s5, 7
	s_waitcnt lgkmcnt(0)
	v_add_u32_e32 v2, s12, v19
	s_movk_i32 s13, 0x3000
	v_mov_b64_e32 v[10:11], s[46:47]
	s_and_b32 s6, s6, 2
	s_mov_b32 s7, 0
	v_mad_i64_i32 v[2:3], s[8:9], v2, s13, v[10:11]
	v_add_u32_e32 v24, 0x200, v18
	v_and_b32_e32 v26, 63, v18
	s_lshl_b32 s8, s6, 8
	s_mov_b32 s9, s7
	v_ashrrev_i32_e32 v29, 6, v24
	v_mov_b32_e32 v23, 0
	v_lshl_add_u64 v[2:3], v[2:3], 0, s[8:9]
	v_lshlrev_b32_e32 v22, 2, v26
	v_add_u32_e32 v4, s12, v29
	v_add_u32_e32 v25, 0x400, v18
	v_lshl_add_u64 v[2:3], v[2:3], 0, v[22:23]
	s_movk_i32 s14, 0x1000
	v_mad_i64_i32 v[4:5], s[10:11], v4, s13, v[10:11]
	v_ashrrev_i32_e32 v33, 6, v25
	v_add_co_u32_e32 v2, vcc, s14, v2
	v_lshl_add_u64 v[4:5], v[4:5], 0, s[8:9]
	v_add_u32_e32 v6, s12, v33
	v_add_u32_e32 v43, 0x600, v18
	v_addc_co_u32_e32 v3, vcc, 0, v3, vcc
	v_lshl_add_u64 v[4:5], v[4:5], 0, v[22:23]
	v_mad_i64_i32 v[6:7], s[10:11], v6, s13, v[10:11]
	v_ashrrev_i32_e32 v30, 6, v43
	v_add_co_u32_e32 v4, vcc, s14, v4
	v_lshl_add_u64 v[6:7], v[6:7], 0, s[8:9]
	v_add_u32_e32 v8, s12, v30
	v_add_u32_e32 v12, 0x800, v18
	v_addc_co_u32_e32 v5, vcc, 0, v5, vcc
	v_lshl_add_u64 v[6:7], v[6:7], 0, v[22:23]
	v_mad_i64_i32 v[8:9], s[10:11], v8, s13, v[10:11]
	v_ashrrev_i32_e32 v32, 6, v12
	v_add_co_u32_e32 v6, vcc, s14, v6
	v_lshl_add_u64 v[8:9], v[8:9], 0, s[8:9]
	v_add_u32_e32 v12, s12, v32
	v_add_u32_e32 v14, 0xa00, v18
	v_addc_co_u32_e32 v7, vcc, 0, v7, vcc
	v_lshl_add_u64 v[8:9], v[8:9], 0, v[22:23]
	v_mad_i64_i32 v[12:13], s[10:11], v12, s13, v[10:11]
	v_ashrrev_i32_e32 v28, 6, v14
	v_add_co_u32_e32 v8, vcc, s14, v8
	v_lshl_add_u64 v[12:13], v[12:13], 0, s[8:9]
	v_add_u32_e32 v14, s12, v28
	v_add_u32_e32 v16, 0xc00, v18
	v_addc_co_u32_e32 v9, vcc, 0, v9, vcc
	v_lshl_add_u64 v[12:13], v[12:13], 0, v[22:23]
	v_mad_i64_i32 v[14:15], s[10:11], v14, s13, v[10:11]
	v_ashrrev_i32_e32 v31, 6, v16
	v_add_co_u32_e32 v12, vcc, s14, v12
	v_lshl_add_u64 v[14:15], v[14:15], 0, s[8:9]
	v_add_u32_e32 v16, s12, v31
	v_add_u32_e32 v20, 0xe00, v18
	v_addc_co_u32_e32 v13, vcc, 0, v13, vcc
	v_lshl_add_u64 v[14:15], v[14:15], 0, v[22:23]
	v_mad_i64_i32 v[16:17], s[10:11], v16, s13, v[10:11]
	v_ashrrev_i32_e32 v27, 6, v20
	v_add_co_u32_e32 v14, vcc, s14, v14
	v_lshl_add_u64 v[16:17], v[16:17], 0, s[8:9]
	v_add_u32_e32 v20, s12, v27
	v_addc_co_u32_e32 v15, vcc, 0, v15, vcc
	v_lshl_add_u64 v[16:17], v[16:17], 0, v[22:23]
	v_mad_i64_i32 v[20:21], s[10:11], v20, s13, v[10:11]
	v_add_co_u32_e32 v16, vcc, s14, v16
	v_lshl_add_u64 v[20:21], v[20:21], 0, s[8:9]
	s_nop 0
	v_addc_co_u32_e32 v17, vcc, 0, v17, vcc
	v_lshl_add_u64 v[20:21], v[20:21], 0, v[22:23]
	v_add_co_u32_e32 v20, vcc, s14, v20
	v_lshlrev_b32_e32 v35, 2, v18
	s_nop 0
	v_addc_co_u32_e32 v21, vcc, 0, v21, vcc
	global_load_dword v42, v[2:3], off offset:2144
	global_load_dword v41, v[4:5], off offset:2144
	global_load_dword v40, v[6:7], off offset:2144
	global_load_dword v39, v[8:9], off offset:2144
	global_load_dword v38, v[12:13], off offset:2144
	global_load_dword v37, v[14:15], off offset:2144
	global_load_dword v36, v[16:17], off offset:2144
	global_load_dword v34, v[20:21], off offset:2144
	v_ashrrev_i32_e32 v2, 5, v18
	v_add_u32_e32 v2, s12, v2
	v_and_b32_e32 v4, 0x7c, v35
	v_mad_i64_i32 v[2:3], s[8:9], v2, s13, v[10:11]
	s_lshl_b32 s8, s6, 9
	s_mov_b32 s9, s7
	v_lshlrev_b32_e32 v20, 2, v4
	v_ashrrev_i32_e32 v4, 5, v24
	v_lshl_add_u64 v[2:3], v[2:3], 0, s[8:9]
	v_mov_b32_e32 v21, v23
	v_add_u32_e32 v4, s12, v4
	v_lshl_add_u64 v[2:3], v[2:3], 0, v[20:21]
	v_mad_i64_i32 v[4:5], s[10:11], v4, s13, v[10:11]
	v_ashrrev_i32_e32 v12, 5, v25
	v_add_co_u32_e32 v2, vcc, s14, v2
	v_lshl_add_u64 v[4:5], v[4:5], 0, s[8:9]
	v_add_u32_e32 v12, s12, v12
	v_addc_co_u32_e32 v3, vcc, 0, v3, vcc
	v_lshl_add_u64 v[4:5], v[4:5], 0, v[20:21]
	v_mad_i64_i32 v[12:13], s[10:11], v12, s13, v[10:11]
	v_ashrrev_i32_e32 v14, 5, v43
	v_add_co_u32_e32 v6, vcc, s14, v4
	v_lshl_add_u64 v[12:13], v[12:13], 0, s[8:9]
	v_add_u32_e32 v14, s12, v14
	v_addc_co_u32_e32 v7, vcc, 0, v5, vcc
	v_lshl_add_u64 v[12:13], v[12:13], 0, v[20:21]
	v_mad_i64_i32 v[10:11], s[10:11], v14, s13, v[10:11]
	v_add_co_u32_e32 v12, vcc, s14, v12
	v_lshl_add_u64 v[10:11], v[10:11], 0, s[8:9]
	s_nop 0
	v_addc_co_u32_e32 v13, vcc, 0, v13, vcc
	v_lshl_add_u64 v[10:11], v[10:11], 0, v[20:21]
	v_add_co_u32_e32 v14, vcc, 0x1000, v10
	global_load_dwordx4 v[2:5], v[2:3], off offset:3168
	s_nop 0
	global_load_dwordx4 v[6:9], v[6:7], off offset:3168
	v_addc_co_u32_e32 v15, vcc, 0, v11, vcc
	global_load_dwordx4 v[10:13], v[12:13], off offset:3168
	s_nop 0
	global_load_dwordx4 v[14:17], v[14:15], off offset:3168
	s_movk_i32 s8, 0x400
	s_lshl_b32 s6, s6, 6
	v_cmp_gt_i32_e32 vcc, s8, v18
	s_load_dwordx2 s[98:99], s[0:1], 0x98
	s_load_dwordx2 s[100:101], s[0:1], 0xa0
	v_and_b32_e32 v150, 15, v18
	v_readlane_b32 s8, v228, 31
	v_lshlrev_b32_e32 v152, 2, v150
	v_mov_b32_e32 v153, 0
	v_readlane_b32 s9, v228, 32
	s_nop 1
	v_lshl_add_u64 v[178:179], s[8:9], 0, v[152:153]
	v_readlane_b32 s8, v228, 10
	s_nop 1
	v_lshl_add_u32 v146, v150, 8, s8
	v_add_u32_e32 v147, s8, v22
	v_add_u32_e32 v148, s94, v22
	v_mov_b32_e32 v149, 0x41b17218
	v_ashrrev_i32_e32 v150, 4, v18
	v_add_u32_e32 v152, s12, v150
	v_mad_i64_i32 v[152:153], vcc, v152, s13, v[178:179]
	global_load_dword v170, v[152:153], off
	v_add_u32_e32 v151, 0x200, v18
	v_ashrrev_i32_e32 v151, 4, v151
	v_add_u32_e32 v154, s12, v151
	v_mad_i64_i32 v[154:155], vcc, v154, s13, v[178:179]
	global_load_dword v171, v[154:155], off
	v_lshl_add_u32 v174, v150, 2, v146
	v_lshl_add_u32 v175, v151, 2, v146
	s_waitcnt lgkmcnt(0)
	s_lshl_b32 s8, s6, 2
	s_mov_b32 s9, 0
	s_mov_b32 s10, 0x4000
	s_mov_b32 s11, 0
	v_and_b32_e32 v156, 0xffffff00, v35
	v_ashrrev_i32_e32 v157, 31, v156
	v_lshl_add_u64 v[158:159], v[156:157], 2, s[98:99]
	v_lshl_add_u64 v[158:159], v[158:159], 0, s[8:9]
	v_lshl_add_u64 v[158:159], v[158:159], 0, v[22:23]
	v_lshl_add_u64 v[158:159], v[158:159], 0, s[10:11]
	global_load_dword v172, v[158:159], off
	v_add_u32_e32 v176, s4, v35
	v_add_u32_e32 v160, 0x800, v35
	v_and_b32_e32 v156, 0xffffff00, v160
	v_ashrrev_i32_e32 v157, 31, v156
	v_lshl_add_u64 v[162:163], v[156:157], 2, s[98:99]
	v_lshl_add_u64 v[162:163], v[162:163], 0, s[8:9]
	v_lshl_add_u64 v[162:163], v[162:163], 0, v[22:23]
	v_lshl_add_u64 v[162:163], v[162:163], 0, s[10:11]
	global_load_dword v173, v[162:163], off
	v_add_u32_e32 v177, s4, v160
	v_ashrrev_i32_e32 v90, 6, v18
	v_add_u32_e32 v164, s6, v90
	v_ashrrev_i32_e32 v165, 31, v164
	v_lshl_add_u64 v[166:167], v[164:165], 2, s[100:101]
	global_load_dword v132, v[166:167], off offset:1024
	v_add_u32_e32 v164, 0x200, v18
	v_ashrrev_i32_e32 v91, 6, v164
	v_add_u32_e32 v164, s6, v91
	v_ashrrev_i32_e32 v165, 31, v164
	v_lshl_add_u64 v[166:167], v[164:165], 2, s[100:101]
	global_load_dword v133, v[166:167], off offset:1024
	v_add_u32_e32 v164, 0x400, v18
	v_ashrrev_i32_e32 v92, 6, v164
	v_add_u32_e32 v164, s6, v92
	v_ashrrev_i32_e32 v165, 31, v164
	v_lshl_add_u64 v[166:167], v[164:165], 2, s[100:101]
	global_load_dword v134, v[166:167], off offset:1024
	v_add_u32_e32 v164, 0x600, v18
	v_ashrrev_i32_e32 v93, 6, v164
	v_add_u32_e32 v164, s6, v93
	v_ashrrev_i32_e32 v165, 31, v164
	v_lshl_add_u64 v[166:167], v[164:165], 2, s[100:101]
	global_load_dword v135, v[166:167], off offset:1024
	v_add_u32_e32 v164, 0x800, v18
	v_ashrrev_i32_e32 v94, 6, v164
	v_add_u32_e32 v164, s6, v94
	v_ashrrev_i32_e32 v165, 31, v164
	v_lshl_add_u64 v[166:167], v[164:165], 2, s[100:101]
	global_load_dword v136, v[166:167], off offset:1024
	v_add_u32_e32 v164, 0xa00, v18
	v_ashrrev_i32_e32 v95, 6, v164
	v_add_u32_e32 v164, s6, v95
	v_ashrrev_i32_e32 v165, 31, v164
	v_lshl_add_u64 v[166:167], v[164:165], 2, s[100:101]
	global_load_dword v137, v[166:167], off offset:1024
	v_add_u32_e32 v164, 0xc00, v18
	v_ashrrev_i32_e32 v96, 6, v164
	v_add_u32_e32 v164, s6, v96
	v_ashrrev_i32_e32 v165, 31, v164
	v_lshl_add_u64 v[166:167], v[164:165], 2, s[100:101]
	global_load_dword v138, v[166:167], off offset:1024
	v_add_u32_e32 v164, 0xe00, v18
	v_ashrrev_i32_e32 v97, 6, v164
	v_add_u32_e32 v164, s6, v97
	v_ashrrev_i32_e32 v165, 31, v164
	v_lshl_add_u64 v[166:167], v[164:165], 2, s[100:101]
	global_load_dword v139, v[166:167], off offset:1024
	s_waitcnt vmcnt(0) lgkmcnt(0)
	s_barrier
	s_or_b32 s16, s5, s3
	ds_write_b32 v174, v170
	ds_write_b32 v175, v171
	ds_write_b32 v176, v172
	ds_write_b32 v177, v173
	s_movk_i32 s15, 0x104
	s_waitcnt lgkmcnt(0)
	s_barrier
	ds_read2st64_b32 v[100:101], v147 offset1:1
	ds_read2st64_b32 v[102:103], v147 offset0:2 offset1:3
	ds_read2st64_b32 v[104:105], v147 offset0:4 offset1:5
	ds_read2st64_b32 v[106:107], v147 offset0:6 offset1:7
	ds_read2st64_b32 v[108:109], v147 offset0:8 offset1:9
	ds_read2st64_b32 v[110:111], v147 offset0:10 offset1:11
	ds_read2st64_b32 v[112:113], v147 offset0:12 offset1:13
	ds_read2st64_b32 v[114:115], v147 offset0:14 offset1:15
	v_lshl_add_u32 v143, v90, 2, s4
	ds_read2st64_b32 v[180:181], v143 offset1:1
	ds_read2st64_b32 v[182:183], v143 offset0:2 offset1:3
	ds_read2st64_b32 v[184:185], v143 offset0:4 offset1:5
	ds_read2st64_b32 v[186:187], v143 offset0:6 offset1:7
	ds_read2st64_b32 v[188:189], v143 offset0:8 offset1:9
	ds_read2st64_b32 v[190:191], v143 offset0:10 offset1:11
	ds_read2st64_b32 v[192:193], v143 offset0:12 offset1:13
	ds_read2st64_b32 v[194:195], v143 offset0:14 offset1:15
	s_waitcnt lgkmcnt(0)
	v_lshl_add_u32 v143, v91, 2, s4
	ds_read2st64_b32 v[204:205], v143 offset1:1
	ds_read2st64_b32 v[206:207], v143 offset0:2 offset1:3
	ds_read2st64_b32 v[208:209], v143 offset0:4 offset1:5
	ds_read2st64_b32 v[210:211], v143 offset0:6 offset1:7
	ds_read2st64_b32 v[212:213], v143 offset0:8 offset1:9
	ds_read2st64_b32 v[214:215], v143 offset0:10 offset1:11
	ds_read2st64_b32 v[216:217], v143 offset0:12 offset1:13
	ds_read2st64_b32 v[218:219], v143 offset0:14 offset1:15
	v_fmac_f32_e32 v132, v100, v180
	v_fmac_f32_e32 v132, v101, v181
	v_fmac_f32_e32 v132, v102, v182
	v_fmac_f32_e32 v132, v103, v183
	v_fmac_f32_e32 v132, v104, v184
	v_fmac_f32_e32 v132, v105, v185
	v_mul_f32_e32 v140, v106, v186
	v_mul_f32_e32 v141, v107, v187
	v_add_f32_e32 v132, v132, v140
	v_add_f32_e32 v132, v132, v141
	v_mul_f32_e32 v140, v108, v188
	v_mul_f32_e32 v141, v109, v189
	v_add_f32_e32 v132, v132, v140
	v_add_f32_e32 v132, v132, v141
	v_mul_f32_e32 v140, v110, v190
	v_mul_f32_e32 v141, v111, v191
	v_add_f32_e32 v132, v132, v140
	v_add_f32_e32 v132, v132, v141
	v_mul_f32_e32 v140, v112, v192
	v_mul_f32_e32 v141, v113, v193
	v_add_f32_e32 v132, v132, v140
	v_add_f32_e32 v132, v132, v141
	v_mul_f32_e32 v140, v114, v194
	v_mul_f32_e32 v141, v115, v195
	v_add_f32_e32 v132, v132, v140
	v_add_f32_e32 v132, v132, v141
	s_mov_b32 s14, 0xbfb8aa3b
	v_min_f32_e32 v141, 0, v132
	v_mul_f32_e64 v140, |v132|, s14
	v_exp_f32_e32 v140, v140
	s_mov_b32 s14, 0x800000
	v_add_f32_e32 v140, 1.0, v140
	v_cmp_gt_f32_e32 vcc, s14, v140
	s_mov_b32 s14, 0x3f317217
	s_nop 0
	v_cndmask_b32_e64 v142, 0, 32, vcc
	v_ldexp_f32 v140, v140, v142
	v_log_f32_e32 v140, v140
	s_nop 0
	v_mul_f32_e32 v142, 0x3f317217, v140
	v_fma_f32 v142, v140, s14, -v142
	v_fmac_f32_e32 v142, 0x3377d1cf, v140
	s_mov_b32 s14, 0x7f800000
	v_fmac_f32_e32 v142, 0x3f317217, v140
	v_cmp_lt_f32_e64 s[18:19], |v140|, s14
	s_nop 1
	v_cndmask_b32_e64 v140, v140, v142, s[18:19]
	v_cndmask_b32_e32 v142, 0, v149, vcc
	v_sub_f32_e32 v140, v140, v142
	v_sub_f32_e32 v140, v141, v140
	v_mul_f32_e32 v142, 0x3d800000, v140
	v_mad_u32_u24 v144, v90, s15, v148
	ds_write_b32 v144, v142
	s_waitcnt lgkmcnt(1)
	v_lshl_add_u32 v143, v92, 2, s4
	ds_read2st64_b32 v[180:181], v143 offset1:1
	ds_read2st64_b32 v[182:183], v143 offset0:2 offset1:3
	ds_read2st64_b32 v[184:185], v143 offset0:4 offset1:5
	ds_read2st64_b32 v[186:187], v143 offset0:6 offset1:7
	ds_read2st64_b32 v[188:189], v143 offset0:8 offset1:9
	ds_read2st64_b32 v[190:191], v143 offset0:10 offset1:11
	ds_read2st64_b32 v[192:193], v143 offset0:12 offset1:13
	ds_read2st64_b32 v[194:195], v143 offset0:14 offset1:15
	v_fmac_f32_e32 v133, v100, v204
	v_fmac_f32_e32 v133, v101, v205
	v_fmac_f32_e32 v133, v102, v206
	v_fmac_f32_e32 v133, v103, v207
	v_fmac_f32_e32 v133, v104, v208
	v_fmac_f32_e32 v133, v105, v209
	v_mul_f32_e32 v140, v106, v210
	v_mul_f32_e32 v141, v107, v211
	v_add_f32_e32 v133, v133, v140
	v_add_f32_e32 v133, v133, v141
	v_mul_f32_e32 v140, v108, v212
	v_mul_f32_e32 v141, v109, v213
	v_add_f32_e32 v133, v133, v140
	v_add_f32_e32 v133, v133, v141
	v_mul_f32_e32 v140, v110, v214
	v_mul_f32_e32 v141, v111, v215
	v_add_f32_e32 v133, v133, v140
	v_add_f32_e32 v133, v133, v141
	v_mul_f32_e32 v140, v112, v216
	v_mul_f32_e32 v141, v113, v217
	v_add_f32_e32 v133, v133, v140
	v_add_f32_e32 v133, v133, v141
	v_mul_f32_e32 v140, v114, v218
	v_mul_f32_e32 v141, v115, v219
	v_add_f32_e32 v133, v133, v140
	v_add_f32_e32 v133, v133, v141
	s_mov_b32 s14, 0xbfb8aa3b
	v_min_f32_e32 v141, 0, v133
	v_mul_f32_e64 v140, |v133|, s14
	v_exp_f32_e32 v140, v140
	s_mov_b32 s14, 0x800000
	v_add_f32_e32 v140, 1.0, v140
	v_cmp_gt_f32_e32 vcc, s14, v140
	s_mov_b32 s14, 0x3f317217
	s_nop 0
	v_cndmask_b32_e64 v142, 0, 32, vcc
	v_ldexp_f32 v140, v140, v142
	v_log_f32_e32 v140, v140
	s_nop 0
	v_mul_f32_e32 v142, 0x3f317217, v140
	v_fma_f32 v142, v140, s14, -v142
	v_fmac_f32_e32 v142, 0x3377d1cf, v140
	s_mov_b32 s14, 0x7f800000
	v_fmac_f32_e32 v142, 0x3f317217, v140
	v_cmp_lt_f32_e64 s[18:19], |v140|, s14
	s_nop 1
	v_cndmask_b32_e64 v140, v140, v142, s[18:19]
	v_cndmask_b32_e32 v142, 0, v149, vcc
	v_sub_f32_e32 v140, v140, v142
	v_sub_f32_e32 v140, v141, v140
	v_mul_f32_e32 v142, 0x3d800000, v140
	v_mad_u32_u24 v144, v91, s15, v148
	ds_write_b32 v144, v142
	s_waitcnt lgkmcnt(1)
	v_lshl_add_u32 v143, v93, 2, s4
	ds_read2st64_b32 v[204:205], v143 offset1:1
	ds_read2st64_b32 v[206:207], v143 offset0:2 offset1:3
	ds_read2st64_b32 v[208:209], v143 offset0:4 offset1:5
	ds_read2st64_b32 v[210:211], v143 offset0:6 offset1:7
	ds_read2st64_b32 v[212:213], v143 offset0:8 offset1:9
	ds_read2st64_b32 v[214:215], v143 offset0:10 offset1:11
	ds_read2st64_b32 v[216:217], v143 offset0:12 offset1:13
	ds_read2st64_b32 v[218:219], v143 offset0:14 offset1:15
	v_fmac_f32_e32 v134, v100, v180
	v_fmac_f32_e32 v134, v101, v181
	v_fmac_f32_e32 v134, v102, v182
	v_fmac_f32_e32 v134, v103, v183
	v_fmac_f32_e32 v134, v104, v184
	v_fmac_f32_e32 v134, v105, v185
	v_mul_f32_e32 v140, v106, v186
	v_mul_f32_e32 v141, v107, v187
	v_add_f32_e32 v134, v134, v140
	v_add_f32_e32 v134, v134, v141
	v_mul_f32_e32 v140, v108, v188
	v_mul_f32_e32 v141, v109, v189
	v_add_f32_e32 v134, v134, v140
	v_add_f32_e32 v134, v134, v141
	v_mul_f32_e32 v140, v110, v190
	v_mul_f32_e32 v141, v111, v191
	v_add_f32_e32 v134, v134, v140
	v_add_f32_e32 v134, v134, v141
	v_mul_f32_e32 v140, v112, v192
	v_mul_f32_e32 v141, v113, v193
	v_add_f32_e32 v134, v134, v140
	v_add_f32_e32 v134, v134, v141
	v_mul_f32_e32 v140, v114, v194
	v_mul_f32_e32 v141, v115, v195
	v_add_f32_e32 v134, v134, v140
	v_add_f32_e32 v134, v134, v141
	s_mov_b32 s14, 0xbfb8aa3b
	v_min_f32_e32 v141, 0, v134
	v_mul_f32_e64 v140, |v134|, s14
	v_exp_f32_e32 v140, v140
	s_mov_b32 s14, 0x800000
	v_add_f32_e32 v140, 1.0, v140
	v_cmp_gt_f32_e32 vcc, s14, v140
	s_mov_b32 s14, 0x3f317217
	s_nop 0
	v_cndmask_b32_e64 v142, 0, 32, vcc
	v_ldexp_f32 v140, v140, v142
	v_log_f32_e32 v140, v140
	s_nop 0
	v_mul_f32_e32 v142, 0x3f317217, v140
	v_fma_f32 v142, v140, s14, -v142
	v_fmac_f32_e32 v142, 0x3377d1cf, v140
	s_mov_b32 s14, 0x7f800000
	v_fmac_f32_e32 v142, 0x3f317217, v140
	v_cmp_lt_f32_e64 s[18:19], |v140|, s14
	s_nop 1
	v_cndmask_b32_e64 v140, v140, v142, s[18:19]
	v_cndmask_b32_e32 v142, 0, v149, vcc
	v_sub_f32_e32 v140, v140, v142
	v_sub_f32_e32 v140, v141, v140
	v_mul_f32_e32 v142, 0x3d800000, v140
	v_mad_u32_u24 v144, v92, s15, v148
	ds_write_b32 v144, v142
	s_waitcnt lgkmcnt(1)
	v_lshl_add_u32 v143, v94, 2, s4
	ds_read2st64_b32 v[180:181], v143 offset1:1
	ds_read2st64_b32 v[182:183], v143 offset0:2 offset1:3
	ds_read2st64_b32 v[184:185], v143 offset0:4 offset1:5
	ds_read2st64_b32 v[186:187], v143 offset0:6 offset1:7
	ds_read2st64_b32 v[188:189], v143 offset0:8 offset1:9
	ds_read2st64_b32 v[190:191], v143 offset0:10 offset1:11
	ds_read2st64_b32 v[192:193], v143 offset0:12 offset1:13
	ds_read2st64_b32 v[194:195], v143 offset0:14 offset1:15
	v_fmac_f32_e32 v135, v100, v204
	v_fmac_f32_e32 v135, v101, v205
	v_fmac_f32_e32 v135, v102, v206
	v_fmac_f32_e32 v135, v103, v207
	v_fmac_f32_e32 v135, v104, v208
	v_fmac_f32_e32 v135, v105, v209
	v_mul_f32_e32 v140, v106, v210
	v_mul_f32_e32 v141, v107, v211
	v_add_f32_e32 v135, v135, v140
	v_add_f32_e32 v135, v135, v141
	v_mul_f32_e32 v140, v108, v212
	v_mul_f32_e32 v141, v109, v213
	v_add_f32_e32 v135, v135, v140
	v_add_f32_e32 v135, v135, v141
	v_mul_f32_e32 v140, v110, v214
	v_mul_f32_e32 v141, v111, v215
	v_add_f32_e32 v135, v135, v140
	v_add_f32_e32 v135, v135, v141
	v_mul_f32_e32 v140, v112, v216
	v_mul_f32_e32 v141, v113, v217
	v_add_f32_e32 v135, v135, v140
	v_add_f32_e32 v135, v135, v141
	v_mul_f32_e32 v140, v114, v218
	v_mul_f32_e32 v141, v115, v219
	v_add_f32_e32 v135, v135, v140
	v_add_f32_e32 v135, v135, v141
	s_mov_b32 s14, 0xbfb8aa3b
	v_min_f32_e32 v141, 0, v135
	v_mul_f32_e64 v140, |v135|, s14
	v_exp_f32_e32 v140, v140
	s_mov_b32 s14, 0x800000
	v_add_f32_e32 v140, 1.0, v140
	v_cmp_gt_f32_e32 vcc, s14, v140
	s_mov_b32 s14, 0x3f317217
	s_nop 0
	v_cndmask_b32_e64 v142, 0, 32, vcc
	v_ldexp_f32 v140, v140, v142
	v_log_f32_e32 v140, v140
	s_nop 0
	v_mul_f32_e32 v142, 0x3f317217, v140
	v_fma_f32 v142, v140, s14, -v142
	v_fmac_f32_e32 v142, 0x3377d1cf, v140
	s_mov_b32 s14, 0x7f800000
	v_fmac_f32_e32 v142, 0x3f317217, v140
	v_cmp_lt_f32_e64 s[18:19], |v140|, s14
	s_nop 1
	v_cndmask_b32_e64 v140, v140, v142, s[18:19]
	v_cndmask_b32_e32 v142, 0, v149, vcc
	v_sub_f32_e32 v140, v140, v142
	v_sub_f32_e32 v140, v141, v140
	v_mul_f32_e32 v142, 0x3d800000, v140
	v_mad_u32_u24 v144, v93, s15, v148
	ds_write_b32 v144, v142
	s_waitcnt lgkmcnt(1)
	v_lshl_add_u32 v143, v95, 2, s4
	ds_read2st64_b32 v[204:205], v143 offset1:1
	ds_read2st64_b32 v[206:207], v143 offset0:2 offset1:3
	ds_read2st64_b32 v[208:209], v143 offset0:4 offset1:5
	ds_read2st64_b32 v[210:211], v143 offset0:6 offset1:7
	ds_read2st64_b32 v[212:213], v143 offset0:8 offset1:9
	ds_read2st64_b32 v[214:215], v143 offset0:10 offset1:11
	ds_read2st64_b32 v[216:217], v143 offset0:12 offset1:13
	ds_read2st64_b32 v[218:219], v143 offset0:14 offset1:15
	v_fmac_f32_e32 v136, v100, v180
	v_fmac_f32_e32 v136, v101, v181
	v_fmac_f32_e32 v136, v102, v182
	v_fmac_f32_e32 v136, v103, v183
	v_fmac_f32_e32 v136, v104, v184
	v_fmac_f32_e32 v136, v105, v185
	v_mul_f32_e32 v140, v106, v186
	v_mul_f32_e32 v141, v107, v187
	v_add_f32_e32 v136, v136, v140
	v_add_f32_e32 v136, v136, v141
	v_mul_f32_e32 v140, v108, v188
	v_mul_f32_e32 v141, v109, v189
	v_add_f32_e32 v136, v136, v140
	v_add_f32_e32 v136, v136, v141
	v_mul_f32_e32 v140, v110, v190
	v_mul_f32_e32 v141, v111, v191
	v_add_f32_e32 v136, v136, v140
	v_add_f32_e32 v136, v136, v141
	v_mul_f32_e32 v140, v112, v192
	v_mul_f32_e32 v141, v113, v193
	v_add_f32_e32 v136, v136, v140
	v_add_f32_e32 v136, v136, v141
	v_mul_f32_e32 v140, v114, v194
	v_mul_f32_e32 v141, v115, v195
	v_add_f32_e32 v136, v136, v140
	v_add_f32_e32 v136, v136, v141
	s_mov_b32 s14, 0xbfb8aa3b
	v_min_f32_e32 v141, 0, v136
	v_mul_f32_e64 v140, |v136|, s14
	v_exp_f32_e32 v140, v140
	s_mov_b32 s14, 0x800000
	v_add_f32_e32 v140, 1.0, v140
	v_cmp_gt_f32_e32 vcc, s14, v140
	s_mov_b32 s14, 0x3f317217
	s_nop 0
	v_cndmask_b32_e64 v142, 0, 32, vcc
	v_ldexp_f32 v140, v140, v142
	v_log_f32_e32 v140, v140
	s_nop 0
	v_mul_f32_e32 v142, 0x3f317217, v140
	v_fma_f32 v142, v140, s14, -v142
	v_fmac_f32_e32 v142, 0x3377d1cf, v140
	s_mov_b32 s14, 0x7f800000
	v_fmac_f32_e32 v142, 0x3f317217, v140
	v_cmp_lt_f32_e64 s[18:19], |v140|, s14
	s_nop 1
	v_cndmask_b32_e64 v140, v140, v142, s[18:19]
	v_cndmask_b32_e32 v142, 0, v149, vcc
	v_sub_f32_e32 v140, v140, v142
	v_sub_f32_e32 v140, v141, v140
	v_mul_f32_e32 v142, 0x3d800000, v140
	v_mad_u32_u24 v144, v94, s15, v148
	ds_write_b32 v144, v142
	s_waitcnt lgkmcnt(1)
	v_lshl_add_u32 v143, v96, 2, s4
	ds_read2st64_b32 v[180:181], v143 offset1:1
	ds_read2st64_b32 v[182:183], v143 offset0:2 offset1:3
	ds_read2st64_b32 v[184:185], v143 offset0:4 offset1:5
	ds_read2st64_b32 v[186:187], v143 offset0:6 offset1:7
	ds_read2st64_b32 v[188:189], v143 offset0:8 offset1:9
	ds_read2st64_b32 v[190:191], v143 offset0:10 offset1:11
	ds_read2st64_b32 v[192:193], v143 offset0:12 offset1:13
	ds_read2st64_b32 v[194:195], v143 offset0:14 offset1:15
	v_fmac_f32_e32 v137, v100, v204
	v_fmac_f32_e32 v137, v101, v205
	v_fmac_f32_e32 v137, v102, v206
	v_fmac_f32_e32 v137, v103, v207
	v_fmac_f32_e32 v137, v104, v208
	v_fmac_f32_e32 v137, v105, v209
	v_mul_f32_e32 v140, v106, v210
	v_mul_f32_e32 v141, v107, v211
	v_add_f32_e32 v137, v137, v140
	v_add_f32_e32 v137, v137, v141
	v_mul_f32_e32 v140, v108, v212
	v_mul_f32_e32 v141, v109, v213
	v_add_f32_e32 v137, v137, v140
	v_add_f32_e32 v137, v137, v141
	v_mul_f32_e32 v140, v110, v214
	v_mul_f32_e32 v141, v111, v215
	v_add_f32_e32 v137, v137, v140
	v_add_f32_e32 v137, v137, v141
	v_mul_f32_e32 v140, v112, v216
	v_mul_f32_e32 v141, v113, v217
	v_add_f32_e32 v137, v137, v140
	v_add_f32_e32 v137, v137, v141
	v_mul_f32_e32 v140, v114, v218
	v_mul_f32_e32 v141, v115, v219
	v_add_f32_e32 v137, v137, v140
	v_add_f32_e32 v137, v137, v141
	s_mov_b32 s14, 0xbfb8aa3b
	v_min_f32_e32 v141, 0, v137
	v_mul_f32_e64 v140, |v137|, s14
	v_exp_f32_e32 v140, v140
	s_mov_b32 s14, 0x800000
	v_add_f32_e32 v140, 1.0, v140
	v_cmp_gt_f32_e32 vcc, s14, v140
	s_mov_b32 s14, 0x3f317217
	s_nop 0
	v_cndmask_b32_e64 v142, 0, 32, vcc
	v_ldexp_f32 v140, v140, v142
	v_log_f32_e32 v140, v140
	s_nop 0
	v_mul_f32_e32 v142, 0x3f317217, v140
	v_fma_f32 v142, v140, s14, -v142
	v_fmac_f32_e32 v142, 0x3377d1cf, v140
	s_mov_b32 s14, 0x7f800000
	v_fmac_f32_e32 v142, 0x3f317217, v140
	v_cmp_lt_f32_e64 s[18:19], |v140|, s14
	s_nop 1
	v_cndmask_b32_e64 v140, v140, v142, s[18:19]
	v_cndmask_b32_e32 v142, 0, v149, vcc
	v_sub_f32_e32 v140, v140, v142
	v_sub_f32_e32 v140, v141, v140
	v_mul_f32_e32 v142, 0x3d800000, v140
	v_mad_u32_u24 v144, v95, s15, v148
	ds_write_b32 v144, v142
	s_waitcnt lgkmcnt(1)
	v_lshl_add_u32 v143, v97, 2, s4
	ds_read2st64_b32 v[204:205], v143 offset1:1
	ds_read2st64_b32 v[206:207], v143 offset0:2 offset1:3
	ds_read2st64_b32 v[208:209], v143 offset0:4 offset1:5
	ds_read2st64_b32 v[210:211], v143 offset0:6 offset1:7
	ds_read2st64_b32 v[212:213], v143 offset0:8 offset1:9
	ds_read2st64_b32 v[214:215], v143 offset0:10 offset1:11
	ds_read2st64_b32 v[216:217], v143 offset0:12 offset1:13
	ds_read2st64_b32 v[218:219], v143 offset0:14 offset1:15
	v_fmac_f32_e32 v138, v100, v180
	v_fmac_f32_e32 v138, v101, v181
	v_fmac_f32_e32 v138, v102, v182
	v_fmac_f32_e32 v138, v103, v183
	v_fmac_f32_e32 v138, v104, v184
	v_fmac_f32_e32 v138, v105, v185
	v_mul_f32_e32 v140, v106, v186
	v_mul_f32_e32 v141, v107, v187
	v_add_f32_e32 v138, v138, v140
	v_add_f32_e32 v138, v138, v141
	v_mul_f32_e32 v140, v108, v188
	v_mul_f32_e32 v141, v109, v189
	v_add_f32_e32 v138, v138, v140
	v_add_f32_e32 v138, v138, v141
	v_mul_f32_e32 v140, v110, v190
	v_mul_f32_e32 v141, v111, v191
	v_add_f32_e32 v138, v138, v140
	v_add_f32_e32 v138, v138, v141
	v_mul_f32_e32 v140, v112, v192
	v_mul_f32_e32 v141, v113, v193
	v_add_f32_e32 v138, v138, v140
	v_add_f32_e32 v138, v138, v141
	v_mul_f32_e32 v140, v114, v194
	v_mul_f32_e32 v141, v115, v195
	v_add_f32_e32 v138, v138, v140
	v_add_f32_e32 v138, v138, v141
	s_mov_b32 s14, 0xbfb8aa3b
	v_min_f32_e32 v141, 0, v138
	v_mul_f32_e64 v140, |v138|, s14
	v_exp_f32_e32 v140, v140
	s_mov_b32 s14, 0x800000
	v_add_f32_e32 v140, 1.0, v140
	v_cmp_gt_f32_e32 vcc, s14, v140
	s_mov_b32 s14, 0x3f317217
	s_nop 0
	v_cndmask_b32_e64 v142, 0, 32, vcc
	v_ldexp_f32 v140, v140, v142
	v_log_f32_e32 v140, v140
	s_nop 0
	v_mul_f32_e32 v142, 0x3f317217, v140
	v_fma_f32 v142, v140, s14, -v142
	v_fmac_f32_e32 v142, 0x3377d1cf, v140
	s_mov_b32 s14, 0x7f800000
	v_fmac_f32_e32 v142, 0x3f317217, v140
	v_cmp_lt_f32_e64 s[18:19], |v140|, s14
	s_nop 1
	v_cndmask_b32_e64 v140, v140, v142, s[18:19]
	v_cndmask_b32_e32 v142, 0, v149, vcc
	v_sub_f32_e32 v140, v140, v142
	v_sub_f32_e32 v140, v141, v140
	v_mul_f32_e32 v142, 0x3d800000, v140
	v_mad_u32_u24 v144, v96, s15, v148
	ds_write_b32 v144, v142
	s_waitcnt lgkmcnt(1)
	v_fmac_f32_e32 v139, v100, v204
	v_fmac_f32_e32 v139, v101, v205
	v_fmac_f32_e32 v139, v102, v206
	v_fmac_f32_e32 v139, v103, v207
	v_fmac_f32_e32 v139, v104, v208
	v_fmac_f32_e32 v139, v105, v209
	v_mul_f32_e32 v140, v106, v210
	v_mul_f32_e32 v141, v107, v211
	v_add_f32_e32 v139, v139, v140
	v_add_f32_e32 v139, v139, v141
	v_mul_f32_e32 v140, v108, v212
	v_mul_f32_e32 v141, v109, v213
	v_add_f32_e32 v139, v139, v140
	v_add_f32_e32 v139, v139, v141
	v_mul_f32_e32 v140, v110, v214
	v_mul_f32_e32 v141, v111, v215
	v_add_f32_e32 v139, v139, v140
	v_add_f32_e32 v139, v139, v141
	v_mul_f32_e32 v140, v112, v216
	v_mul_f32_e32 v141, v113, v217
	v_add_f32_e32 v139, v139, v140
	v_add_f32_e32 v139, v139, v141
	v_mul_f32_e32 v140, v114, v218
	v_mul_f32_e32 v141, v115, v219
	v_add_f32_e32 v139, v139, v140
	v_add_f32_e32 v139, v139, v141
	s_mov_b32 s14, 0xbfb8aa3b
	v_min_f32_e32 v141, 0, v139
	v_mul_f32_e64 v140, |v139|, s14
	v_exp_f32_e32 v140, v140
	s_mov_b32 s14, 0x800000
	v_add_f32_e32 v140, 1.0, v140
	v_cmp_gt_f32_e32 vcc, s14, v140
	s_mov_b32 s14, 0x3f317217
	s_nop 0
	v_cndmask_b32_e64 v142, 0, 32, vcc
	v_ldexp_f32 v140, v140, v142
	v_log_f32_e32 v140, v140
	s_nop 0
	v_mul_f32_e32 v142, 0x3f317217, v140
	v_fma_f32 v142, v140, s14, -v142
	v_fmac_f32_e32 v142, 0x3377d1cf, v140
	s_mov_b32 s14, 0x7f800000
	v_fmac_f32_e32 v142, 0x3f317217, v140
	v_cmp_lt_f32_e64 s[18:19], |v140|, s14
	s_nop 1
	v_cndmask_b32_e64 v140, v140, v142, s[18:19]
	v_cndmask_b32_e32 v142, 0, v149, vcc
	v_sub_f32_e32 v140, v140, v142
	v_sub_f32_e32 v140, v141, v140
	v_mul_f32_e32 v142, 0x3d800000, v140
	v_mad_u32_u24 v144, v97, s15, v148
	ds_write_b32 v144, v142
	s_ashr_i32 s3, s2, 6
	s_mul_i32 s4, s3, 0x820
	s_add_i32 s4, s4, s94
	v_lshl_add_u32 v24, v26, 2, s4
	s_waitcnt lgkmcnt(0)
	s_barrier
	ds_read2_b32 v[22:23], v24 offset1:65
	v_and_b32_e32 v21, 64, v1
	v_add_u32_e32 v25, -1, v1
	v_cmp_lt_i32_e32 vcc, v25, v21
	v_subrev_u32_e32 v49, 32, v1
	v_cmp_lt_i32_e64 s[14:15], v49, v21
	v_cndmask_b32_e32 v25, v25, v1, vcc
	v_lshlrev_b32_e32 v25, 2, v25
	s_waitcnt lgkmcnt(0)
	ds_bpermute_b32 v43, v25, v22
	v_cmp_eq_u32_e32 vcc, 0, v26
	ds_bpermute_b32 v47, v25, v23
	s_movk_i32 s4, 0x104
	s_mov_b32 s17, 0
	s_waitcnt lgkmcnt(1)
	v_add_f32_e32 v43, v22, v43
	v_cndmask_b32_e32 v22, v43, v22, vcc
	v_add_u32_e32 v43, -2, v1
	v_cmp_lt_i32_e64 s[6:7], v43, v21
	s_waitcnt lgkmcnt(0)
	v_add_f32_e32 v47, v23, v47
	v_cndmask_b32_e32 v23, v47, v23, vcc
	v_cndmask_b32_e64 v43, v43, v1, s[6:7]
	v_lshlrev_b32_e32 v43, 2, v43
	ds_bpermute_b32 v44, v43, v22
	v_cmp_gt_u32_e64 s[6:7], 2, v26
	ds_bpermute_b32 v47, v43, v23
	s_and_b32 s3, s3, 3
	s_ashr_i32 s2, s2, 8
	s_waitcnt lgkmcnt(1)
	v_add_f32_e32 v44, v22, v44
	v_cndmask_b32_e64 v22, v44, v22, s[6:7]
	v_add_u32_e32 v44, -4, v1
	v_cmp_lt_i32_e64 s[8:9], v44, v21
	s_waitcnt lgkmcnt(0)
	v_add_f32_e32 v47, v23, v47
	v_cndmask_b32_e64 v23, v47, v23, s[6:7]
	v_cndmask_b32_e64 v44, v44, v1, s[8:9]
	v_lshlrev_b32_e32 v44, 2, v44
	ds_bpermute_b32 v45, v44, v22
	v_cmp_gt_u32_e64 s[8:9], 4, v26
	ds_bpermute_b32 v47, v44, v23
	s_waitcnt lgkmcnt(1)
	v_add_f32_e32 v45, v22, v45
	v_cndmask_b32_e64 v22, v45, v22, s[8:9]
	v_add_u32_e32 v45, -8, v1
	v_cmp_lt_i32_e64 s[10:11], v45, v21
	s_nop 1
	v_cndmask_b32_e64 v45, v45, v1, s[10:11]
	v_lshlrev_b32_e32 v45, 2, v45
	ds_bpermute_b32 v46, v45, v22
	v_cmp_gt_u32_e64 s[10:11], 8, v26
	s_waitcnt lgkmcnt(0)
	v_add_f32_e32 v46, v22, v46
	v_cndmask_b32_e64 v22, v46, v22, s[10:11]
	v_add_u32_e32 v46, -16, v1
	v_cmp_lt_i32_e64 s[12:13], v46, v21
	v_cndmask_b32_e64 v21, v49, v1, s[14:15]
	v_lshlrev_b32_e32 v21, 2, v21
	v_cndmask_b32_e64 v46, v46, v1, s[12:13]
	v_lshlrev_b32_e32 v46, 2, v46
	ds_bpermute_b32 v48, v46, v22
	v_cmp_gt_u32_e64 s[12:13], 16, v26
	v_cmp_gt_u32_e64 s[14:15], 32, v26
	s_waitcnt lgkmcnt(0)
	v_add_f32_e32 v48, v22, v48
	v_cndmask_b32_e64 v48, v48, v22, s[12:13]
	v_add_f32_e32 v22, v23, v47
	v_cndmask_b32_e64 v47, v22, v23, s[8:9]
	ds_read2_b32 v[22:23], v24 offset0:130 offset1:195
	ds_bpermute_b32 v50, v45, v47
	ds_bpermute_b32 v51, v21, v48
	s_waitcnt lgkmcnt(2)
	ds_bpermute_b32 v49, v25, v22
	s_waitcnt lgkmcnt(2)
	v_add_f32_e32 v50, v47, v50
	v_cndmask_b32_e64 v47, v50, v47, s[10:11]
	ds_bpermute_b32 v50, v46, v47
	s_waitcnt lgkmcnt(2)
	v_add_f32_e32 v51, v48, v51
	s_waitcnt lgkmcnt(1)
	v_add_f32_e32 v49, v22, v49
	v_cndmask_b32_e32 v22, v49, v22, vcc
	ds_bpermute_b32 v49, v43, v22
	s_waitcnt lgkmcnt(1)
	v_add_f32_e32 v50, v47, v50
	v_cndmask_b32_e64 v47, v50, v47, s[12:13]
	ds_bpermute_b32 v50, v21, v47
	v_cndmask_b32_e64 v48, v51, v48, s[14:15]
	s_waitcnt lgkmcnt(1)
	v_add_f32_e32 v49, v22, v49
	v_cndmask_b32_e64 v22, v49, v22, s[6:7]
	ds_bpermute_b32 v49, v44, v22
	ds_bpermute_b32 v51, v25, v23
	s_waitcnt lgkmcnt(2)
	v_add_f32_e32 v50, v47, v50
	v_cndmask_b32_e64 v47, v50, v47, s[14:15]
	ds_write2_b32 v24, v48, v47 offset1:65
	s_waitcnt lgkmcnt(2)
	v_add_f32_e32 v49, v22, v49
	v_cndmask_b32_e64 v22, v49, v22, s[8:9]
	s_waitcnt lgkmcnt(1)
	v_add_f32_e32 v50, v23, v51
	ds_bpermute_b32 v49, v45, v22
	v_cndmask_b32_e32 v23, v50, v23, vcc
	ds_bpermute_b32 v50, v43, v23
	s_waitcnt lgkmcnt(1)
	v_add_f32_e32 v47, v22, v49
	v_cndmask_b32_e64 v47, v47, v22, s[10:11]
	s_waitcnt lgkmcnt(0)
	v_add_f32_e32 v22, v23, v50
	v_cndmask_b32_e64 v49, v22, v23, s[6:7]
	v_add_u32_e32 v50, 0x400, v24
	ds_read2_b32 v[22:23], v50 offset0:4 offset1:69
	ds_bpermute_b32 v51, v44, v49
	ds_bpermute_b32 v48, v46, v47
	s_waitcnt lgkmcnt(2)
	ds_bpermute_b32 v52, v25, v22
	s_waitcnt lgkmcnt(2)
	v_add_f32_e32 v51, v49, v51
	v_cndmask_b32_e64 v49, v51, v49, s[8:9]
	ds_bpermute_b32 v51, v45, v49
	s_waitcnt lgkmcnt(2)
	v_add_f32_e32 v48, v47, v48
	v_cndmask_b32_e64 v47, v48, v47, s[12:13]
	s_waitcnt lgkmcnt(1)
	v_add_f32_e32 v52, v22, v52
	ds_bpermute_b32 v48, v21, v47
	v_cndmask_b32_e32 v22, v52, v22, vcc
	ds_bpermute_b32 v52, v43, v22
	s_waitcnt lgkmcnt(2)
	v_add_f32_e32 v51, v49, v51
	v_cndmask_b32_e64 v49, v51, v49, s[10:11]
	ds_bpermute_b32 v51, v46, v49
	s_waitcnt lgkmcnt(2)
	v_add_f32_e32 v48, v47, v48
	v_cndmask_b32_e64 v47, v48, v47, s[14:15]
	s_waitcnt lgkmcnt(1)
	v_add_f32_e32 v48, v22, v52
	v_cndmask_b32_e64 v22, v48, v22, s[6:7]
	ds_bpermute_b32 v48, v44, v22
	s_waitcnt lgkmcnt(1)
	v_add_f32_e32 v51, v49, v51
	v_cndmask_b32_e64 v49, v51, v49, s[12:13]
	ds_bpermute_b32 v51, v25, v23
	ds_bpermute_b32 v52, v21, v49
	s_waitcnt lgkmcnt(2)
	v_add_f32_e32 v48, v22, v48
	v_cndmask_b32_e64 v22, v48, v22, s[8:9]
	ds_bpermute_b32 v48, v45, v22
	s_waitcnt lgkmcnt(2)
	v_add_f32_e32 v51, v23, v51
	v_cndmask_b32_e32 v23, v51, v23, vcc
	ds_bpermute_b32 v51, v43, v23
	s_waitcnt lgkmcnt(2)
	v_add_f32_e32 v52, v49, v52
	s_waitcnt lgkmcnt(1)
	v_add_f32_e32 v48, v22, v48
	v_cndmask_b32_e64 v22, v48, v22, s[10:11]
	ds_bpermute_b32 v48, v46, v22
	s_waitcnt lgkmcnt(1)
	v_add_f32_e32 v51, v23, v51
	v_cndmask_b32_e64 v23, v51, v23, s[6:7]
	ds_bpermute_b32 v51, v44, v23
	v_cndmask_b32_e64 v49, v52, v49, s[14:15]
	s_waitcnt lgkmcnt(1)
	v_add_f32_e32 v48, v22, v48
	v_cndmask_b32_e64 v48, v48, v22, s[12:13]
	ds_write2_b32 v24, v47, v49 offset0:130 offset1:195
	s_waitcnt lgkmcnt(1)
	v_add_f32_e32 v22, v23, v51
	v_cndmask_b32_e64 v51, v22, v23, s[8:9]
	ds_read2_b32 v[22:23], v50 offset0:134 offset1:199
	ds_bpermute_b32 v52, v21, v48
	ds_bpermute_b32 v53, v45, v51
	s_waitcnt lgkmcnt(2)
	ds_bpermute_b32 v47, v25, v22
	ds_bpermute_b32 v25, v25, v23
	s_waitcnt lgkmcnt(3)
	v_add_f32_e32 v24, v48, v52
	v_cndmask_b32_e64 v24, v24, v48, s[14:15]
	s_waitcnt lgkmcnt(2)
	v_add_f32_e32 v48, v51, v53
	s_waitcnt lgkmcnt(1)
	v_add_f32_e32 v47, v22, v47
	s_waitcnt lgkmcnt(0)
	v_add_f32_e32 v25, v23, v25
	v_cndmask_b32_e32 v22, v47, v22, vcc
	v_cndmask_b32_e32 v23, v25, v23, vcc
	ds_bpermute_b32 v47, v43, v22
	ds_bpermute_b32 v25, v43, v23
	v_cndmask_b32_e64 v48, v48, v51, s[10:11]
	ds_bpermute_b32 v49, v46, v48
	s_waitcnt lgkmcnt(2)
	v_add_f32_e32 v47, v22, v47
	s_waitcnt lgkmcnt(1)
	v_add_f32_e32 v25, v23, v25
	v_cndmask_b32_e64 v22, v47, v22, s[6:7]
	v_cndmask_b32_e64 v23, v25, v23, s[6:7]
	ds_bpermute_b32 v47, v44, v22
	ds_bpermute_b32 v25, v44, v23
	s_waitcnt lgkmcnt(2)
	v_add_f32_e32 v43, v48, v49
	v_cndmask_b32_e64 v43, v43, v48, s[12:13]
	v_readlane_b32 s6, v228, 8
	s_waitcnt lgkmcnt(1)
	v_add_f32_e32 v44, v22, v47
	s_waitcnt lgkmcnt(0)
	v_add_f32_e32 v25, v23, v25
	v_cndmask_b32_e64 v22, v44, v22, s[8:9]
	v_cndmask_b32_e64 v23, v25, v23, s[8:9]
	ds_bpermute_b32 v44, v45, v22
	ds_bpermute_b32 v25, v45, v23
	ds_bpermute_b32 v45, v21, v43
	v_readlane_b32 s7, v228, 9
	s_waitcnt lgkmcnt(2)
	v_add_f32_e32 v44, v22, v44
	s_waitcnt lgkmcnt(1)
	v_add_f32_e32 v25, v23, v25
	v_cndmask_b32_e64 v22, v44, v22, s[10:11]
	v_cndmask_b32_e64 v23, v25, v23, s[10:11]
	ds_bpermute_b32 v44, v46, v22
	ds_bpermute_b32 v25, v46, v23
	s_waitcnt lgkmcnt(2)
	v_add_f32_e32 v45, v43, v45
	s_waitcnt lgkmcnt(1)
	v_add_f32_e32 v44, v22, v44
	s_waitcnt lgkmcnt(0)
	v_add_f32_e32 v25, v23, v25
	v_cndmask_b32_e64 v22, v44, v22, s[12:13]
	v_cndmask_b32_e64 v23, v25, v23, s[12:13]
	ds_bpermute_b32 v44, v21, v22
	ds_bpermute_b32 v21, v21, v23
	v_cndmask_b32_e64 v25, v45, v43, s[14:15]
	ds_write2_b32 v50, v24, v25 offset0:4 offset1:69
	s_waitcnt lgkmcnt(2)
	v_add_f32_e32 v24, v22, v44
	s_waitcnt lgkmcnt(1)
	v_add_f32_e32 v21, v23, v21
	v_cndmask_b32_e64 v22, v24, v22, s[14:15]
	v_cndmask_b32_e64 v21, v21, v23, s[14:15]
	ds_write2_b32 v50, v22, v21 offset0:134 offset1:199
	v_mov_b32_e32 v21, s94
	v_mad_u32_u24 v21, v26, s4, v21
	v_lshl_add_u32 v19, v19, 2, v21
	s_waitcnt lgkmcnt(0)
	s_barrier
	ds_read_b32 v24, v19
	ds_read_b32 v19, v21 offset:252
	s_lshl_b64 s[4:5], s[16:17], 14
	s_add_u32 s4, s6, s4
	s_addc_u32 s5, s7, s5
	v_lshl_add_u32 v28, v28, 2, v21
	s_waitcnt lgkmcnt(0)
	v_sub_f32_e32 v19, v19, v24
	v_mul_f32_e32 v19, 0x3fb8aa3b, v19
	v_exp_f32_e32 v19, v19
	s_lshl_b32 s3, s3, 7
	v_mul_f32_e32 v22, v42, v19
	v_ashrrev_i32_e32 v19, 31, v18
	v_lshl_add_u32 v42, v18, 2, s94
	ds_write_b32 v42, v22 offset:16640
	v_lshl_add_u64 v[22:23], v[18:19], 2, s[4:5]
	global_store_dword v[22:23], v24, off
	v_lshl_add_u32 v24, v29, 2, v21
	ds_read_b32 v24, v24
	ds_read_b32 v25, v21 offset:252
	s_movk_i32 s4, 0x1000
	s_waitcnt lgkmcnt(0)
	v_sub_f32_e32 v25, v25, v24
	v_mul_f32_e32 v25, 0x3fb8aa3b, v25
	v_exp_f32_e32 v25, v25
	s_nop 0
	v_mul_f32_e32 v25, v41, v25
	ds_write_b32 v42, v25 offset:18688
	global_store_dword v[22:23], v24, off offset:2048
	v_lshl_add_u32 v24, v33, 2, v21
	ds_read_b32 v29, v24
	ds_read_b32 v24, v21 offset:252
	s_waitcnt lgkmcnt(0)
	v_sub_f32_e32 v24, v24, v29
	v_mul_f32_e32 v24, 0x3fb8aa3b, v24
	v_exp_f32_e32 v24, v24
	s_nop 0
	v_mul_f32_e32 v24, v40, v24
	ds_write_b32 v42, v24 offset:20736
	v_add_co_u32_e32 v24, vcc, s4, v22
	s_movk_i32 s4, 0x2000
	s_nop 0
	v_addc_co_u32_e32 v25, vcc, 0, v23, vcc
	global_store_dword v[24:25], v29, off
	v_lshl_add_u32 v29, v30, 2, v21
	ds_read_b32 v29, v29
	ds_read_b32 v30, v21 offset:252
	s_waitcnt lgkmcnt(0)
	v_sub_f32_e32 v30, v30, v29
	v_mul_f32_e32 v30, 0x3fb8aa3b, v30
	v_exp_f32_e32 v30, v30
	s_nop 0
	v_mul_f32_e32 v30, v39, v30
	ds_write_b32 v42, v30 offset:22784
	global_store_dword v[24:25], v29, off offset:2048
	v_lshl_add_u32 v24, v32, 2, v21
	ds_read_b32 v29, v24
	ds_read_b32 v24, v21 offset:252
	s_waitcnt lgkmcnt(0)
	v_sub_f32_e32 v24, v24, v29
	v_mul_f32_e32 v24, 0x3fb8aa3b, v24
	v_exp_f32_e32 v24, v24
	s_nop 0
	v_mul_f32_e32 v24, v38, v24
	ds_write_b32 v42, v24 offset:24832
	v_add_co_u32_e32 v24, vcc, s4, v22
	s_movk_i32 s4, 0x3000
	s_nop 0
	v_addc_co_u32_e32 v25, vcc, 0, v23, vcc
	global_store_dword v[24:25], v29, off
	ds_read_b32 v28, v28
	ds_read_b32 v29, v21 offset:252
	s_waitcnt lgkmcnt(0)
	v_sub_f32_e32 v29, v29, v28
	v_mul_f32_e32 v29, 0x3fb8aa3b, v29
	v_exp_f32_e32 v29, v29
	s_nop 0
	v_mul_f32_e32 v29, v37, v29
	ds_write_b32 v42, v29 offset:26880
	global_store_dword v[24:25], v28, off offset:2048
	v_lshl_add_u32 v24, v31, 2, v21
	ds_read_b32 v28, v24
	ds_read_b32 v24, v21 offset:252
	s_waitcnt lgkmcnt(0)
	v_sub_f32_e32 v24, v24, v28
	v_mul_f32_e32 v24, 0x3fb8aa3b, v24
	v_exp_f32_e32 v24, v24
	s_nop 0
	v_mul_f32_e32 v24, v36, v24
	ds_write_b32 v42, v24 offset:28928
	v_add_co_u32_e32 v24, vcc, s4, v22
	v_lshl_add_u32 v22, v27, 2, v21
	s_nop 0
	v_addc_co_u32_e32 v25, vcc, 0, v23, vcc
	global_store_dword v[24:25], v28, off
	ds_read_b32 v23, v22
	ds_read_b32 v21, v21 offset:252
	v_lshrrev_b32_e32 v22, 5, v26
	v_and_b32_e32 v26, 31, v18
	s_lshl_b32 s4, s2, 7
	s_waitcnt lgkmcnt(0)
	v_sub_f32_e32 v21, v21, v23
	v_mul_f32_e32 v21, 0x3fb8aa3b, v21
	v_exp_f32_e32 v21, v21
	s_nop 0
	v_mul_f32_e32 v21, v34, v21
	ds_write_b32 v42, v21 offset:30976
	v_and_b32_e32 v21, 0x3fffff80, v35
	v_lshlrev_b32_e32 v21, 2, v21
	v_add3_u32 v20, s94, v21, v20
	global_store_dword v[24:25], v23, off offset:2048
	ds_write_b128 v20, v[2:5] offset:33024
	ds_write_b128 v20, v[6:9] offset:41216
	ds_write_b128 v20, v[10:13] offset:49408
	ds_write_b128 v20, v[14:17] offset:57600
	v_lshlrev_b32_e32 v2, 9, v22
	v_lshlrev_b32_e32 v20, 2, v26
	v_or3_b32 v2, v2, s3, v20
	v_add_u32_e32 v2, s94, v2
	v_add_u32_e32 v21, 0x8100, v2
	v_lshl_add_u32 v2, v22, 8, s4
	v_or_b32_e32 v2, v2, v20
	v_add_u32_e32 v2, s94, v2
	v_add_u32_e32 v23, 0x4100, v2
	v_mov_b32_e32 v2, 0
	s_mov_b32 s4, s17
	v_mov_b32_e32 v3, v2
	v_mov_b32_e32 v4, v2
	v_mov_b32_e32 v5, v2
	v_mov_b32_e32 v6, v2
	v_mov_b32_e32 v7, v2
	v_mov_b32_e32 v8, v2
	v_mov_b32_e32 v9, v2
	v_mov_b32_e32 v10, v2
	v_mov_b32_e32 v11, v2
	v_mov_b32_e32 v12, v2
	v_mov_b32_e32 v13, v2
	v_mov_b32_e32 v14, v2
	v_mov_b32_e32 v15, v2
	v_mov_b32_e32 v16, v2
	v_mov_b32_e32 v17, v2
	s_waitcnt lgkmcnt(0)
	s_barrier
